# GEMM K-loops restructured: B0 fragment reads issued one load segment earlier (L8/L4, covered by vmcnt(10) one barrier earlier), LDS reads first in every load segment, trailing SALU/VALU of MMA segment
# speedup vs baseline: 1.0497x; 1.0065x over previous
; #define PG8_STAGE(bufoff, gbase, voff) do { _Pragma("unroll") for (int _i = 0; _i < 2; ++_i) \
;         __builtin_amdgcn_global_load_lds((const unsigned*)((const char*)(gbase) + (voff)[_i]), (LAS unsigned*)(lds + (bufoff) + ldsw + _i * 8192), 16, 0, 0); } while (0)
; #define PG8_LDA(dst, b, h) do { _Pragma("unroll") for (int m = 0; m < 4; ++m) _Pragma("unroll") for (int k = 0; k < 2; ++k) dst[m][k] = *(const LAS bf16x8*)(lds + PG8_SA(b, h) + aoff + m * 2048 + k * 1024); } while (0)
; #define PG8_LDB(dst, b, h) do { _Pragma("unroll") for (int n = 0; n < 2; ++n) _Pragma("unroll") for (int k = 0; k < 2; ++k) dst[n][k] = *(const LAS bf16x8*)(lds + PG8_SB(b, h) + boff + n * 2048 + k * 1024); } while (0)
; #define PG8_MMA(ai, bj, At, Bt) do { __builtin_amdgcn_s_setprio(1); _Pragma("unroll") for (int m = 0; m < 4; ++m) _Pragma("unroll") for (int n = 0; n < 2; ++n) _Pragma("unroll") for (int k = 0; k < 2; ++k) \
;         acc[ai][bj][m][n] = __builtin_amdgcn_mfma_f32_16x16x32_bf16(Bt[n][k], At[m][k], acc[ai][bj][m][n], 0, 0, 0); __builtin_amdgcn_s_setprio(0); } while (0)
; #define PG8_WAIT_L(n) asm volatile("s_waitcnt lgkmcnt(" #n ")" ::: "memory")
; #define PG8_BAR __builtin_amdgcn_s_barrier()
; #define PG8_SCHED __builtin_amdgcn_sched_barrier(0)
; template <class Epi, bool KS0 = false>
; __device__ __forceinline__ void gemm_phase(const int WID, LAS unsigned char* lds, const Gemm g, const StaticOrder& S, const Epi& E) {
;     ...
;         const bool has_next = S.next(ui + 1, nxt);
;         const char* nA = has_next ? (const char*)g.A + (size_t)nxt.pm * tstep : cA; const char* nB = has_next ? (const char*)g.Bt + (size_t)nxt.pn * tstep : cB;
;         for (int t = 0; t < nt; t += 2) {
;             const bool last = (t == nt - 2);
;             const char* a1 = cA + (size_t)(t + 1) * kstep;
;             const char* a2 = last ? nA : cA + (size_t)(t + 2) * kstep; const char* b2 = last ? nB : cB + (size_t)(t + 2) * kstep;
;             const char* a3 = a2 + kstep; const char* b3 = b2 + kstep;
;             PG8_LDB(B0, 0, 0); PG8_SCHED; PG8_LDA(At, 0, 0); PG8_STAGE(PG8_SA(1, 1), a1 + hstep, voffA);
;             PG8_WAIT_L(8); PG8_BAR; PG8_WAIT_L(0); PG8_MMA(0, 0, At, B0); PG8_BAR; PG8_SCHED;
.LBB0_85:
	s_ashr_i32 s15, s14, 31
	v_cmp_lt_i64_e32 vcc, s[16:17], v[140:141]
	s_lshl_b64 s[16:17], s[14:15], 20
	s_add_u32 s16, s30, s16
	s_addc_u32 s17, s31, s17
	s_and_b64 s[18:19], vcc, exec
	s_cselect_b32 s15, s17, s21
	s_cselect_b32 s46, s16, s20
	s_ashr_i32 s13, s12, 31
	s_lshl_b64 s[18:19], s[12:13], 20
	s_add_u32 s18, s94, s18
	s_addc_u32 s19, s95, s19
	s_and_b64 s[24:25], vcc, exec
	s_cselect_b32 s13, s19, s23
	s_cselect_b32 s47, s18, s22
	s_add_u32 s20, s20, 0x80080
	s_addc_u32 s21, s21, 0
	s_add_u32 s48, s22, 0x100
	v_mov_b32_e32 v0, 0
	s_addc_u32 s49, s23, 0
	s_mov_b32 s50, -2
	v_mov_b32_e32 v1, v0
	v_mov_b32_e32 v2, v0
	v_mov_b32_e32 v3, v0
	v_mov_b32_e32 v4, v0
	v_mov_b32_e32 v5, v0
	v_mov_b32_e32 v6, v0
	v_mov_b32_e32 v7, v0
	v_mov_b32_e32 v8, v0
	v_mov_b32_e32 v9, v0
	v_mov_b32_e32 v10, v0
	v_mov_b32_e32 v11, v0
	v_mov_b32_e32 v16, v0
	v_mov_b32_e32 v17, v0
	v_mov_b32_e32 v18, v0
	v_mov_b32_e32 v19, v0
	v_mov_b32_e32 v24, v0
	v_mov_b32_e32 v25, v0
	v_mov_b32_e32 v26, v0
	v_mov_b32_e32 v27, v0
	v_mov_b32_e32 v32, v0
	v_mov_b32_e32 v33, v0
	v_mov_b32_e32 v34, v0
	v_mov_b32_e32 v35, v0
	v_mov_b32_e32 v40, v0
	v_mov_b32_e32 v41, v0
	v_mov_b32_e32 v42, v0
	v_mov_b32_e32 v43, v0
	v_mov_b32_e32 v48, v0
	v_mov_b32_e32 v49, v0
	v_mov_b32_e32 v50, v0
	v_mov_b32_e32 v51, v0
	v_mov_b32_e32 v12, v0
	v_mov_b32_e32 v13, v0
	v_mov_b32_e32 v14, v0
	v_mov_b32_e32 v15, v0
	v_mov_b32_e32 v20, v0
	v_mov_b32_e32 v21, v0
	v_mov_b32_e32 v22, v0
	v_mov_b32_e32 v23, v0
	v_mov_b32_e32 v28, v0
	v_mov_b32_e32 v29, v0
	v_mov_b32_e32 v30, v0
	v_mov_b32_e32 v31, v0
	v_mov_b32_e32 v36, v0
	v_mov_b32_e32 v37, v0
	v_mov_b32_e32 v38, v0
	v_mov_b32_e32 v39, v0
	v_mov_b32_e32 v44, v0
	v_mov_b32_e32 v45, v0
	v_mov_b32_e32 v46, v0
	v_mov_b32_e32 v47, v0
	v_mov_b32_e32 v52, v0
	v_mov_b32_e32 v53, v0
	v_mov_b32_e32 v54, v0
	v_mov_b32_e32 v55, v0
	v_mov_b32_e32 v56, v0
	v_mov_b32_e32 v57, v0
	v_mov_b32_e32 v58, v0
	v_mov_b32_e32 v59, v0
	v_mov_b32_e32 v60, v0
	v_mov_b32_e32 v61, v0
	v_mov_b32_e32 v62, v0
	v_mov_b32_e32 v63, v0
	v_mov_b32_e32 v64, v0
	v_mov_b32_e32 v65, v0
	v_mov_b32_e32 v66, v0
	v_mov_b32_e32 v67, v0
	v_mov_b32_e32 v68, v0
	v_mov_b32_e32 v69, v0
	v_mov_b32_e32 v70, v0
	v_mov_b32_e32 v71, v0
	v_mov_b32_e32 v72, v0
	v_mov_b32_e32 v73, v0
	v_mov_b32_e32 v74, v0
	v_mov_b32_e32 v75, v0
	v_mov_b32_e32 v80, v0
	v_mov_b32_e32 v81, v0
	v_mov_b32_e32 v82, v0
	v_mov_b32_e32 v83, v0
	v_mov_b32_e32 v88, v0
	v_mov_b32_e32 v89, v0
	v_mov_b32_e32 v90, v0
	v_mov_b32_e32 v91, v0
	v_mov_b32_e32 v96, v0
	v_mov_b32_e32 v97, v0
	v_mov_b32_e32 v98, v0
	v_mov_b32_e32 v99, v0
	v_mov_b32_e32 v108, v0
	v_mov_b32_e32 v109, v0
	v_mov_b32_e32 v110, v0
	v_mov_b32_e32 v111, v0
	v_mov_b32_e32 v116, v0
	v_mov_b32_e32 v117, v0
	v_mov_b32_e32 v118, v0
	v_mov_b32_e32 v119, v0
	v_mov_b32_e32 v76, v0
	v_mov_b32_e32 v77, v0
	v_mov_b32_e32 v78, v0
	v_mov_b32_e32 v79, v0
	v_mov_b32_e32 v84, v0
	v_mov_b32_e32 v85, v0
	v_mov_b32_e32 v86, v0
	v_mov_b32_e32 v87, v0
	v_mov_b32_e32 v92, v0
	v_mov_b32_e32 v93, v0
	v_mov_b32_e32 v94, v0
	v_mov_b32_e32 v95, v0
	v_mov_b32_e32 v100, v0
	v_mov_b32_e32 v101, v0
	v_mov_b32_e32 v102, v0
	v_mov_b32_e32 v103, v0
	v_mov_b32_e32 v104, v0
	v_mov_b32_e32 v105, v0
	v_mov_b32_e32 v106, v0
	v_mov_b32_e32 v107, v0
	v_mov_b32_e32 v112, v0
	v_mov_b32_e32 v113, v0
	v_mov_b32_e32 v114, v0
	v_mov_b32_e32 v115, v0
	v_mov_b32_e32 v120, v0
	v_mov_b32_e32 v121, v0
	v_mov_b32_e32 v122, v0
	v_mov_b32_e32 v123, v0
	v_mov_b32_e32 v124, v0
	v_mov_b32_e32 v125, v0
	v_mov_b32_e32 v126, v0
	v_mov_b32_e32 v127, v0
	ds_read_b128 v[152:155], v148
	ds_read_b128 v[156:159], v148 offset:1024
	ds_read_b128 v[160:163], v148 offset:2048
	ds_read_b128 v[164:167], v148 offset:3072
.LBB0_86:
	ds_read_b128 v[168:171], v149
	ds_read_b128 v[172:175], v149 offset:1024
	ds_read_b128 v[176:179], v149 offset:2048
	ds_read_b128 v[180:183], v149 offset:3072
	ds_read_b128 v[184:187], v149 offset:4096
	ds_read_b128 v[188:191], v149 offset:5120
	ds_read_b128 v[192:195], v149 offset:6144
	ds_read_b128 v[196:199], v149 offset:7168
	s_add_u32 s22, s20, 0xfff80080
	s_addc_u32 s23, s21, -1
	s_cmp_eq_u32 s50, 28
	s_cselect_b32 s25, s15, s23
	s_cselect_b32 s24, s46, s22
	s_cselect_b32 s23, s13, s49
	s_cselect_b32 s22, s47, s48
	v_lshl_add_u64 v[144:145], s[20:21], 0, v[136:137]
	s_add_i32 m0, s34, 0xc000
	s_nop 0
	global_load_lds_dwordx4 v[144:145], off
	s_add_i32 m0, s34, 0xe000
	s_nop 0
	global_load_lds_dwordx4 v138, s[20:21]
	s_waitcnt lgkmcnt(8)
	s_barrier
	s_waitcnt lgkmcnt(0)
	v_mfma_f32_16x16x32_bf16 v[124:127], v[152:155], v[168:171], v[124:127]
	v_mfma_f32_16x16x32_bf16 v[120:123], v[160:163], v[168:171], v[120:123]
	v_mfma_f32_16x16x32_bf16 v[112:115], v[152:155], v[176:179], v[112:115]
	v_mfma_f32_16x16x32_bf16 v[104:107], v[160:163], v[176:179], v[104:107]
	v_mfma_f32_16x16x32_bf16 v[100:103], v[152:155], v[184:187], v[100:103]
	v_mfma_f32_16x16x32_bf16 v[92:95], v[160:163], v[184:187], v[92:95]
	v_mfma_f32_16x16x32_bf16 v[84:87], v[152:155], v[192:195], v[84:87]
	v_mfma_f32_16x16x32_bf16 v[76:79], v[160:163], v[192:195], v[76:79]
	v_mfma_f32_16x16x32_bf16 v[124:127], v[156:159], v[172:175], v[124:127]
	v_mfma_f32_16x16x32_bf16 v[120:123], v[164:167], v[172:175], v[120:123]
	v_mfma_f32_16x16x32_bf16 v[112:115], v[156:159], v[180:183], v[112:115]
	v_mfma_f32_16x16x32_bf16 v[104:107], v[164:167], v[180:183], v[104:107]
	v_mfma_f32_16x16x32_bf16 v[100:103], v[156:159], v[188:191], v[100:103]
	v_mfma_f32_16x16x32_bf16 v[92:95], v[164:167], v[188:191], v[92:95]
	v_mfma_f32_16x16x32_bf16 v[84:87], v[156:159], v[196:199], v[84:87]
	v_mfma_f32_16x16x32_bf16 v[76:79], v[164:167], v[196:199], v[76:79]
	s_barrier
; #define PG8_STAGE(bufoff, gbase, voff) do { _Pragma("unroll") for (int _i = 0; _i < 2; ++_i) \
;         __builtin_amdgcn_global_load_lds((const unsigned*)((const char*)(gbase) + (voff)[_i]), (LAS unsigned*)(lds + (bufoff) + ldsw + _i * 8192), 16, 0, 0); } while (0)
; #define PG8_LDA(dst, b, h) do { _Pragma("unroll") for (int m = 0; m < 4; ++m) _Pragma("unroll") for (int k = 0; k < 2; ++k) dst[m][k] = *(const LAS bf16x8*)(lds + PG8_SA(b, h) + aoff + m * 2048 + k * 1024); } while (0)
; #define PG8_LDB(dst, b, h) do { _Pragma("unroll") for (int n = 0; n < 2; ++n) _Pragma("unroll") for (int k = 0; k < 2; ++k) dst[n][k] = *(const LAS bf16x8*)(lds + PG8_SB(b, h) + boff + n * 2048 + k * 1024); } while (0)
; #define PG8_MMA(ai, bj, At, Bt) do { __builtin_amdgcn_s_setprio(1); _Pragma("unroll") for (int m = 0; m < 4; ++m) _Pragma("unroll") for (int n = 0; n < 2; ++n) _Pragma("unroll") for (int k = 0; k < 2; ++k) \
;         acc[ai][bj][m][n] = __builtin_amdgcn_mfma_f32_16x16x32_bf16(Bt[n][k], At[m][k], acc[ai][bj][m][n], 0, 0, 0); __builtin_amdgcn_s_setprio(0); } while (0)
; #define PG8_WAIT_V(n) asm volatile("s_waitcnt vmcnt(" #n ")" ::: "memory")
; #define PG8_WAIT_L(n) asm volatile("s_waitcnt lgkmcnt(" #n ")" ::: "memory")
; #define PG8_BAR __builtin_amdgcn_s_barrier()
; #define PG8_SCHED __builtin_amdgcn_sched_barrier(0)
; template <class Epi, bool KS0 = false>
; __device__ __forceinline__ void gemm_phase(const int WID, LAS unsigned char* lds, const Gemm g, const StaticOrder& S, const Epi& E) {
;     ...
;             PG8_LDB(B1, 0, 1); PG8_STAGE(PG8_SB(0, 0), b2, voffB);
;             PG8_BAR; PG8_WAIT_L(0); PG8_MMA(0, 1, At, B1); PG8_BAR;
;             PG8_LDA(At, 0, 1); PG8_STAGE(PG8_SA(0, 0), a2, voffA);
;             PG8_BAR; PG8_WAIT_L(0); PG8_MMA(1, 0, At, B0); PG8_BAR; PG8_SCHED;
;             PG8_STAGE(PG8_SB(0, 1), b2 + hstep, voffB);
;             PG8_WAIT_V(6); PG8_BAR; PG8_MMA(1, 1, At, B1); PG8_BAR;
;             PG8_LDB(B0, 1, 0); PG8_SCHED; PG8_LDA(At, 1, 0); PG8_STAGE(PG8_SA(0, 1), a2 + hstep, voffA);
;             PG8_WAIT_L(8); PG8_BAR; PG8_WAIT_L(0); PG8_MMA(0, 0, At, B0); PG8_BAR; PG8_SCHED;
;             PG8_LDB(B1, 1, 1); PG8_STAGE(PG8_SB(1, 0), b3, voffB);
	ds_read_b128 v[200:203], v150
	ds_read_b128 v[204:207], v150 offset:1024
	ds_read_b128 v[208:211], v150 offset:2048
	ds_read_b128 v[212:215], v150 offset:3072
	s_add_i32 s51, s42, s26
	v_lshl_add_u64 v[144:145], s[22:23], 0, v[132:133]
	s_mov_b32 m0, s51
	s_nop 0
	global_load_lds_dwordx4 v[144:145], off
	v_lshl_add_u64 v[216:217], s[22:23], 0, v[128:129]
	s_add_i32 m0, s51, 0x2000
	s_nop 0
	global_load_lds_dwordx4 v[216:217], off
	s_barrier
	s_waitcnt lgkmcnt(0)
	v_mfma_f32_16x16x32_bf16 v[116:119], v[200:203], v[168:171], v[116:119]
	v_mfma_f32_16x16x32_bf16 v[108:111], v[208:211], v[168:171], v[108:111]
	s_mov_b32 m0, s34
	v_lshl_add_u64 v[218:219], s[24:25], 0, v[134:135]
	v_mfma_f32_16x16x32_bf16 v[96:99], v[200:203], v[176:179], v[96:99]
	v_mfma_f32_16x16x32_bf16 v[88:91], v[208:211], v[176:179], v[88:91]
	v_mfma_f32_16x16x32_bf16 v[80:83], v[200:203], v[184:187], v[80:83]
	v_mfma_f32_16x16x32_bf16 v[72:75], v[208:211], v[184:187], v[72:75]
	v_mfma_f32_16x16x32_bf16 v[68:71], v[200:203], v[192:195], v[68:71]
	v_mfma_f32_16x16x32_bf16 v[64:67], v[208:211], v[192:195], v[64:67]
	v_mfma_f32_16x16x32_bf16 v[116:119], v[204:207], v[172:175], v[116:119]
	v_mfma_f32_16x16x32_bf16 v[108:111], v[212:215], v[172:175], v[108:111]
	v_mfma_f32_16x16x32_bf16 v[96:99], v[204:207], v[180:183], v[96:99]
	v_mfma_f32_16x16x32_bf16 v[88:91], v[212:215], v[180:183], v[88:91]
	v_mfma_f32_16x16x32_bf16 v[80:83], v[204:207], v[188:191], v[80:83]
	v_mfma_f32_16x16x32_bf16 v[72:75], v[212:215], v[188:191], v[72:75]
	v_mfma_f32_16x16x32_bf16 v[68:71], v[204:207], v[196:199], v[68:71]
	v_mfma_f32_16x16x32_bf16 v[64:67], v[212:215], v[196:199], v[64:67]
	s_barrier
	ds_read_b128 v[168:171], v149 offset:16384
	ds_read_b128 v[172:175], v149 offset:17408
	ds_read_b128 v[176:179], v149 offset:18432
	ds_read_b128 v[180:183], v149 offset:19456
	ds_read_b128 v[184:187], v149 offset:20480
	ds_read_b128 v[188:191], v149 offset:21504
	ds_read_b128 v[192:195], v149 offset:22528
	ds_read_b128 v[196:199], v149 offset:23552
	global_load_lds_dwordx4 v[218:219], off
	v_lshl_add_u64 v[220:221], s[24:25], 0, v[130:131]
	s_mov_b32 m0, s35
	s_nop 0
	global_load_lds_dwordx4 v[220:221], off
	s_waitcnt vmcnt(10)
	s_barrier
	s_waitcnt lgkmcnt(0)
	v_mfma_f32_16x16x32_bf16 v[60:63], v[152:155], v[168:171], v[60:63]
	v_mfma_f32_16x16x32_bf16 v[56:59], v[160:163], v[168:171], v[56:59]
	v_mfma_f32_16x16x32_bf16 v[52:55], v[152:155], v[176:179], v[52:55]
	v_mfma_f32_16x16x32_bf16 v[44:47], v[160:163], v[176:179], v[44:47]
	v_mfma_f32_16x16x32_bf16 v[36:39], v[152:155], v[184:187], v[36:39]
	v_mfma_f32_16x16x32_bf16 v[28:31], v[160:163], v[184:187], v[28:31]
	v_mfma_f32_16x16x32_bf16 v[20:23], v[152:155], v[192:195], v[20:23]
	v_mfma_f32_16x16x32_bf16 v[12:15], v[160:163], v[192:195], v[12:15]
	v_mfma_f32_16x16x32_bf16 v[60:63], v[156:159], v[172:175], v[60:63]
	v_mfma_f32_16x16x32_bf16 v[56:59], v[164:167], v[172:175], v[56:59]
	v_mfma_f32_16x16x32_bf16 v[52:55], v[156:159], v[180:183], v[52:55]
	v_mfma_f32_16x16x32_bf16 v[44:47], v[164:167], v[180:183], v[44:47]
	v_mfma_f32_16x16x32_bf16 v[36:39], v[156:159], v[188:191], v[36:39]
	v_mfma_f32_16x16x32_bf16 v[28:31], v[164:167], v[188:191], v[28:31]
	v_mfma_f32_16x16x32_bf16 v[20:23], v[156:159], v[196:199], v[20:23]
	v_mfma_f32_16x16x32_bf16 v[12:15], v[164:167], v[196:199], v[12:15]
	s_barrier
	v_add_u32_e32 v152, 0x18000, v147
	ds_read_b128 v[156:159], v152 offset:1024
	ds_read_b128 v[160:163], v152 offset:2048
	ds_read_b128 v[164:167], v152 offset:3072
	ds_read_b128 v[152:155], v152
	s_add_u32 s52, s22, 0x80000
	s_addc_u32 s53, s23, 0
	s_add_i32 s51, s43, s26
	s_mov_b32 m0, s51
	s_nop 0
	global_load_lds_dwordx4 v132, s[52:53]
	s_add_i32 m0, s51, 0x2000
	s_nop 0
	global_load_lds_dwordx4 v128, s[52:53]
	s_waitcnt vmcnt(6)
	s_barrier
	v_mfma_f32_16x16x32_bf16 v[48:51], v[200:203], v[168:171], v[48:51]
	v_mfma_f32_16x16x32_bf16 v[40:43], v[208:211], v[168:171], v[40:43]
	s_add_i32 s51, 0, 0x18000
	v_mfma_f32_16x16x32_bf16 v[32:35], v[200:203], v[176:179], v[32:35]
	v_mfma_f32_16x16x32_bf16 v[24:27], v[208:211], v[176:179], v[24:27]
	v_mfma_f32_16x16x32_bf16 v[16:19], v[200:203], v[184:187], v[16:19]
	v_mfma_f32_16x16x32_bf16 v[8:11], v[208:211], v[184:187], v[8:11]
	v_mfma_f32_16x16x32_bf16 v[4:7], v[200:203], v[192:195], v[4:7]
	v_mfma_f32_16x16x32_bf16 v[0:3], v[208:211], v[192:195], v[0:3]
	v_mfma_f32_16x16x32_bf16 v[48:51], v[204:207], v[172:175], v[48:51]
	v_mfma_f32_16x16x32_bf16 v[40:43], v[212:215], v[172:175], v[40:43]
	v_mfma_f32_16x16x32_bf16 v[32:35], v[204:207], v[180:183], v[32:35]
	v_mfma_f32_16x16x32_bf16 v[24:27], v[212:215], v[180:183], v[24:27]
	v_mfma_f32_16x16x32_bf16 v[16:19], v[204:207], v[188:191], v[16:19]
	v_mfma_f32_16x16x32_bf16 v[8:11], v[212:215], v[188:191], v[8:11]
	v_mfma_f32_16x16x32_bf16 v[4:7], v[204:207], v[196:199], v[4:7]
	v_mfma_f32_16x16x32_bf16 v[0:3], v[212:215], v[196:199], v[0:3]
	s_barrier
	ds_read_b128 v[168:171], v149 offset:32768
	ds_read_b128 v[172:175], v149 offset:33792
	ds_read_b128 v[176:179], v149 offset:34816
	ds_read_b128 v[180:183], v149 offset:35840
	ds_read_b128 v[184:187], v149 offset:36864
	ds_read_b128 v[188:191], v149 offset:37888
	ds_read_b128 v[192:195], v149 offset:38912
	ds_read_b128 v[196:199], v149 offset:39936
	s_add_u32 s24, s24, 0x80000
	s_addc_u32 s25, s25, 0
	s_mov_b32 m0, s38
	v_lshl_add_u64 v[200:201], s[24:25], 0, v[134:135]
	global_load_lds_dwordx4 v[200:201], off
	s_mov_b32 m0, s39
	s_nop 0
	global_load_lds_dwordx4 v130, s[24:25]
	s_waitcnt lgkmcnt(8)
	s_barrier
; __device__ __forceinline__ int lane_id_() { int l; asm volatile("v_mbcnt_lo_u32_b32 %0, -1, 0\n\tv_mbcnt_hi_u32_b32 %0, -1, %0" : "=v"(l)); return l; }
; #define PG8_STAGE(bufoff, gbase, voff) do { _Pragma("unroll") for (int _i = 0; _i < 2; ++_i) \
;         __builtin_amdgcn_global_load_lds((const unsigned*)((const char*)(gbase) + (voff)[_i]), (LAS unsigned*)(lds + (bufoff) + ldsw + _i * 8192), 16, 0, 0); } while (0)
; #define PG8_LDA(dst, b, h) do { _Pragma("unroll") for (int m = 0; m < 4; ++m) _Pragma("unroll") for (int k = 0; k < 2; ++k) dst[m][k] = *(const LAS bf16x8*)(lds + PG8_SA(b, h) + aoff + m * 2048 + k * 1024); } while (0)
; #define PG8_MMA(ai, bj, At, Bt) do { __builtin_amdgcn_s_setprio(1); _Pragma("unroll") for (int m = 0; m < 4; ++m) _Pragma("unroll") for (int n = 0; n < 2; ++n) _Pragma("unroll") for (int k = 0; k < 2; ++k) \
;         acc[ai][bj][m][n] = __builtin_amdgcn_mfma_f32_16x16x32_bf16(Bt[n][k], At[m][k], acc[ai][bj][m][n], 0, 0, 0); __builtin_amdgcn_s_setprio(0); } while (0)
; #define PG8_WAIT_V(n) asm volatile("s_waitcnt vmcnt(" #n ")" ::: "memory")
; #define PG8_BAR __builtin_amdgcn_s_barrier()
; template <class Epi, bool KS0 = false>
; __device__ __forceinline__ void gemm_phase(const int WID, LAS unsigned char* lds, const Gemm g, const StaticOrder& S, const Epi& E) {
;     ...
;             PG8_BAR; PG8_WAIT_L(0); PG8_MMA(0, 1, At, B1); PG8_BAR;
;             PG8_LDA(At, 1, 1); PG8_STAGE(PG8_SA(1, 0), a3, voffA);
;             PG8_BAR; PG8_WAIT_L(0); PG8_MMA(1, 0, At, B0); PG8_BAR; PG8_SCHED;
;             PG8_STAGE(PG8_SB(1, 1), b3 + hstep, voffB);
;             PG8_WAIT_V(6); PG8_BAR; PG8_MMA(1, 1, At, B1); PG8_BAR;
;         }
;         { int fr2 = lane_id_(), fq2; fq2 = fr2 >> 4; fr2 &= 15; asm volatile("" : "+v"(fr2), "+v"(fq2)); E(acc, cur, wr, wc, fr2, fq2); }
;         if (!has_next) break;
;     __device__ __forceinline__ void operator()(f32x4 (&acc)[2][2][4][2], const Unit& u, int wr, int wc, int fr, int fq) const {
;         bf16_t* base; size_t s_ai, s_m, s_bj;
;         if (frag && u.pn >= fmin) { base = O + ((size_t)(u.pm * frag + u.pn) << 16) + (size_t)((((wr * 4 + wc) * 16) * 64 + fq * 16 + fr) << 3); s_ai = 4096; s_m = 1024; s_bj = 512; }
;         else if (frag) { base = O + ((size_t)(u.pm * frag + u.pn) << 16) + (size_t)(((wr * 64 + fr) << 8) + wc * 32 + 8 * fq); s_ai = (size_t)HALF * 256; s_m = 16 * 256; s_bj = HALF; }
	s_waitcnt lgkmcnt(0)
	v_mfma_f32_16x16x32_bf16 v[124:127], v[152:155], v[168:171], v[124:127]
	v_mfma_f32_16x16x32_bf16 v[120:123], v[160:163], v[168:171], v[120:123]
	v_mfma_f32_16x16x32_bf16 v[112:115], v[152:155], v[176:179], v[112:115]
	v_mfma_f32_16x16x32_bf16 v[104:107], v[160:163], v[176:179], v[104:107]
	v_mfma_f32_16x16x32_bf16 v[100:103], v[152:155], v[184:187], v[100:103]
	v_mfma_f32_16x16x32_bf16 v[92:95], v[160:163], v[184:187], v[92:95]
	v_mfma_f32_16x16x32_bf16 v[84:87], v[152:155], v[192:195], v[84:87]
	v_mfma_f32_16x16x32_bf16 v[76:79], v[160:163], v[192:195], v[76:79]
	v_mfma_f32_16x16x32_bf16 v[124:127], v[156:159], v[172:175], v[124:127]
	v_mfma_f32_16x16x32_bf16 v[120:123], v[164:167], v[172:175], v[120:123]
	v_mfma_f32_16x16x32_bf16 v[112:115], v[156:159], v[180:183], v[112:115]
	v_mfma_f32_16x16x32_bf16 v[104:107], v[164:167], v[180:183], v[104:107]
	v_mfma_f32_16x16x32_bf16 v[100:103], v[156:159], v[188:191], v[100:103]
	v_mfma_f32_16x16x32_bf16 v[92:95], v[164:167], v[188:191], v[92:95]
	v_mfma_f32_16x16x32_bf16 v[84:87], v[156:159], v[196:199], v[84:87]
	v_mfma_f32_16x16x32_bf16 v[76:79], v[164:167], v[196:199], v[76:79]
	s_barrier
	s_add_i32 s24, 0, 0x1c000
	v_add_u32_e32 v151, s24, v147
	ds_read_b128 v[200:203], v151
	ds_read_b128 v[204:207], v151 offset:1024
	ds_read_b128 v[208:211], v151 offset:2048
	ds_read_b128 v[212:215], v151 offset:3072
	s_add_i32 s25, s51, s26
	v_lshl_add_u64 v[144:145], v[144:145], 0, s[8:9]
	s_mov_b32 m0, s25
	s_nop 0
	global_load_lds_dwordx4 v[144:145], off
	v_lshl_add_u64 v[144:145], v[216:217], 0, s[8:9]
	s_add_i32 m0, s25, 0x2000
	s_nop 0
	global_load_lds_dwordx4 v[144:145], off
	s_barrier
	s_waitcnt lgkmcnt(0)
	v_mfma_f32_16x16x32_bf16 v[116:119], v[200:203], v[168:171], v[116:119]
	v_mfma_f32_16x16x32_bf16 v[108:111], v[208:211], v[168:171], v[108:111]
	s_mov_b32 m0, s40
	v_lshl_add_u64 v[144:145], v[218:219], 0, s[8:9]
	v_mfma_f32_16x16x32_bf16 v[96:99], v[200:203], v[176:179], v[96:99]
	v_mfma_f32_16x16x32_bf16 v[88:91], v[208:211], v[176:179], v[88:91]
	v_mfma_f32_16x16x32_bf16 v[80:83], v[200:203], v[184:187], v[80:83]
	v_mfma_f32_16x16x32_bf16 v[72:75], v[208:211], v[184:187], v[72:75]
	v_mfma_f32_16x16x32_bf16 v[68:71], v[200:203], v[192:195], v[68:71]
	v_mfma_f32_16x16x32_bf16 v[64:67], v[208:211], v[192:195], v[64:67]
	v_mfma_f32_16x16x32_bf16 v[116:119], v[204:207], v[172:175], v[116:119]
	v_mfma_f32_16x16x32_bf16 v[108:111], v[212:215], v[172:175], v[108:111]
	v_mfma_f32_16x16x32_bf16 v[96:99], v[204:207], v[180:183], v[96:99]
	v_mfma_f32_16x16x32_bf16 v[88:91], v[212:215], v[180:183], v[88:91]
	v_mfma_f32_16x16x32_bf16 v[80:83], v[204:207], v[188:191], v[80:83]
	v_mfma_f32_16x16x32_bf16 v[72:75], v[212:215], v[188:191], v[72:75]
	v_mfma_f32_16x16x32_bf16 v[68:71], v[204:207], v[196:199], v[68:71]
	v_mfma_f32_16x16x32_bf16 v[64:67], v[212:215], v[196:199], v[64:67]
	s_barrier
	ds_read_b128 v[168:171], v149 offset:49152
	ds_read_b128 v[172:175], v149 offset:50176
	ds_read_b128 v[176:179], v149 offset:51200
	ds_read_b128 v[180:183], v149 offset:52224
	ds_read_b128 v[184:187], v149 offset:53248
	ds_read_b128 v[188:191], v149 offset:54272
	ds_read_b128 v[192:195], v149 offset:55296
	ds_read_b128 v[196:199], v149 offset:56320
	global_load_lds_dwordx4 v[144:145], off
	v_lshl_add_u64 v[144:145], v[220:221], 0, s[8:9]
	s_mov_b32 m0, s41
	s_nop 0
	global_load_lds_dwordx4 v[144:145], off
	s_waitcnt vmcnt(10)
	s_barrier
	s_waitcnt lgkmcnt(0)
	v_mfma_f32_16x16x32_bf16 v[60:63], v[152:155], v[168:171], v[60:63]
	v_mfma_f32_16x16x32_bf16 v[56:59], v[160:163], v[168:171], v[56:59]
	v_mfma_f32_16x16x32_bf16 v[52:55], v[152:155], v[176:179], v[52:55]
	v_mfma_f32_16x16x32_bf16 v[44:47], v[160:163], v[176:179], v[44:47]
	v_mfma_f32_16x16x32_bf16 v[36:39], v[152:155], v[184:187], v[36:39]
	v_mfma_f32_16x16x32_bf16 v[28:31], v[160:163], v[184:187], v[28:31]
	v_mfma_f32_16x16x32_bf16 v[20:23], v[152:155], v[192:195], v[20:23]
	v_mfma_f32_16x16x32_bf16 v[12:15], v[160:163], v[192:195], v[12:15]
	v_mfma_f32_16x16x32_bf16 v[60:63], v[156:159], v[172:175], v[60:63]
	v_mfma_f32_16x16x32_bf16 v[56:59], v[164:167], v[172:175], v[56:59]
	v_mfma_f32_16x16x32_bf16 v[52:55], v[156:159], v[180:183], v[52:55]
	v_mfma_f32_16x16x32_bf16 v[44:47], v[164:167], v[180:183], v[44:47]
	v_mfma_f32_16x16x32_bf16 v[36:39], v[156:159], v[188:191], v[36:39]
	v_mfma_f32_16x16x32_bf16 v[28:31], v[164:167], v[188:191], v[28:31]
	v_mfma_f32_16x16x32_bf16 v[20:23], v[156:159], v[196:199], v[20:23]
	v_mfma_f32_16x16x32_bf16 v[12:15], v[164:167], v[196:199], v[12:15]
	s_barrier
	ds_read_b128 v[152:155], v148
	ds_read_b128 v[156:159], v148 offset:1024
	ds_read_b128 v[160:163], v148 offset:2048
	ds_read_b128 v[164:167], v148 offset:3072
	s_add_u32 s22, s22, 0x80080
	s_addc_u32 s23, s23, 0
	s_add_i32 s24, s24, s26
	s_mov_b32 m0, s24
	s_nop 0
	global_load_lds_dwordx4 v132, s[22:23]
	s_add_i32 m0, s24, 0x2000
	s_nop 0
	global_load_lds_dwordx4 v128, s[22:23]
	s_waitcnt vmcnt(6)
	s_barrier
	v_mfma_f32_16x16x32_bf16 v[48:51], v[200:203], v[168:171], v[48:51]
	v_mfma_f32_16x16x32_bf16 v[40:43], v[208:211], v[168:171], v[40:43]
	s_add_i32 s50, s50, 2
	s_add_u32 s20, s20, 0x100
	s_addc_u32 s21, s21, 0
	s_add_u32 s48, s48, 0x100
	s_addc_u32 s49, s49, 0
	s_cmp_gt_u32 s50, 29
	v_mfma_f32_16x16x32_bf16 v[32:35], v[200:203], v[176:179], v[32:35]
	v_mfma_f32_16x16x32_bf16 v[24:27], v[208:211], v[176:179], v[24:27]
	v_mfma_f32_16x16x32_bf16 v[16:19], v[200:203], v[184:187], v[16:19]
	v_mfma_f32_16x16x32_bf16 v[8:11], v[208:211], v[184:187], v[8:11]
	v_mfma_f32_16x16x32_bf16 v[4:7], v[200:203], v[192:195], v[4:7]
	v_mfma_f32_16x16x32_bf16 v[0:3], v[208:211], v[192:195], v[0:3]
	v_mfma_f32_16x16x32_bf16 v[48:51], v[204:207], v[172:175], v[48:51]
	v_mfma_f32_16x16x32_bf16 v[40:43], v[212:215], v[172:175], v[40:43]
	v_mfma_f32_16x16x32_bf16 v[32:35], v[204:207], v[180:183], v[32:35]
	v_mfma_f32_16x16x32_bf16 v[24:27], v[212:215], v[180:183], v[24:27]
	v_mfma_f32_16x16x32_bf16 v[16:19], v[204:207], v[188:191], v[16:19]
	v_mfma_f32_16x16x32_bf16 v[8:11], v[212:215], v[188:191], v[8:11]
	v_mfma_f32_16x16x32_bf16 v[4:7], v[204:207], v[196:199], v[4:7]
	v_mfma_f32_16x16x32_bf16 v[0:3], v[212:215], v[196:199], v[0:3]
	s_barrier
	s_cbranch_scc0 .LBB0_86
	s_waitcnt lgkmcnt(0)
	v_mbcnt_lo_u32_b32 v144, -1, 0
	v_mbcnt_hi_u32_b32 v144, -1, v144
	s_cmp_lt_i32 s45, 8
	v_ashrrev_i32_e32 v145, 4, v144
	v_and_b32_e32 v151, 15, v144
	s_mov_b64 s[20:21], -1
	s_cbranch_scc1 .LBB0_89
	v_add_u32_e32 v144, s55, v151
	v_lshlrev_b32_e32 v152, 7, v145
	v_lshl_add_u32 v144, v144, 3, v152
	s_mov_b64 s[20:21], 0

; #define PG8_STAGE(bufoff, gbase, voff) do { _Pragma("unroll") for (int _i = 0; _i < 2; ++_i) \
;         __builtin_amdgcn_global_load_lds((const unsigned*)((const char*)(gbase) + (voff)[_i]), (LAS unsigned*)(lds + (bufoff) + ldsw + _i * 8192), 16, 0, 0); } while (0)
; #define PG8_LDA(dst, b, h) do { _Pragma("unroll") for (int m = 0; m < 4; ++m) _Pragma("unroll") for (int k = 0; k < 2; ++k) dst[m][k] = *(const LAS bf16x8*)(lds + PG8_SA(b, h) + aoff + m * 2048 + k * 1024); } while (0)
; #define PG8_LDB(dst, b, h) do { _Pragma("unroll") for (int n = 0; n < 2; ++n) _Pragma("unroll") for (int k = 0; k < 2; ++k) dst[n][k] = *(const LAS bf16x8*)(lds + PG8_SB(b, h) + boff + n * 2048 + k * 1024); } while (0)
; #define PG8_MMA(ai, bj, At, Bt) do { __builtin_amdgcn_s_setprio(1); _Pragma("unroll") for (int m = 0; m < 4; ++m) _Pragma("unroll") for (int n = 0; n < 2; ++n) _Pragma("unroll") for (int k = 0; k < 2; ++k) \
;         acc[ai][bj][m][n] = __builtin_amdgcn_mfma_f32_16x16x32_bf16(Bt[n][k], At[m][k], acc[ai][bj][m][n], 0, 0, 0); __builtin_amdgcn_s_setprio(0); } while (0)
; #define PG8_WAIT_L(n) asm volatile("s_waitcnt lgkmcnt(" #n ")" ::: "memory")
; #define PG8_BAR __builtin_amdgcn_s_barrier()
; #define PG8_SCHED __builtin_amdgcn_sched_barrier(0)
; template <class Epi, bool KS0 = false>
; __device__ __forceinline__ void gemm_phase(const int WID, LAS unsigned char* lds, const Gemm g, const StaticOrder& S, const Epi& E) {
;     ...
;         const bool has_next = S.next(ui + 1, nxt);
;         const char* nA = has_next ? (const char*)g.A + (size_t)nxt.pm * tstep : cA; const char* nB = has_next ? (const char*)g.Bt + (size_t)nxt.pn * tstep : cB;
;         for (int t = 0; t < nt; t += 2) {
;             const bool last = (t == nt - 2);
;             const char* a1 = cA + (size_t)(t + 1) * kstep;
;             const char* a2 = last ? nA : cA + (size_t)(t + 2) * kstep; const char* b2 = last ? nB : cB + (size_t)(t + 2) * kstep;
;             const char* a3 = a2 + kstep; const char* b3 = b2 + kstep;
;             PG8_LDB(B0, 0, 0); PG8_SCHED; PG8_LDA(At, 0, 0); PG8_STAGE(PG8_SA(1, 1), a1 + hstep, voffA);
;             PG8_WAIT_L(8); PG8_BAR; PG8_WAIT_L(0); PG8_MMA(0, 0, At, B0); PG8_BAR; PG8_SCHED;
.LBB0_669:
	s_ashr_i32 s11, s10, 31
	v_cmp_lt_i64_e32 vcc, s[12:13], v[188:189]
	s_lshl_b64 s[12:13], s[10:11], 20
	s_add_u32 s12, s30, s12
	s_addc_u32 s13, s31, s13
	s_and_b64 s[14:15], vcc, exec
	s_cselect_b32 s11, s13, s21
	s_cselect_b32 s19, s12, s20
	s_ashr_i32 s9, s8, 31
	s_lshl_b64 s[14:15], s[8:9], 20
	v_readlane_b32 s44, v254, 11
	v_readlane_b32 s45, v254, 12
	s_add_u32 s14, s44, s14
	s_addc_u32 s15, s45, s15
	s_and_b64 s[44:45], vcc, exec
	s_cselect_b32 s9, s15, s43
	s_cselect_b32 s50, s14, s42
	s_add_u32 s20, s20, 0x80080
	s_addc_u32 s21, s21, 0
	s_add_u32 s51, s42, 0x100
	v_mov_b32_e32 v0, 0
	s_addc_u32 s52, s43, 0
	s_mov_b32 s53, -2
	s_waitcnt lgkmcnt(0)
	v_mov_b32_e32 v1, v0
	v_mov_b32_e32 v2, v0
	v_mov_b32_e32 v3, v0
	v_mov_b32_e32 v4, v0
	v_mov_b32_e32 v5, v0
	v_mov_b32_e32 v6, v0
	v_mov_b32_e32 v7, v0
	v_mov_b32_e32 v16, v0
	v_mov_b32_e32 v17, v0
	v_mov_b32_e32 v18, v0
	v_mov_b32_e32 v19, v0
	v_mov_b32_e32 v20, v0
	v_mov_b32_e32 v21, v0
	v_mov_b32_e32 v22, v0
	v_mov_b32_e32 v23, v0
	v_mov_b32_e32 v32, v0
	v_mov_b32_e32 v33, v0
	v_mov_b32_e32 v34, v0
	v_mov_b32_e32 v35, v0
	v_mov_b32_e32 v36, v0
	v_mov_b32_e32 v37, v0
	v_mov_b32_e32 v38, v0
	v_mov_b32_e32 v39, v0
	v_mov_b32_e32 v48, v0
	v_mov_b32_e32 v49, v0
	v_mov_b32_e32 v50, v0
	v_mov_b32_e32 v51, v0
	v_mov_b32_e32 v52, v0
	v_mov_b32_e32 v53, v0
	v_mov_b32_e32 v54, v0
	v_mov_b32_e32 v55, v0
	v_mov_b32_e32 v8, v0
	v_mov_b32_e32 v9, v0
	v_mov_b32_e32 v10, v0
	v_mov_b32_e32 v11, v0
	v_mov_b32_e32 v12, v0
	v_mov_b32_e32 v13, v0
	v_mov_b32_e32 v14, v0
	v_mov_b32_e32 v15, v0
	v_mov_b32_e32 v24, v0
	v_mov_b32_e32 v25, v0
	v_mov_b32_e32 v26, v0
	v_mov_b32_e32 v27, v0
	v_mov_b32_e32 v28, v0
	v_mov_b32_e32 v29, v0
	v_mov_b32_e32 v30, v0
	v_mov_b32_e32 v31, v0
	v_mov_b32_e32 v40, v0
	v_mov_b32_e32 v41, v0
	v_mov_b32_e32 v42, v0
	v_mov_b32_e32 v43, v0
	v_mov_b32_e32 v44, v0
	v_mov_b32_e32 v45, v0
	v_mov_b32_e32 v46, v0
	v_mov_b32_e32 v47, v0
	v_mov_b32_e32 v56, v0
	v_mov_b32_e32 v57, v0
	v_mov_b32_e32 v58, v0
	v_mov_b32_e32 v59, v0
	v_mov_b32_e32 v60, v0
	v_mov_b32_e32 v61, v0
	v_mov_b32_e32 v62, v0
	v_mov_b32_e32 v63, v0
	v_mov_b32_e32 v64, v0
	v_mov_b32_e32 v65, v0
	v_mov_b32_e32 v66, v0
	v_mov_b32_e32 v67, v0
	v_mov_b32_e32 v68, v0
	v_mov_b32_e32 v69, v0
	v_mov_b32_e32 v70, v0
	v_mov_b32_e32 v71, v0
	v_mov_b32_e32 v80, v0
	v_mov_b32_e32 v81, v0
	v_mov_b32_e32 v82, v0
	v_mov_b32_e32 v83, v0
	v_mov_b32_e32 v84, v0
	v_mov_b32_e32 v85, v0
	v_mov_b32_e32 v86, v0
	v_mov_b32_e32 v87, v0
	v_mov_b32_e32 v96, v0
	v_mov_b32_e32 v97, v0
	v_mov_b32_e32 v98, v0
	v_mov_b32_e32 v99, v0
	v_mov_b32_e32 v100, v0
	v_mov_b32_e32 v101, v0
	v_mov_b32_e32 v102, v0
	v_mov_b32_e32 v103, v0
	v_mov_b32_e32 v112, v0
	v_mov_b32_e32 v113, v0
	v_mov_b32_e32 v114, v0
	v_mov_b32_e32 v115, v0
	v_mov_b32_e32 v116, v0
	v_mov_b32_e32 v117, v0
	v_mov_b32_e32 v118, v0
	v_mov_b32_e32 v119, v0
	v_mov_b32_e32 v72, v0
	v_mov_b32_e32 v73, v0
	v_mov_b32_e32 v74, v0
	v_mov_b32_e32 v75, v0
	v_mov_b32_e32 v76, v0
	v_mov_b32_e32 v77, v0
	v_mov_b32_e32 v78, v0
	v_mov_b32_e32 v79, v0
	v_mov_b32_e32 v88, v0
	v_mov_b32_e32 v89, v0
	v_mov_b32_e32 v90, v0
	v_mov_b32_e32 v91, v0
	v_mov_b32_e32 v92, v0
	v_mov_b32_e32 v93, v0
	v_mov_b32_e32 v94, v0
	v_mov_b32_e32 v95, v0
	v_mov_b32_e32 v104, v0
	v_mov_b32_e32 v105, v0
	v_mov_b32_e32 v106, v0
	v_mov_b32_e32 v107, v0
	v_mov_b32_e32 v108, v0
	v_mov_b32_e32 v109, v0
	v_mov_b32_e32 v110, v0
	v_mov_b32_e32 v111, v0
	v_mov_b32_e32 v120, v0
	v_mov_b32_e32 v121, v0
	v_mov_b32_e32 v122, v0
	v_mov_b32_e32 v123, v0
	v_mov_b32_e32 v124, v0
	v_mov_b32_e32 v125, v0
	v_mov_b32_e32 v126, v0
	v_mov_b32_e32 v127, v0
	ds_read_b128 v[128:131], v206
	ds_read_b128 v[132:135], v206 offset:1024
	ds_read_b128 v[136:139], v206 offset:2048
	ds_read_b128 v[140:143], v206 offset:3072
.LBB0_670:
	ds_read_b128 v[144:147], v207
	ds_read_b128 v[148:151], v207 offset:1024
	ds_read_b128 v[152:155], v207 offset:2048
	ds_read_b128 v[156:159], v207 offset:3072
	ds_read_b128 v[160:163], v207 offset:4096
	ds_read_b128 v[164:167], v207 offset:5120
	ds_read_b128 v[168:171], v207 offset:6144
	ds_read_b128 v[172:175], v207 offset:7168
	s_add_u32 s42, s20, 0xfff80080
	s_addc_u32 s43, s21, -1
	s_cmp_eq_u32 s53, 28
	s_cselect_b32 s45, s11, s43
	s_cselect_b32 s44, s19, s42
	s_cselect_b32 s43, s9, s52
	s_cselect_b32 s42, s50, s51
	v_lshl_add_u64 v[192:193], s[20:21], 0, v[184:185]
	s_add_i32 m0, s23, 0xc000
	s_nop 0
	global_load_lds_dwordx4 v[192:193], off
	s_add_i32 m0, s23, 0xe000
	s_nop 0
	global_load_lds_dwordx4 v186, s[20:21]
	s_waitcnt lgkmcnt(8)
	s_barrier
	s_waitcnt lgkmcnt(0)
	v_mfma_f32_16x16x32_bf16 v[124:127], v[128:131], v[144:147], v[124:127]
	v_mfma_f32_16x16x32_bf16 v[120:123], v[136:139], v[144:147], v[120:123]
	v_mfma_f32_16x16x32_bf16 v[108:111], v[128:131], v[152:155], v[108:111]
	v_mfma_f32_16x16x32_bf16 v[104:107], v[136:139], v[152:155], v[104:107]
	v_mfma_f32_16x16x32_bf16 v[92:95], v[128:131], v[160:163], v[92:95]
	v_mfma_f32_16x16x32_bf16 v[88:91], v[136:139], v[160:163], v[88:91]
	v_mfma_f32_16x16x32_bf16 v[76:79], v[128:131], v[168:171], v[76:79]
	v_mfma_f32_16x16x32_bf16 v[72:75], v[136:139], v[168:171], v[72:75]
	v_mfma_f32_16x16x32_bf16 v[124:127], v[132:135], v[148:151], v[124:127]
	v_mfma_f32_16x16x32_bf16 v[120:123], v[140:143], v[148:151], v[120:123]
	v_mfma_f32_16x16x32_bf16 v[108:111], v[132:135], v[156:159], v[108:111]
	v_mfma_f32_16x16x32_bf16 v[104:107], v[140:143], v[156:159], v[104:107]
	v_mfma_f32_16x16x32_bf16 v[92:95], v[132:135], v[164:167], v[92:95]
	v_mfma_f32_16x16x32_bf16 v[88:91], v[140:143], v[164:167], v[88:91]
	v_mfma_f32_16x16x32_bf16 v[76:79], v[132:135], v[172:175], v[76:79]
	v_mfma_f32_16x16x32_bf16 v[72:75], v[140:143], v[172:175], v[72:75]
	s_barrier
; #define PG8_STAGE(bufoff, gbase, voff) do { _Pragma("unroll") for (int _i = 0; _i < 2; ++_i) \
;         __builtin_amdgcn_global_load_lds((const unsigned*)((const char*)(gbase) + (voff)[_i]), (LAS unsigned*)(lds + (bufoff) + ldsw + _i * 8192), 16, 0, 0); } while (0)
; #define PG8_LDA(dst, b, h) do { _Pragma("unroll") for (int m = 0; m < 4; ++m) _Pragma("unroll") for (int k = 0; k < 2; ++k) dst[m][k] = *(const LAS bf16x8*)(lds + PG8_SA(b, h) + aoff + m * 2048 + k * 1024); } while (0)
; #define PG8_LDB(dst, b, h) do { _Pragma("unroll") for (int n = 0; n < 2; ++n) _Pragma("unroll") for (int k = 0; k < 2; ++k) dst[n][k] = *(const LAS bf16x8*)(lds + PG8_SB(b, h) + boff + n * 2048 + k * 1024); } while (0)
; #define PG8_MMA(ai, bj, At, Bt) do { __builtin_amdgcn_s_setprio(1); _Pragma("unroll") for (int m = 0; m < 4; ++m) _Pragma("unroll") for (int n = 0; n < 2; ++n) _Pragma("unroll") for (int k = 0; k < 2; ++k) \
;         acc[ai][bj][m][n] = __builtin_amdgcn_mfma_f32_16x16x32_bf16(Bt[n][k], At[m][k], acc[ai][bj][m][n], 0, 0, 0); __builtin_amdgcn_s_setprio(0); } while (0)
; #define PG8_WAIT_V(n) asm volatile("s_waitcnt vmcnt(" #n ")" ::: "memory")
; #define PG8_WAIT_L(n) asm volatile("s_waitcnt lgkmcnt(" #n ")" ::: "memory")
; #define PG8_BAR __builtin_amdgcn_s_barrier()
; #define PG8_SCHED __builtin_amdgcn_sched_barrier(0)
; template <class Epi, bool KS0 = false>
; __device__ __forceinline__ void gemm_phase(const int WID, LAS unsigned char* lds, const Gemm g, const StaticOrder& S, const Epi& E) {
;     ...
;             PG8_LDB(B1, 0, 1); PG8_STAGE(PG8_SB(0, 0), b2, voffB);
;             PG8_BAR; PG8_WAIT_L(0); PG8_MMA(0, 1, At, B1); PG8_BAR;
;             PG8_LDA(At, 0, 1); PG8_STAGE(PG8_SA(0, 0), a2, voffA);
;             PG8_BAR; PG8_WAIT_L(0); PG8_MMA(1, 0, At, B0); PG8_BAR; PG8_SCHED;
;             PG8_STAGE(PG8_SB(0, 1), b2 + hstep, voffB);
;             PG8_WAIT_V(6); PG8_BAR; PG8_MMA(1, 1, At, B1); PG8_BAR;
;             PG8_LDB(B0, 1, 0); PG8_SCHED; PG8_LDA(At, 1, 0); PG8_STAGE(PG8_SA(0, 1), a2 + hstep, voffA);
;             PG8_WAIT_L(8); PG8_BAR; PG8_WAIT_L(0); PG8_MMA(0, 0, At, B0); PG8_BAR; PG8_SCHED;
;             PG8_LDB(B1, 1, 1); PG8_STAGE(PG8_SB(1, 0), b3, voffB);
	ds_read_b128 v[192:195], v208
	ds_read_b128 v[196:199], v208 offset:1024
	ds_read_b128 v[200:203], v208 offset:2048
	ds_read_b128 v[210:213], v208 offset:3072
	s_add_i32 s54, s35, s26
	v_lshl_add_u64 v[214:215], s[42:43], 0, v[178:179]
	s_mov_b32 m0, s54
	s_nop 0
	global_load_lds_dwordx4 v[214:215], off
	v_lshl_add_u64 v[216:217], s[42:43], 0, v[182:183]
	s_add_i32 m0, s54, 0x2000
	s_nop 0
	global_load_lds_dwordx4 v[216:217], off
	s_barrier
	s_waitcnt lgkmcnt(0)
	v_mfma_f32_16x16x32_bf16 v[116:119], v[192:195], v[144:147], v[116:119]
	v_mfma_f32_16x16x32_bf16 v[112:115], v[200:203], v[144:147], v[112:115]
	s_mov_b32 m0, s23
	v_lshl_add_u64 v[218:219], s[44:45], 0, v[176:177]
	v_mfma_f32_16x16x32_bf16 v[100:103], v[192:195], v[152:155], v[100:103]
	v_mfma_f32_16x16x32_bf16 v[96:99], v[200:203], v[152:155], v[96:99]
	v_mfma_f32_16x16x32_bf16 v[84:87], v[192:195], v[160:163], v[84:87]
	v_mfma_f32_16x16x32_bf16 v[80:83], v[200:203], v[160:163], v[80:83]
	v_mfma_f32_16x16x32_bf16 v[68:71], v[192:195], v[168:171], v[68:71]
	v_mfma_f32_16x16x32_bf16 v[64:67], v[200:203], v[168:171], v[64:67]
	v_mfma_f32_16x16x32_bf16 v[116:119], v[196:199], v[148:151], v[116:119]
	v_mfma_f32_16x16x32_bf16 v[112:115], v[210:213], v[148:151], v[112:115]
	v_mfma_f32_16x16x32_bf16 v[100:103], v[196:199], v[156:159], v[100:103]
	v_mfma_f32_16x16x32_bf16 v[96:99], v[210:213], v[156:159], v[96:99]
	v_mfma_f32_16x16x32_bf16 v[84:87], v[196:199], v[164:167], v[84:87]
	v_mfma_f32_16x16x32_bf16 v[80:83], v[210:213], v[164:167], v[80:83]
	v_mfma_f32_16x16x32_bf16 v[68:71], v[196:199], v[172:175], v[68:71]
	v_mfma_f32_16x16x32_bf16 v[64:67], v[210:213], v[172:175], v[64:67]
	s_barrier
	ds_read_b128 v[144:147], v207 offset:16384
	ds_read_b128 v[148:151], v207 offset:17408
	ds_read_b128 v[152:155], v207 offset:18432
	ds_read_b128 v[156:159], v207 offset:19456
	ds_read_b128 v[160:163], v207 offset:20480
	ds_read_b128 v[164:167], v207 offset:21504
	ds_read_b128 v[168:171], v207 offset:22528
	ds_read_b128 v[172:175], v207 offset:23552
	global_load_lds_dwordx4 v[218:219], off
	v_lshl_add_u64 v[220:221], s[44:45], 0, v[180:181]
	s_mov_b32 m0, s24
	s_nop 0
	global_load_lds_dwordx4 v[220:221], off
	s_waitcnt vmcnt(10)
	s_barrier
	s_waitcnt lgkmcnt(0)
	v_mfma_f32_16x16x32_bf16 v[60:63], v[128:131], v[144:147], v[60:63]
	v_mfma_f32_16x16x32_bf16 v[56:59], v[136:139], v[144:147], v[56:59]
	v_mfma_f32_16x16x32_bf16 v[44:47], v[128:131], v[152:155], v[44:47]
	v_mfma_f32_16x16x32_bf16 v[40:43], v[136:139], v[152:155], v[40:43]
	v_mfma_f32_16x16x32_bf16 v[28:31], v[128:131], v[160:163], v[28:31]
	v_mfma_f32_16x16x32_bf16 v[24:27], v[136:139], v[160:163], v[24:27]
	v_mfma_f32_16x16x32_bf16 v[12:15], v[128:131], v[168:171], v[12:15]
	v_mfma_f32_16x16x32_bf16 v[8:11], v[136:139], v[168:171], v[8:11]
	v_mfma_f32_16x16x32_bf16 v[60:63], v[132:135], v[148:151], v[60:63]
	v_mfma_f32_16x16x32_bf16 v[56:59], v[140:143], v[148:151], v[56:59]
	v_mfma_f32_16x16x32_bf16 v[44:47], v[132:135], v[156:159], v[44:47]
	v_mfma_f32_16x16x32_bf16 v[40:43], v[140:143], v[156:159], v[40:43]
	v_mfma_f32_16x16x32_bf16 v[28:31], v[132:135], v[164:167], v[28:31]
	v_mfma_f32_16x16x32_bf16 v[24:27], v[140:143], v[164:167], v[24:27]
	v_mfma_f32_16x16x32_bf16 v[12:15], v[132:135], v[172:175], v[12:15]
	v_mfma_f32_16x16x32_bf16 v[8:11], v[140:143], v[172:175], v[8:11]
	s_barrier
	v_add_u32_e32 v128, 0x18000, v205
	ds_read_b128 v[132:135], v128 offset:1024
	ds_read_b128 v[136:139], v128 offset:2048
	ds_read_b128 v[140:143], v128 offset:3072
	ds_read_b128 v[128:131], v128
	s_add_u32 s54, s42, 0x80000
	s_addc_u32 s55, s43, 0
	s_add_i32 s58, s48, s26
	s_mov_b32 m0, s58
	s_nop 0
	global_load_lds_dwordx4 v178, s[54:55]
	s_add_i32 m0, s58, 0x2000
	s_nop 0
	global_load_lds_dwordx4 v182, s[54:55]
	s_waitcnt vmcnt(6)
	s_barrier
	v_mfma_f32_16x16x32_bf16 v[52:55], v[192:195], v[144:147], v[52:55]
	v_mfma_f32_16x16x32_bf16 v[48:51], v[200:203], v[144:147], v[48:51]
	s_add_i32 s54, 0, 0x18000
	v_mfma_f32_16x16x32_bf16 v[36:39], v[192:195], v[152:155], v[36:39]
	v_mfma_f32_16x16x32_bf16 v[32:35], v[200:203], v[152:155], v[32:35]
	v_mfma_f32_16x16x32_bf16 v[20:23], v[192:195], v[160:163], v[20:23]
	v_mfma_f32_16x16x32_bf16 v[16:19], v[200:203], v[160:163], v[16:19]
	v_mfma_f32_16x16x32_bf16 v[4:7], v[192:195], v[168:171], v[4:7]
	v_mfma_f32_16x16x32_bf16 v[0:3], v[200:203], v[168:171], v[0:3]
	v_mfma_f32_16x16x32_bf16 v[52:55], v[196:199], v[148:151], v[52:55]
	v_mfma_f32_16x16x32_bf16 v[48:51], v[210:213], v[148:151], v[48:51]
	v_mfma_f32_16x16x32_bf16 v[36:39], v[196:199], v[156:159], v[36:39]
	v_mfma_f32_16x16x32_bf16 v[32:35], v[210:213], v[156:159], v[32:35]
	v_mfma_f32_16x16x32_bf16 v[20:23], v[196:199], v[164:167], v[20:23]
	v_mfma_f32_16x16x32_bf16 v[16:19], v[210:213], v[164:167], v[16:19]
	v_mfma_f32_16x16x32_bf16 v[4:7], v[196:199], v[172:175], v[4:7]
	v_mfma_f32_16x16x32_bf16 v[0:3], v[210:213], v[172:175], v[0:3]
	s_barrier
	ds_read_b128 v[144:147], v207 offset:32768
	ds_read_b128 v[148:151], v207 offset:33792
	ds_read_b128 v[152:155], v207 offset:34816
	ds_read_b128 v[156:159], v207 offset:35840
	ds_read_b128 v[160:163], v207 offset:36864
	ds_read_b128 v[164:167], v207 offset:37888
	ds_read_b128 v[168:171], v207 offset:38912
	ds_read_b128 v[172:175], v207 offset:39936
	s_add_u32 s44, s44, 0x80000
	s_addc_u32 s45, s45, 0
	s_mov_b32 m0, s25
	v_lshl_add_u64 v[192:193], s[44:45], 0, v[176:177]
	global_load_lds_dwordx4 v[192:193], off
	s_mov_b32 m0, s28
	s_nop 0
	global_load_lds_dwordx4 v180, s[44:45]
	s_waitcnt lgkmcnt(8)
	s_barrier
; #define PG8_STAGE(bufoff, gbase, voff) do { _Pragma("unroll") for (int _i = 0; _i < 2; ++_i) \
;         __builtin_amdgcn_global_load_lds((const unsigned*)((const char*)(gbase) + (voff)[_i]), (LAS unsigned*)(lds + (bufoff) + ldsw + _i * 8192), 16, 0, 0); } while (0)
; #define PG8_LDA(dst, b, h) do { _Pragma("unroll") for (int m = 0; m < 4; ++m) _Pragma("unroll") for (int k = 0; k < 2; ++k) dst[m][k] = *(const LAS bf16x8*)(lds + PG8_SA(b, h) + aoff + m * 2048 + k * 1024); } while (0)
; #define PG8_MMA(ai, bj, At, Bt) do { __builtin_amdgcn_s_setprio(1); _Pragma("unroll") for (int m = 0; m < 4; ++m) _Pragma("unroll") for (int n = 0; n < 2; ++n) _Pragma("unroll") for (int k = 0; k < 2; ++k) \
;         acc[ai][bj][m][n] = __builtin_amdgcn_mfma_f32_16x16x32_bf16(Bt[n][k], At[m][k], acc[ai][bj][m][n], 0, 0, 0); __builtin_amdgcn_s_setprio(0); } while (0)
; #define PG8_WAIT_L(n) asm volatile("s_waitcnt lgkmcnt(" #n ")" ::: "memory")
; #define PG8_BAR __builtin_amdgcn_s_barrier()
; #define PG8_SCHED __builtin_amdgcn_sched_barrier(0)
; template <class Epi, bool KS0 = false>
; __device__ __forceinline__ void gemm_phase(const int WID, LAS unsigned char* lds, const Gemm g, const StaticOrder& S, const Epi& E) {
;     ...
;             PG8_BAR; PG8_WAIT_L(0); PG8_MMA(0, 1, At, B1); PG8_BAR;
;             PG8_LDA(At, 1, 1); PG8_STAGE(PG8_SA(1, 0), a3, voffA);
;             PG8_BAR; PG8_WAIT_L(0); PG8_MMA(1, 0, At, B0); PG8_BAR; PG8_SCHED;
;             PG8_STAGE(PG8_SB(1, 1), b3 + hstep, voffB);
	s_waitcnt lgkmcnt(0)
	v_mfma_f32_16x16x32_bf16 v[124:127], v[128:131], v[144:147], v[124:127]
	v_mfma_f32_16x16x32_bf16 v[120:123], v[136:139], v[144:147], v[120:123]
	v_mfma_f32_16x16x32_bf16 v[108:111], v[128:131], v[152:155], v[108:111]
	v_mfma_f32_16x16x32_bf16 v[104:107], v[136:139], v[152:155], v[104:107]
	v_mfma_f32_16x16x32_bf16 v[92:95], v[128:131], v[160:163], v[92:95]
	v_mfma_f32_16x16x32_bf16 v[88:91], v[136:139], v[160:163], v[88:91]
	v_mfma_f32_16x16x32_bf16 v[76:79], v[128:131], v[168:171], v[76:79]
	v_mfma_f32_16x16x32_bf16 v[72:75], v[136:139], v[168:171], v[72:75]
	v_mfma_f32_16x16x32_bf16 v[124:127], v[132:135], v[148:151], v[124:127]
	v_mfma_f32_16x16x32_bf16 v[120:123], v[140:143], v[148:151], v[120:123]
	v_mfma_f32_16x16x32_bf16 v[108:111], v[132:135], v[156:159], v[108:111]
	v_mfma_f32_16x16x32_bf16 v[104:107], v[140:143], v[156:159], v[104:107]
	v_mfma_f32_16x16x32_bf16 v[92:95], v[132:135], v[164:167], v[92:95]
	v_mfma_f32_16x16x32_bf16 v[88:91], v[140:143], v[164:167], v[88:91]
	v_mfma_f32_16x16x32_bf16 v[76:79], v[132:135], v[172:175], v[76:79]
	v_mfma_f32_16x16x32_bf16 v[72:75], v[140:143], v[172:175], v[72:75]
	s_barrier
	s_add_i32 s44, 0, 0x1c000
	v_add_u32_e32 v210, s44, v205
	ds_read_b128 v[192:195], v210
	ds_read_b128 v[196:199], v210 offset:1024
	ds_read_b128 v[200:203], v210 offset:2048
	ds_read_b128 v[210:213], v210 offset:3072
	s_add_i32 s45, s54, s26
	v_lshl_add_u64 v[214:215], v[214:215], 0, s[0:1]
	s_mov_b32 m0, s45
	s_nop 0
	global_load_lds_dwordx4 v[214:215], off
	v_lshl_add_u64 v[214:215], v[216:217], 0, s[0:1]
	s_add_i32 m0, s45, 0x2000
	s_nop 0
	global_load_lds_dwordx4 v[214:215], off
	s_barrier
	s_waitcnt lgkmcnt(0)
	v_mfma_f32_16x16x32_bf16 v[116:119], v[192:195], v[144:147], v[116:119]
	v_mfma_f32_16x16x32_bf16 v[112:115], v[200:203], v[144:147], v[112:115]
	s_mov_b32 m0, s29
	v_lshl_add_u64 v[214:215], v[218:219], 0, s[0:1]
	v_mfma_f32_16x16x32_bf16 v[100:103], v[192:195], v[152:155], v[100:103]
	v_mfma_f32_16x16x32_bf16 v[96:99], v[200:203], v[152:155], v[96:99]
	v_mfma_f32_16x16x32_bf16 v[84:87], v[192:195], v[160:163], v[84:87]
	v_mfma_f32_16x16x32_bf16 v[80:83], v[200:203], v[160:163], v[80:83]
	v_mfma_f32_16x16x32_bf16 v[68:71], v[192:195], v[168:171], v[68:71]
	v_mfma_f32_16x16x32_bf16 v[64:67], v[200:203], v[168:171], v[64:67]
	v_mfma_f32_16x16x32_bf16 v[116:119], v[196:199], v[148:151], v[116:119]
	v_mfma_f32_16x16x32_bf16 v[112:115], v[210:213], v[148:151], v[112:115]
	v_mfma_f32_16x16x32_bf16 v[100:103], v[196:199], v[156:159], v[100:103]
	v_mfma_f32_16x16x32_bf16 v[96:99], v[210:213], v[156:159], v[96:99]
	v_mfma_f32_16x16x32_bf16 v[84:87], v[196:199], v[164:167], v[84:87]
	v_mfma_f32_16x16x32_bf16 v[80:83], v[210:213], v[164:167], v[80:83]
	v_mfma_f32_16x16x32_bf16 v[68:71], v[196:199], v[172:175], v[68:71]
	v_mfma_f32_16x16x32_bf16 v[64:67], v[210:213], v[172:175], v[64:67]
	s_barrier
	ds_read_b128 v[144:147], v207 offset:49152
	ds_read_b128 v[148:151], v207 offset:50176
	ds_read_b128 v[152:155], v207 offset:51200
	ds_read_b128 v[156:159], v207 offset:52224
	ds_read_b128 v[160:163], v207 offset:53248
	ds_read_b128 v[164:167], v207 offset:54272
	ds_read_b128 v[168:171], v207 offset:55296
	ds_read_b128 v[172:175], v207 offset:56320
	global_load_lds_dwordx4 v[214:215], off
	v_lshl_add_u64 v[214:215], v[220:221], 0, s[0:1]
	s_mov_b32 m0, s34
	s_nop 0
	global_load_lds_dwordx4 v[214:215], off
	s_waitcnt vmcnt(10)
	s_barrier
	s_waitcnt lgkmcnt(0)
	v_mfma_f32_16x16x32_bf16 v[60:63], v[128:131], v[144:147], v[60:63]
	v_mfma_f32_16x16x32_bf16 v[56:59], v[136:139], v[144:147], v[56:59]
	v_mfma_f32_16x16x32_bf16 v[44:47], v[128:131], v[152:155], v[44:47]
	v_mfma_f32_16x16x32_bf16 v[40:43], v[136:139], v[152:155], v[40:43]
	v_mfma_f32_16x16x32_bf16 v[28:31], v[128:131], v[160:163], v[28:31]
	v_mfma_f32_16x16x32_bf16 v[24:27], v[136:139], v[160:163], v[24:27]
	v_mfma_f32_16x16x32_bf16 v[12:15], v[128:131], v[168:171], v[12:15]
	v_mfma_f32_16x16x32_bf16 v[8:11], v[136:139], v[168:171], v[8:11]
	v_mfma_f32_16x16x32_bf16 v[60:63], v[132:135], v[148:151], v[60:63]
	v_mfma_f32_16x16x32_bf16 v[56:59], v[140:143], v[148:151], v[56:59]
	v_mfma_f32_16x16x32_bf16 v[44:47], v[132:135], v[156:159], v[44:47]
	v_mfma_f32_16x16x32_bf16 v[40:43], v[140:143], v[156:159], v[40:43]
	v_mfma_f32_16x16x32_bf16 v[28:31], v[132:135], v[164:167], v[28:31]
	v_mfma_f32_16x16x32_bf16 v[24:27], v[140:143], v[164:167], v[24:27]
	v_mfma_f32_16x16x32_bf16 v[12:15], v[132:135], v[172:175], v[12:15]
	v_mfma_f32_16x16x32_bf16 v[8:11], v[140:143], v[172:175], v[8:11]
	s_barrier
	ds_read_b128 v[128:131], v206
	ds_read_b128 v[132:135], v206 offset:1024
	ds_read_b128 v[136:139], v206 offset:2048
	ds_read_b128 v[140:143], v206 offset:3072
	s_add_u32 s42, s42, 0x80080
	s_addc_u32 s43, s43, 0
	s_add_i32 s44, s44, s26
	s_mov_b32 m0, s44
	s_nop 0
	global_load_lds_dwordx4 v178, s[42:43]
	s_add_i32 m0, s44, 0x2000
	s_nop 0
	global_load_lds_dwordx4 v182, s[42:43]
	s_waitcnt vmcnt(6)
	s_barrier
; __device__ __forceinline__ unsigned cvt_pk_bf16(float lo, float hi) { unsigned r; asm volatile("v_cvt_pk_bf16_f32 %0, %1, %2" : "=v"(r) : "v"(lo), "v"(hi)); return r; }
; __device__ __forceinline__ float bflo(unsigned w) { return __uint_as_float(w << 16); }
; __device__ __forceinline__ float bfhi(unsigned w) { return __uint_as_float(w & 0xffff0000u); }
; template <class Epi, bool KS0 = false>
; __device__ __forceinline__ void gemm_phase(const int WID, LAS unsigned char* lds, const Gemm g, const StaticOrder& S, const Epi& E) {
;     ...
;             PG8_WAIT_V(6); PG8_BAR; PG8_MMA(1, 1, At, B1); PG8_BAR;
;     __device__ __forceinline__ void operator()(f32x4 (&acc)[2][2][4][2], const Unit& u, int wr, int wc, int fr, int fq) const {
;         const int row0 = u.pm * BM + wr * 64 + fr, col0 = u.pn * BM + wc * 32 + 8 * fq;
; #pragma unroll
;         for (int ai = 0; ai < 2; ++ai) {
;             f32x4 r[4][2][2];
; #pragma unroll
;             for (int m = 0; m < 4; ++m)
; #pragma unroll
;                 for (int bj = 0; bj < 2; ++bj) { const size_t o = (size_t)(row0 + ai * HALF + m * 16) * DM + col0 + bj * HALF;
;                     if (RB) { const u32x4 w = *(const u32x4*)((const bf16_t*)res + o); r[m][bj][0] = (f32x4){bflo(w.x), bfhi(w.x), bflo(w.y), bfhi(w.y)}; r[m][bj][1] = (f32x4){bflo(w.z), bfhi(w.z), bflo(w.w), bfhi(w.w)}; }
;                     else { r[m][bj][0] = __builtin_nontemporal_load((const f32x4*)((const float*)res + o)); r[m][bj][1] = __builtin_nontemporal_load((const f32x4*)((const float*)res + o + 4)); } }
; #pragma unroll
;             for (int m = 0; m < 4; ++m) { const int row = row0 + ai * HALF + m * 16; const size_t off = (size_t)row * DM + col0; float s = 0.f;
; #pragma unroll
;                 for (int bj = 0; bj < 2; ++bj) { const f32x4 v0 = acc[ai][bj][m][0] + r[m][bj][0], v1 = acc[ai][bj][m][1] + r[m][bj][1];
;                     u32x4 w; w.x = cvt_pk_bf16(v0[0], v0[1]); w.y = cvt_pk_bf16(v0[2], v0[3]); w.z = cvt_pk_bf16(v1[0], v1[1]); w.w = cvt_pk_bf16(v1[2], v1[3]);
;                     *(u32x4*)(outb + off + bj * HALF) = w;
;                     s += ((v0[0] * v0[0] + v0[1] * v0[1]) + (v0[2] * v0[2] + v0[3] * v0[3])) + ((v1[0] * v1[0] + v1[1] * v1[1]) + (v1[2] * v1[2] + v1[3] * v1[3])); }
;                 s += __shfl_xor(s, 16); s += __shfl_xor(s, 32);
;                 if (fq == 0) ssq[(size_t)row * 32 + u.pn * 4 + wc] = s; }
	v_mfma_f32_16x16x32_bf16 v[52:55], v[192:195], v[144:147], v[52:55]
	v_mfma_f32_16x16x32_bf16 v[48:51], v[200:203], v[144:147], v[48:51]
	s_add_i32 s53, s53, 2
	s_add_u32 s20, s20, 0x100
	s_addc_u32 s21, s21, 0
	s_add_u32 s51, s51, 0x100
	s_addc_u32 s52, s52, 0
	s_cmp_gt_u32 s53, 29
	v_mfma_f32_16x16x32_bf16 v[36:39], v[192:195], v[152:155], v[36:39]
	v_mfma_f32_16x16x32_bf16 v[32:35], v[200:203], v[152:155], v[32:35]
	v_mfma_f32_16x16x32_bf16 v[20:23], v[192:195], v[160:163], v[20:23]
	v_mfma_f32_16x16x32_bf16 v[16:19], v[200:203], v[160:163], v[16:19]
	v_mfma_f32_16x16x32_bf16 v[4:7], v[192:195], v[168:171], v[4:7]
	v_mfma_f32_16x16x32_bf16 v[0:3], v[200:203], v[168:171], v[0:3]
	v_mfma_f32_16x16x32_bf16 v[52:55], v[196:199], v[148:151], v[52:55]
	v_mfma_f32_16x16x32_bf16 v[48:51], v[210:213], v[148:151], v[48:51]
	v_mfma_f32_16x16x32_bf16 v[36:39], v[196:199], v[156:159], v[36:39]
	v_mfma_f32_16x16x32_bf16 v[32:35], v[210:213], v[156:159], v[32:35]
	v_mfma_f32_16x16x32_bf16 v[20:23], v[196:199], v[164:167], v[20:23]
	v_mfma_f32_16x16x32_bf16 v[16:19], v[210:213], v[164:167], v[16:19]
	v_mfma_f32_16x16x32_bf16 v[4:7], v[196:199], v[172:175], v[4:7]
	v_mfma_f32_16x16x32_bf16 v[0:3], v[210:213], v[172:175], v[0:3]
	s_barrier
	s_cbranch_scc0 .LBB0_670
	s_waitcnt lgkmcnt(0)
	v_mbcnt_lo_u32_b32 v128, -1, 0
	v_mbcnt_hi_u32_b32 v128, -1, v128
	s_lshl_b32 s9, s18, 8
	v_ashrrev_i32_e32 v210, 4, v128
	v_and_b32_e32 v128, 15, v128
	s_add_i32 s9, s9, s22
	v_readlane_b32 s11, v254, 19
	v_add_u32_e32 v194, s9, v128
	s_lshl_b32 s9, s2, 8
	s_or_b32 s9, s9, s11
	v_lshl_add_u32 v192, v210, 3, s9
	v_ashrrev_i32_e32 v193, 31, v192
	v_ashrrev_i32_e32 v195, 31, v194
	v_lshl_add_u64 v[196:197], v[192:193], 2, s[56:57]
	v_lshlrev_b64 v[128:129], 13, v[194:195]
	v_lshl_add_u64 v[128:129], v[196:197], 0, v[128:129]
	global_load_dwordx4 v[212:215], v[128:129], off nt
	global_load_dwordx4 v[216:219], v[128:129], off offset:16 nt
	global_load_dwordx4 v[220:223], v[128:129], off offset:512 nt
	global_load_dwordx4 v[224:227], v[128:129], off offset:528 nt
	v_add_u32_e32 v202, 16, v194
	v_add_u32_e32 v200, 32, v194
	v_add_u32_e32 v198, 48, v194
	v_ashrrev_i32_e32 v203, 31, v202
	v_ashrrev_i32_e32 v201, 31, v200
	v_ashrrev_i32_e32 v199, 31, v198
	v_lshlrev_b64 v[128:129], 13, v[202:203]
	v_lshlrev_b64 v[130:131], 13, v[200:201]
	v_lshlrev_b64 v[132:133], 13, v[198:199]
	v_lshl_add_u64 v[128:129], v[196:197], 0, v[128:129]
	v_lshl_add_u64 v[130:131], v[196:197], 0, v[130:131]
	v_lshl_add_u64 v[132:133], v[196:197], 0, v[132:133]
	global_load_dwordx4 v[168:171], v[128:129], off offset:16 nt
	global_load_dwordx4 v[172:175], v[128:129], off nt
	global_load_dwordx4 v[160:163], v[128:129], off offset:528 nt
	global_load_dwordx4 v[164:167], v[128:129], off offset:512 nt
	global_load_dwordx4 v[152:155], v[130:131], off offset:16 nt
	global_load_dwordx4 v[156:159], v[130:131], off nt
	global_load_dwordx4 v[144:147], v[130:131], off offset:528 nt
	global_load_dwordx4 v[148:151], v[130:131], off offset:512 nt
	global_load_dwordx4 v[136:139], v[132:133], off offset:16 nt
	global_load_dwordx4 v[140:143], v[132:133], off nt
	s_nop 0
	global_load_dwordx4 v[128:131], v[132:133], off offset:528 nt
	s_nop 0
	global_load_dwordx4 v[132:135], v[132:133], off offset:512 nt
	v_and_b32_e32 v228, 64, v209
	v_xor_b32_e32 v211, 16, v209
	v_add_u32_e32 v228, 64, v228
	v_xor_b32_e32 v229, 32, v209
	v_cmp_lt_i32_e32 vcc, v211, v228
	s_lshl_b32 s18, s2, 2
	s_ashr_i32 s19, s18, 31
	v_cndmask_b32_e32 v211, v209, v211, vcc
	v_cmp_lt_i32_e32 vcc, v229, v228
	s_waitcnt vmcnt(0)
	v_pk_add_f32 v[126:127], v[126:127], v[214:215]
	v_pk_add_f32 v[124:125], v[124:125], v[212:213]
	v_pk_add_f32 v[122:123], v[122:123], v[218:219]
	v_pk_add_f32 v[120:121], v[120:121], v[216:217]
	v_pk_add_f32 v[118:119], v[118:119], v[222:223]
	v_pk_add_f32 v[116:117], v[116:117], v[220:221]
	v_pk_add_f32 v[212:213], v[114:115], v[226:227]
	v_pk_add_f32 v[214:215], v[112:113], v[224:225]
	v_cndmask_b32_e32 v230, v209, v229, vcc
	v_cmp_eq_u32_e32 vcc, 0, v210
	v_lshlrev_b32_e32 v210, 2, v211
	v_cvt_pk_bf16_f32 v112, v124, v125
	v_cvt_pk_bf16_f32 v113, v126, v127
	v_mul_f32_e32 v114, v125, v125
	v_mul_f32_e32 v115, v127, v127
	v_mul_f32_e32 v125, v121, v121
	v_mul_f32_e32 v127, v123, v123
	v_mul_f32_e32 v211, v117, v117
	v_mul_f32_e32 v216, v119, v119
	v_mul_f32_e32 v217, v215, v215
	v_mul_f32_e32 v218, v213, v213
	v_fmac_f32_e32 v114, v124, v124
	v_fmac_f32_e32 v115, v126, v126
	v_fmac_f32_e32 v125, v120, v120
	v_fmac_f32_e32 v127, v122, v122
	v_fmac_f32_e32 v211, v116, v116
	v_fmac_f32_e32 v216, v118, v118
	v_fmac_f32_e32 v217, v214, v214
	v_fmac_f32_e32 v218, v212, v212
	v_add_f32_e32 v114, v114, v115
	v_add_f32_e32 v115, v125, v127
	v_add_f32_e32 v124, v211, v216
	v_add_f32_e32 v125, v217, v218
	v_add_f32_e32 v114, v114, v115
	v_add_f32_e32 v115, v124, v125
	v_add_f32_e32 v124, v114, v115
	ds_bpermute_b32 v125, v210, v124
	v_lshlrev_b64 v[228:229], 12, v[194:195]
	v_lshl_add_u64 v[228:229], s[6:7], 0, v[228:229]
	v_lshl_add_u64 v[228:229], v[192:193], 1, v[228:229]
	v_cvt_pk_bf16_f32 v114, v120, v121
	v_cvt_pk_bf16_f32 v115, v122, v123
	global_store_dwordx4 v[228:229], v[112:115], off
	v_lshlrev_b32_e32 v120, 2, v230
	s_waitcnt lgkmcnt(0)
	v_add_f32_e32 v112, v124, v125
	ds_bpermute_b32 v113, v120, v112
	v_cvt_pk_bf16_f32 v114, v116, v117
	v_cvt_pk_bf16_f32 v115, v118, v119
	v_cvt_pk_bf16_f32 v116, v214, v215
	v_cvt_pk_bf16_f32 v117, v212, v213
	global_store_dwordx4 v[228:229], v[114:117], off offset:256
	s_and_saveexec_b64 s[20:21], vcc
	s_cbranch_execz .LBB0_673
	v_lshlrev_b64 v[114:115], 7, v[194:195]
	v_lshl_add_u64 v[114:115], s[16:17], 0, v[114:115]
	v_lshl_add_u64 v[114:115], s[18:19], 2, v[114:115]
	s_lshl_b32 s2, s27, 2
	v_lshl_add_u64 v[114:115], v[114:115], 0, s[2:3]
	s_waitcnt lgkmcnt(0)
	v_add_f32_e32 v112, v112, v113
	global_store_dword v[114:115], v112, off

; #define PG8_STAGE(bufoff, gbase, voff) do { _Pragma("unroll") for (int _i = 0; _i < 2; ++_i) \
;         __builtin_amdgcn_global_load_lds((const unsigned*)((const char*)(gbase) + (voff)[_i]), (LAS unsigned*)(lds + (bufoff) + ldsw + _i * 8192), 16, 0, 0); } while (0)
; #define PG8_LDA(dst, b, h) do { _Pragma("unroll") for (int m = 0; m < 4; ++m) _Pragma("unroll") for (int k = 0; k < 2; ++k) dst[m][k] = *(const LAS bf16x8*)(lds + PG8_SA(b, h) + aoff + m * 2048 + k * 1024); } while (0)
; #define PG8_LDB(dst, b, h) do { _Pragma("unroll") for (int n = 0; n < 2; ++n) _Pragma("unroll") for (int k = 0; k < 2; ++k) dst[n][k] = *(const LAS bf16x8*)(lds + PG8_SB(b, h) + boff + n * 2048 + k * 1024); } while (0)
; #define PG8_MMA(ai, bj, At, Bt) do { __builtin_amdgcn_s_setprio(1); _Pragma("unroll") for (int m = 0; m < 4; ++m) _Pragma("unroll") for (int n = 0; n < 2; ++n) _Pragma("unroll") for (int k = 0; k < 2; ++k) \
;         acc[ai][bj][m][n] = __builtin_amdgcn_mfma_f32_16x16x32_bf16(Bt[n][k], At[m][k], acc[ai][bj][m][n], 0, 0, 0); __builtin_amdgcn_s_setprio(0); } while (0)
; #define PG8_WAIT_L(n) asm volatile("s_waitcnt lgkmcnt(" #n ")" ::: "memory")
; #define PG8_BAR __builtin_amdgcn_s_barrier()
; #define PG8_SCHED __builtin_amdgcn_sched_barrier(0)
; template <class Epi, bool KS0 = false>
; __device__ __forceinline__ void gemm_phase(const int WID, LAS unsigned char* lds, const Gemm g, const StaticOrder& S, const Epi& E) {
;     ...
;         const bool has_next = S.next(ui + 1, nxt);
;         const char* nA = has_next ? (const char*)g.A + (size_t)nxt.pm * tstep : cA; const char* nB = has_next ? (const char*)g.Bt + (size_t)nxt.pn * tstep : cB;
;         for (int t = 0; t < nt; t += 2) {
;             const bool last = (t == nt - 2);
;             const char* a1 = cA + (size_t)(t + 1) * kstep;
;             const char* a2 = last ? nA : cA + (size_t)(t + 2) * kstep; const char* b2 = last ? nB : cB + (size_t)(t + 2) * kstep;
;             const char* a3 = a2 + kstep; const char* b3 = b2 + kstep;
;             PG8_LDB(B0, 0, 0); PG8_SCHED; PG8_LDA(At, 0, 0); PG8_STAGE(PG8_SA(1, 1), a1 + hstep, voffA);
;             PG8_WAIT_L(8); PG8_BAR; PG8_WAIT_L(0); PG8_MMA(0, 0, At, B0); PG8_BAR; PG8_SCHED;
.LBB0_776:
	s_ashr_i32 s55, s54, 31
	v_cmp_lt_i64_e32 vcc, s[14:15], v[148:149]
	s_lshl_b64 s[14:15], s[54:55], 20
	s_add_u32 s56, s6, s14
	s_addc_u32 s57, s7, s15
	s_and_b64 s[14:15], vcc, exec
	s_cselect_b32 s28, s57, s3
	s_cselect_b32 s29, s56, s2
	s_ashr_i32 s53, s52, 31
	s_lshl_b64 s[14:15], s[52:53], 20
	v_readlane_b32 s42, v254, 9
	v_readlane_b32 s43, v254, 10
	s_add_u32 s58, s42, s14
	s_addc_u32 s59, s43, s15
	s_and_b64 s[14:15], vcc, exec
	s_cselect_b32 s42, s59, s13
	s_cselect_b32 s43, s58, s12
	s_add_u32 s2, s2, 0x80080
	s_addc_u32 s3, s3, 0
	s_add_u32 s44, s12, 0x100
	v_mov_b32_e32 v0, 0
	s_addc_u32 s45, s13, 0
	s_mov_b32 s53, -2
	v_mov_b32_e32 v1, v0
	v_mov_b32_e32 v2, v0
	v_mov_b32_e32 v3, v0
	v_mov_b32_e32 v4, v0
	v_mov_b32_e32 v5, v0
	v_mov_b32_e32 v6, v0
	v_mov_b32_e32 v7, v0
	v_mov_b32_e32 v32, v0
	v_mov_b32_e32 v33, v0
	v_mov_b32_e32 v34, v0
	v_mov_b32_e32 v35, v0
	v_mov_b32_e32 v36, v0
	v_mov_b32_e32 v37, v0
	v_mov_b32_e32 v38, v0
	v_mov_b32_e32 v39, v0
	v_mov_b32_e32 v40, v0
	v_mov_b32_e32 v41, v0
	v_mov_b32_e32 v42, v0
	v_mov_b32_e32 v43, v0
	v_mov_b32_e32 v44, v0
	v_mov_b32_e32 v45, v0
	v_mov_b32_e32 v46, v0
	v_mov_b32_e32 v47, v0
	v_mov_b32_e32 v56, v0
	v_mov_b32_e32 v57, v0
	v_mov_b32_e32 v58, v0
	v_mov_b32_e32 v59, v0
	v_mov_b32_e32 v60, v0
	v_mov_b32_e32 v61, v0
	v_mov_b32_e32 v62, v0
	v_mov_b32_e32 v63, v0
	v_mov_b32_e32 v8, v0
	v_mov_b32_e32 v9, v0
	v_mov_b32_e32 v10, v0
	v_mov_b32_e32 v11, v0
	v_mov_b32_e32 v16, v0
	v_mov_b32_e32 v17, v0
	v_mov_b32_e32 v18, v0
	v_mov_b32_e32 v19, v0
	v_mov_b32_e32 v48, v0
	v_mov_b32_e32 v49, v0
	v_mov_b32_e32 v50, v0
	v_mov_b32_e32 v51, v0
	v_mov_b32_e32 v52, v0
	v_mov_b32_e32 v53, v0
	v_mov_b32_e32 v54, v0
	v_mov_b32_e32 v55, v0
	v_mov_b32_e32 v64, v0
	v_mov_b32_e32 v65, v0
	v_mov_b32_e32 v66, v0
	v_mov_b32_e32 v67, v0
	v_mov_b32_e32 v68, v0
	v_mov_b32_e32 v69, v0
	v_mov_b32_e32 v70, v0
	v_mov_b32_e32 v71, v0
	v_mov_b32_e32 v72, v0
	v_mov_b32_e32 v73, v0
	v_mov_b32_e32 v74, v0
	v_mov_b32_e32 v75, v0
	v_mov_b32_e32 v76, v0
	v_mov_b32_e32 v77, v0
	v_mov_b32_e32 v78, v0
	v_mov_b32_e32 v79, v0
	v_mov_b32_e32 v20, v0
	v_mov_b32_e32 v21, v0
	v_mov_b32_e32 v22, v0
	v_mov_b32_e32 v23, v0
	v_mov_b32_e32 v28, v0
	v_mov_b32_e32 v29, v0
	v_mov_b32_e32 v30, v0
	v_mov_b32_e32 v31, v0
	v_mov_b32_e32 v80, v0
	v_mov_b32_e32 v81, v0
	v_mov_b32_e32 v82, v0
	v_mov_b32_e32 v83, v0
	v_mov_b32_e32 v84, v0
	v_mov_b32_e32 v85, v0
	v_mov_b32_e32 v86, v0
	v_mov_b32_e32 v87, v0
	v_mov_b32_e32 v92, v0
	v_mov_b32_e32 v93, v0
	v_mov_b32_e32 v94, v0
	v_mov_b32_e32 v95, v0
	v_mov_b32_e32 v100, v0
	v_mov_b32_e32 v101, v0
	v_mov_b32_e32 v102, v0
	v_mov_b32_e32 v103, v0
	v_mov_b32_e32 v120, v0
	v_mov_b32_e32 v121, v0
	v_mov_b32_e32 v122, v0
	v_mov_b32_e32 v123, v0
	v_mov_b32_e32 v12, v0
	v_mov_b32_e32 v13, v0
	v_mov_b32_e32 v14, v0
	v_mov_b32_e32 v15, v0
	v_mov_b32_e32 v24, v0
	v_mov_b32_e32 v25, v0
	v_mov_b32_e32 v26, v0
	v_mov_b32_e32 v27, v0
	v_mov_b32_e32 v88, v0
	v_mov_b32_e32 v89, v0
	v_mov_b32_e32 v90, v0
	v_mov_b32_e32 v91, v0
	v_mov_b32_e32 v96, v0
	v_mov_b32_e32 v97, v0
	v_mov_b32_e32 v98, v0
	v_mov_b32_e32 v99, v0
	v_mov_b32_e32 v104, v0
	v_mov_b32_e32 v105, v0
	v_mov_b32_e32 v106, v0
	v_mov_b32_e32 v107, v0
	v_mov_b32_e32 v112, v0
	v_mov_b32_e32 v113, v0
	v_mov_b32_e32 v114, v0
	v_mov_b32_e32 v115, v0
	v_mov_b32_e32 v116, v0
	v_mov_b32_e32 v117, v0
	v_mov_b32_e32 v118, v0
	v_mov_b32_e32 v119, v0
	v_mov_b32_e32 v124, v0
	v_mov_b32_e32 v125, v0
	v_mov_b32_e32 v126, v0
	v_mov_b32_e32 v127, v0
	v_mov_b32_e32 v128, v0
	v_mov_b32_e32 v129, v0
	v_mov_b32_e32 v130, v0
	v_mov_b32_e32 v131, v0
	ds_read_b128 v[108:111], v175
	ds_read_b128 v[132:135], v175 offset:1024
	ds_read_b128 v[136:139], v175 offset:2048
	ds_read_b128 v[152:155], v175 offset:3072
.LBB0_777:
	ds_read_b128 v[156:159], v176
	ds_read_b128 v[160:163], v176 offset:1024
	ds_read_b128 v[164:167], v176 offset:2048
	ds_read_b128 v[168:171], v176 offset:3072
	ds_read_b128 v[180:183], v176 offset:4096
	ds_read_b128 v[184:187], v176 offset:5120
	ds_read_b128 v[188:191], v176 offset:6144
	ds_read_b128 v[192:195], v176 offset:7168
	s_add_u32 s12, s2, 0xfff80080
	s_addc_u32 s13, s3, -1
	s_cmp_eq_u32 s53, 28
	s_cselect_b32 s15, s28, s13
	s_cselect_b32 s14, s29, s12
	s_cselect_b32 s13, s42, s45
	s_cselect_b32 s12, s43, s44
	v_lshl_add_u64 v[196:197], s[2:3], 0, v[144:145]
	s_add_i32 m0, s9, 0xc000
	s_nop 0
	global_load_lds_dwordx4 v[196:197], off
	s_add_i32 m0, s9, 0xe000
	s_nop 0
	global_load_lds_dwordx4 v146, s[2:3]
	s_waitcnt lgkmcnt(8)
	s_barrier
	s_waitcnt lgkmcnt(0)
	v_mfma_f32_16x16x32_bf16 v[128:131], v[108:111], v[156:159], v[128:131]
	v_mfma_f32_16x16x32_bf16 v[124:127], v[136:139], v[156:159], v[124:127]
	v_mfma_f32_16x16x32_bf16 v[116:119], v[108:111], v[164:167], v[116:119]
	v_mfma_f32_16x16x32_bf16 v[112:115], v[136:139], v[164:167], v[112:115]
	v_mfma_f32_16x16x32_bf16 v[104:107], v[108:111], v[180:183], v[104:107]
	v_mfma_f32_16x16x32_bf16 v[96:99], v[136:139], v[180:183], v[96:99]
	v_mfma_f32_16x16x32_bf16 v[88:91], v[108:111], v[188:191], v[88:91]
	v_mfma_f32_16x16x32_bf16 v[24:27], v[136:139], v[188:191], v[24:27]
	v_mfma_f32_16x16x32_bf16 v[128:131], v[132:135], v[160:163], v[128:131]
	v_mfma_f32_16x16x32_bf16 v[124:127], v[152:155], v[160:163], v[124:127]
	v_mfma_f32_16x16x32_bf16 v[116:119], v[132:135], v[168:171], v[116:119]
	v_mfma_f32_16x16x32_bf16 v[112:115], v[152:155], v[168:171], v[112:115]
	v_mfma_f32_16x16x32_bf16 v[104:107], v[132:135], v[184:187], v[104:107]
	v_mfma_f32_16x16x32_bf16 v[96:99], v[152:155], v[184:187], v[96:99]
	v_mfma_f32_16x16x32_bf16 v[88:91], v[132:135], v[192:195], v[88:91]
	v_mfma_f32_16x16x32_bf16 v[24:27], v[152:155], v[192:195], v[24:27]
	s_barrier
; #define PG8_STAGE(bufoff, gbase, voff) do { _Pragma("unroll") for (int _i = 0; _i < 2; ++_i) \
;         __builtin_amdgcn_global_load_lds((const unsigned*)((const char*)(gbase) + (voff)[_i]), (LAS unsigned*)(lds + (bufoff) + ldsw + _i * 8192), 16, 0, 0); } while (0)
; #define PG8_LDA(dst, b, h) do { _Pragma("unroll") for (int m = 0; m < 4; ++m) _Pragma("unroll") for (int k = 0; k < 2; ++k) dst[m][k] = *(const LAS bf16x8*)(lds + PG8_SA(b, h) + aoff + m * 2048 + k * 1024); } while (0)
; #define PG8_LDB(dst, b, h) do { _Pragma("unroll") for (int n = 0; n < 2; ++n) _Pragma("unroll") for (int k = 0; k < 2; ++k) dst[n][k] = *(const LAS bf16x8*)(lds + PG8_SB(b, h) + boff + n * 2048 + k * 1024); } while (0)
; #define PG8_MMA(ai, bj, At, Bt) do { __builtin_amdgcn_s_setprio(1); _Pragma("unroll") for (int m = 0; m < 4; ++m) _Pragma("unroll") for (int n = 0; n < 2; ++n) _Pragma("unroll") for (int k = 0; k < 2; ++k) \
;         acc[ai][bj][m][n] = __builtin_amdgcn_mfma_f32_16x16x32_bf16(Bt[n][k], At[m][k], acc[ai][bj][m][n], 0, 0, 0); __builtin_amdgcn_s_setprio(0); } while (0)
; #define PG8_WAIT_V(n) asm volatile("s_waitcnt vmcnt(" #n ")" ::: "memory")
; #define PG8_WAIT_L(n) asm volatile("s_waitcnt lgkmcnt(" #n ")" ::: "memory")
; #define PG8_BAR __builtin_amdgcn_s_barrier()
; #define PG8_SCHED __builtin_amdgcn_sched_barrier(0)
; template <class Epi, bool KS0 = false>
; __device__ __forceinline__ void gemm_phase(const int WID, LAS unsigned char* lds, const Gemm g, const StaticOrder& S, const Epi& E) {
;     ...
;             PG8_LDB(B1, 0, 1); PG8_STAGE(PG8_SB(0, 0), b2, voffB);
;             PG8_BAR; PG8_WAIT_L(0); PG8_MMA(0, 1, At, B1); PG8_BAR;
;             PG8_LDA(At, 0, 1); PG8_STAGE(PG8_SA(0, 0), a2, voffA);
;             PG8_BAR; PG8_WAIT_L(0); PG8_MMA(1, 0, At, B0); PG8_BAR; PG8_SCHED;
;             PG8_STAGE(PG8_SB(0, 1), b2 + hstep, voffB);
;             PG8_WAIT_V(6); PG8_BAR; PG8_MMA(1, 1, At, B1); PG8_BAR;
;             PG8_LDB(B0, 1, 0); PG8_SCHED; PG8_LDA(At, 1, 0); PG8_STAGE(PG8_SA(0, 1), a2 + hstep, voffA);
;             PG8_WAIT_L(8); PG8_BAR; PG8_WAIT_L(0); PG8_MMA(0, 0, At, B0); PG8_BAR; PG8_SCHED;
;             PG8_LDB(B1, 1, 1); PG8_STAGE(PG8_SB(1, 0), b3, voffB);
	ds_read_b128 v[196:199], v177
	ds_read_b128 v[200:203], v177 offset:1024
	ds_read_b128 v[204:207], v177 offset:2048
	ds_read_b128 v[210:213], v177 offset:3072
	s_add_i32 s55, s63, s26
	v_lshl_add_u64 v[214:215], s[12:13], 0, v[140:141]
	s_mov_b32 m0, s55
	s_nop 0
	global_load_lds_dwordx4 v[214:215], off
	v_lshl_add_u64 v[216:217], s[12:13], 0, v[142:143]
	s_add_i32 m0, s55, 0x2000
	s_nop 0
	global_load_lds_dwordx4 v[216:217], off
	s_barrier
	s_waitcnt lgkmcnt(0)
	v_mfma_f32_16x16x32_bf16 v[12:15], v[196:199], v[156:159], v[12:15]
	v_mfma_f32_16x16x32_bf16 v[120:123], v[204:207], v[156:159], v[120:123]
	s_mov_b32 m0, s9
	v_lshl_add_u64 v[218:219], s[14:15], 0, v[140:141]
	v_mfma_f32_16x16x32_bf16 v[100:103], v[196:199], v[164:167], v[100:103]
	v_mfma_f32_16x16x32_bf16 v[92:95], v[204:207], v[164:167], v[92:95]
	v_mfma_f32_16x16x32_bf16 v[84:87], v[196:199], v[180:183], v[84:87]
	v_mfma_f32_16x16x32_bf16 v[80:83], v[204:207], v[180:183], v[80:83]
	v_mfma_f32_16x16x32_bf16 v[28:31], v[196:199], v[188:191], v[28:31]
	v_mfma_f32_16x16x32_bf16 v[20:23], v[204:207], v[188:191], v[20:23]
	v_mfma_f32_16x16x32_bf16 v[12:15], v[200:203], v[160:163], v[12:15]
	v_mfma_f32_16x16x32_bf16 v[120:123], v[210:213], v[160:163], v[120:123]
	v_mfma_f32_16x16x32_bf16 v[100:103], v[200:203], v[168:171], v[100:103]
	v_mfma_f32_16x16x32_bf16 v[92:95], v[210:213], v[168:171], v[92:95]
	v_mfma_f32_16x16x32_bf16 v[84:87], v[200:203], v[184:187], v[84:87]
	v_mfma_f32_16x16x32_bf16 v[80:83], v[210:213], v[184:187], v[80:83]
	v_mfma_f32_16x16x32_bf16 v[28:31], v[200:203], v[192:195], v[28:31]
	v_mfma_f32_16x16x32_bf16 v[20:23], v[210:213], v[192:195], v[20:23]
	s_barrier
	ds_read_b128 v[156:159], v176 offset:16384
	ds_read_b128 v[160:163], v176 offset:17408
	ds_read_b128 v[164:167], v176 offset:18432
	ds_read_b128 v[168:171], v176 offset:19456
	ds_read_b128 v[180:183], v176 offset:20480
	ds_read_b128 v[184:187], v176 offset:21504
	ds_read_b128 v[188:191], v176 offset:22528
	ds_read_b128 v[192:195], v176 offset:23552
	global_load_lds_dwordx4 v[218:219], off
	v_lshl_add_u64 v[220:221], s[14:15], 0, v[142:143]
	s_mov_b32 m0, s11
	s_nop 0
	global_load_lds_dwordx4 v[220:221], off
	s_waitcnt vmcnt(10)
	s_barrier
	s_waitcnt lgkmcnt(0)
	v_mfma_f32_16x16x32_bf16 v[76:79], v[108:111], v[156:159], v[76:79]
	v_mfma_f32_16x16x32_bf16 v[72:75], v[136:139], v[156:159], v[72:75]
	v_mfma_f32_16x16x32_bf16 v[68:71], v[108:111], v[164:167], v[68:71]
	v_mfma_f32_16x16x32_bf16 v[64:67], v[136:139], v[164:167], v[64:67]
	v_mfma_f32_16x16x32_bf16 v[52:55], v[108:111], v[180:183], v[52:55]
	v_mfma_f32_16x16x32_bf16 v[48:51], v[136:139], v[180:183], v[48:51]
	v_mfma_f32_16x16x32_bf16 v[16:19], v[108:111], v[188:191], v[16:19]
	v_mfma_f32_16x16x32_bf16 v[8:11], v[136:139], v[188:191], v[8:11]
	v_mfma_f32_16x16x32_bf16 v[76:79], v[132:135], v[160:163], v[76:79]
	v_mfma_f32_16x16x32_bf16 v[72:75], v[152:155], v[160:163], v[72:75]
	v_mfma_f32_16x16x32_bf16 v[68:71], v[132:135], v[168:171], v[68:71]
	v_mfma_f32_16x16x32_bf16 v[64:67], v[152:155], v[168:171], v[64:67]
	v_mfma_f32_16x16x32_bf16 v[52:55], v[132:135], v[184:187], v[52:55]
	v_mfma_f32_16x16x32_bf16 v[48:51], v[152:155], v[184:187], v[48:51]
	v_mfma_f32_16x16x32_bf16 v[16:19], v[132:135], v[192:195], v[16:19]
	v_mfma_f32_16x16x32_bf16 v[8:11], v[152:155], v[192:195], v[8:11]
	s_barrier
	v_add_u32_e32 v108, 0x18000, v174
	ds_read_b128 v[132:135], v108 offset:1024
	ds_read_b128 v[136:139], v108 offset:2048
	ds_read_b128 v[152:155], v108 offset:3072
	ds_read_b128 v[108:111], v108
	s_add_u32 s70, s12, 0x80000
	s_addc_u32 s71, s13, 0
	s_add_i32 s55, s64, s26
	s_mov_b32 m0, s55
	s_nop 0
	global_load_lds_dwordx4 v140, s[70:71]
	s_add_i32 m0, s55, 0x2000
	s_nop 0
	global_load_lds_dwordx4 v142, s[70:71]
	s_waitcnt vmcnt(6)
	s_barrier
	v_mfma_f32_16x16x32_bf16 v[60:63], v[196:199], v[156:159], v[60:63]
	v_mfma_f32_16x16x32_bf16 v[56:59], v[204:207], v[156:159], v[56:59]
	s_add_i32 s55, 0, 0x18000
	v_mfma_f32_16x16x32_bf16 v[44:47], v[196:199], v[164:167], v[44:47]
	v_mfma_f32_16x16x32_bf16 v[40:43], v[204:207], v[164:167], v[40:43]
	v_mfma_f32_16x16x32_bf16 v[36:39], v[196:199], v[180:183], v[36:39]
	v_mfma_f32_16x16x32_bf16 v[32:35], v[204:207], v[180:183], v[32:35]
	v_mfma_f32_16x16x32_bf16 v[4:7], v[196:199], v[188:191], v[4:7]
	v_mfma_f32_16x16x32_bf16 v[0:3], v[204:207], v[188:191], v[0:3]
	v_mfma_f32_16x16x32_bf16 v[60:63], v[200:203], v[160:163], v[60:63]
	v_mfma_f32_16x16x32_bf16 v[56:59], v[210:213], v[160:163], v[56:59]
	v_mfma_f32_16x16x32_bf16 v[44:47], v[200:203], v[168:171], v[44:47]
	v_mfma_f32_16x16x32_bf16 v[40:43], v[210:213], v[168:171], v[40:43]
	v_mfma_f32_16x16x32_bf16 v[36:39], v[200:203], v[184:187], v[36:39]
	v_mfma_f32_16x16x32_bf16 v[32:35], v[210:213], v[184:187], v[32:35]
	v_mfma_f32_16x16x32_bf16 v[4:7], v[200:203], v[192:195], v[4:7]
	v_mfma_f32_16x16x32_bf16 v[0:3], v[210:213], v[192:195], v[0:3]
	s_barrier
	ds_read_b128 v[156:159], v176 offset:32768
	ds_read_b128 v[160:163], v176 offset:33792
	ds_read_b128 v[164:167], v176 offset:34816
	ds_read_b128 v[168:171], v176 offset:35840
	ds_read_b128 v[180:183], v176 offset:36864
	ds_read_b128 v[184:187], v176 offset:37888
	ds_read_b128 v[188:191], v176 offset:38912
	ds_read_b128 v[192:195], v176 offset:39936
	s_add_u32 s14, s14, 0x80000
	s_addc_u32 s15, s15, 0
	s_mov_b32 m0, s18
	v_lshl_add_u64 v[196:197], s[14:15], 0, v[140:141]
	global_load_lds_dwordx4 v[196:197], off
	s_mov_b32 m0, s19
	s_nop 0
	global_load_lds_dwordx4 v142, s[14:15]
	s_waitcnt lgkmcnt(8)
	s_barrier
; #define PG8_STAGE(bufoff, gbase, voff) do { _Pragma("unroll") for (int _i = 0; _i < 2; ++_i) \
;         __builtin_amdgcn_global_load_lds((const unsigned*)((const char*)(gbase) + (voff)[_i]), (LAS unsigned*)(lds + (bufoff) + ldsw + _i * 8192), 16, 0, 0); } while (0)
; #define PG8_LDA(dst, b, h) do { _Pragma("unroll") for (int m = 0; m < 4; ++m) _Pragma("unroll") for (int k = 0; k < 2; ++k) dst[m][k] = *(const LAS bf16x8*)(lds + PG8_SA(b, h) + aoff + m * 2048 + k * 1024); } while (0)
; #define PG8_MMA(ai, bj, At, Bt) do { __builtin_amdgcn_s_setprio(1); _Pragma("unroll") for (int m = 0; m < 4; ++m) _Pragma("unroll") for (int n = 0; n < 2; ++n) _Pragma("unroll") for (int k = 0; k < 2; ++k) \
;         acc[ai][bj][m][n] = __builtin_amdgcn_mfma_f32_16x16x32_bf16(Bt[n][k], At[m][k], acc[ai][bj][m][n], 0, 0, 0); __builtin_amdgcn_s_setprio(0); } while (0)
; #define PG8_WAIT_L(n) asm volatile("s_waitcnt lgkmcnt(" #n ")" ::: "memory")
; #define PG8_BAR __builtin_amdgcn_s_barrier()
; #define PG8_SCHED __builtin_amdgcn_sched_barrier(0)
; template <class Epi, bool KS0 = false>
; __device__ __forceinline__ void gemm_phase(const int WID, LAS unsigned char* lds, const Gemm g, const StaticOrder& S, const Epi& E) {
;     ...
;             PG8_BAR; PG8_WAIT_L(0); PG8_MMA(0, 1, At, B1); PG8_BAR;
;             PG8_LDA(At, 1, 1); PG8_STAGE(PG8_SA(1, 0), a3, voffA);
;             PG8_BAR; PG8_WAIT_L(0); PG8_MMA(1, 0, At, B0); PG8_BAR; PG8_SCHED;
;             PG8_STAGE(PG8_SB(1, 1), b3 + hstep, voffB);
	s_waitcnt lgkmcnt(0)
	v_mfma_f32_16x16x32_bf16 v[128:131], v[108:111], v[156:159], v[128:131]
	v_mfma_f32_16x16x32_bf16 v[124:127], v[136:139], v[156:159], v[124:127]
	v_mfma_f32_16x16x32_bf16 v[116:119], v[108:111], v[164:167], v[116:119]
	v_mfma_f32_16x16x32_bf16 v[112:115], v[136:139], v[164:167], v[112:115]
	v_mfma_f32_16x16x32_bf16 v[104:107], v[108:111], v[180:183], v[104:107]
	v_mfma_f32_16x16x32_bf16 v[96:99], v[136:139], v[180:183], v[96:99]
	v_mfma_f32_16x16x32_bf16 v[88:91], v[108:111], v[188:191], v[88:91]
	v_mfma_f32_16x16x32_bf16 v[24:27], v[136:139], v[188:191], v[24:27]
	v_mfma_f32_16x16x32_bf16 v[128:131], v[132:135], v[160:163], v[128:131]
	v_mfma_f32_16x16x32_bf16 v[124:127], v[152:155], v[160:163], v[124:127]
	v_mfma_f32_16x16x32_bf16 v[116:119], v[132:135], v[168:171], v[116:119]
	v_mfma_f32_16x16x32_bf16 v[112:115], v[152:155], v[168:171], v[112:115]
	v_mfma_f32_16x16x32_bf16 v[104:107], v[132:135], v[184:187], v[104:107]
	v_mfma_f32_16x16x32_bf16 v[96:99], v[152:155], v[184:187], v[96:99]
	v_mfma_f32_16x16x32_bf16 v[88:91], v[132:135], v[192:195], v[88:91]
	v_mfma_f32_16x16x32_bf16 v[24:27], v[152:155], v[192:195], v[24:27]
	s_barrier
	s_add_i32 s14, 0, 0x1c000
	v_add_u32_e32 v179, s14, v174
	ds_read_b128 v[196:199], v179
	ds_read_b128 v[200:203], v179 offset:1024
	ds_read_b128 v[204:207], v179 offset:2048
	ds_read_b128 v[210:213], v179 offset:3072
	s_add_i32 s15, s55, s26
	v_lshl_add_u64 v[214:215], v[214:215], 0, s[50:51]
	s_mov_b32 m0, s15
	s_nop 0
	global_load_lds_dwordx4 v[214:215], off
	v_lshl_add_u64 v[214:215], v[216:217], 0, s[50:51]
	s_add_i32 m0, s15, 0x2000
	s_nop 0
	global_load_lds_dwordx4 v[214:215], off
	s_barrier
	s_waitcnt lgkmcnt(0)
	v_mfma_f32_16x16x32_bf16 v[12:15], v[196:199], v[156:159], v[12:15]
	v_mfma_f32_16x16x32_bf16 v[120:123], v[204:207], v[156:159], v[120:123]
	s_mov_b32 m0, s61
	v_lshl_add_u64 v[214:215], v[218:219], 0, s[50:51]
	v_mfma_f32_16x16x32_bf16 v[100:103], v[196:199], v[164:167], v[100:103]
	v_mfma_f32_16x16x32_bf16 v[92:95], v[204:207], v[164:167], v[92:95]
	v_mfma_f32_16x16x32_bf16 v[84:87], v[196:199], v[180:183], v[84:87]
	v_mfma_f32_16x16x32_bf16 v[80:83], v[204:207], v[180:183], v[80:83]
	v_mfma_f32_16x16x32_bf16 v[28:31], v[196:199], v[188:191], v[28:31]
	v_mfma_f32_16x16x32_bf16 v[20:23], v[204:207], v[188:191], v[20:23]
	v_mfma_f32_16x16x32_bf16 v[12:15], v[200:203], v[160:163], v[12:15]
	v_mfma_f32_16x16x32_bf16 v[120:123], v[210:213], v[160:163], v[120:123]
	v_mfma_f32_16x16x32_bf16 v[100:103], v[200:203], v[168:171], v[100:103]
	v_mfma_f32_16x16x32_bf16 v[92:95], v[210:213], v[168:171], v[92:95]
	v_mfma_f32_16x16x32_bf16 v[84:87], v[200:203], v[184:187], v[84:87]
	v_mfma_f32_16x16x32_bf16 v[80:83], v[210:213], v[184:187], v[80:83]
	v_mfma_f32_16x16x32_bf16 v[28:31], v[200:203], v[192:195], v[28:31]
	v_mfma_f32_16x16x32_bf16 v[20:23], v[210:213], v[192:195], v[20:23]
	s_barrier
	ds_read_b128 v[156:159], v176 offset:49152
	ds_read_b128 v[160:163], v176 offset:50176
	ds_read_b128 v[164:167], v176 offset:51200
	ds_read_b128 v[168:171], v176 offset:52224
	ds_read_b128 v[180:183], v176 offset:53248
	ds_read_b128 v[184:187], v176 offset:54272
	ds_read_b128 v[188:191], v176 offset:55296
	ds_read_b128 v[192:195], v176 offset:56320
	global_load_lds_dwordx4 v[214:215], off
	v_lshl_add_u64 v[214:215], v[220:221], 0, s[50:51]
	s_mov_b32 m0, s62
	s_nop 0
	global_load_lds_dwordx4 v[214:215], off
	s_waitcnt vmcnt(10)
	s_barrier
	s_waitcnt lgkmcnt(0)
	v_mfma_f32_16x16x32_bf16 v[76:79], v[108:111], v[156:159], v[76:79]
	v_mfma_f32_16x16x32_bf16 v[72:75], v[136:139], v[156:159], v[72:75]
	v_mfma_f32_16x16x32_bf16 v[68:71], v[108:111], v[164:167], v[68:71]
	v_mfma_f32_16x16x32_bf16 v[64:67], v[136:139], v[164:167], v[64:67]
	v_mfma_f32_16x16x32_bf16 v[52:55], v[108:111], v[180:183], v[52:55]
	v_mfma_f32_16x16x32_bf16 v[48:51], v[136:139], v[180:183], v[48:51]
	v_mfma_f32_16x16x32_bf16 v[16:19], v[108:111], v[188:191], v[16:19]
	v_mfma_f32_16x16x32_bf16 v[8:11], v[136:139], v[188:191], v[8:11]
	v_mfma_f32_16x16x32_bf16 v[76:79], v[132:135], v[160:163], v[76:79]
	v_mfma_f32_16x16x32_bf16 v[72:75], v[152:155], v[160:163], v[72:75]
	v_mfma_f32_16x16x32_bf16 v[68:71], v[132:135], v[168:171], v[68:71]
	v_mfma_f32_16x16x32_bf16 v[64:67], v[152:155], v[168:171], v[64:67]
	v_mfma_f32_16x16x32_bf16 v[52:55], v[132:135], v[184:187], v[52:55]
	v_mfma_f32_16x16x32_bf16 v[48:51], v[152:155], v[184:187], v[48:51]
	v_mfma_f32_16x16x32_bf16 v[16:19], v[132:135], v[192:195], v[16:19]
	v_mfma_f32_16x16x32_bf16 v[8:11], v[152:155], v[192:195], v[8:11]
	s_barrier
; #define LAS __attribute__((address_space(3)))
; #define PG8_STAGE(bufoff, gbase, voff) do { _Pragma("unroll") for (int _i = 0; _i < 2; ++_i) \
;         __builtin_amdgcn_global_load_lds((const unsigned*)((const char*)(gbase) + (voff)[_i]), (LAS unsigned*)(lds + (bufoff) + ldsw + _i * 8192), 16, 0, 0); } while (0)
; #define PG8_MMA(ai, bj, At, Bt) do { __builtin_amdgcn_s_setprio(1); _Pragma("unroll") for (int m = 0; m < 4; ++m) _Pragma("unroll") for (int n = 0; n < 2; ++n) _Pragma("unroll") for (int k = 0; k < 2; ++k) \
;         acc[ai][bj][m][n] = __builtin_amdgcn_mfma_f32_16x16x32_bf16(Bt[n][k], At[m][k], acc[ai][bj][m][n], 0, 0, 0); __builtin_amdgcn_s_setprio(0); } while (0)
; #define PG8_WAIT_V(n) asm volatile("s_waitcnt vmcnt(" #n ")" ::: "memory")
; #define PG8_BAR __builtin_amdgcn_s_barrier()
; template <class Epi, bool KS0 = false>
; __device__ __forceinline__ void gemm_phase(const int WID, LAS unsigned char* lds, const Gemm g, const StaticOrder& S, const Epi& E) {
;     ...
;             PG8_STAGE(PG8_SB(1, 1), b3 + hstep, voffB);
;             PG8_WAIT_V(6); PG8_BAR; PG8_MMA(1, 1, At, B1); PG8_BAR;
;     __device__ __forceinline__ void operator()(f32x4 (&acc)[2][2][4][2], const Unit& u, int wr, int wc, int fr, int fq) const {
;         const int rowt = u.pm * BM + wr * 64 + fr, cl0 = wc * 32 + 4 * fq, wv = wr * 4 + wc, ln = fq * 16 + fr;
;         float cwr[4];
; #pragma unroll
;         for (int i = 0; i < 4; ++i) { const float* srcp = (i < 3) ? (cw + (size_t)i * FF2) : cb; cwr[i] = srcp[(ln >> 5) * FF + u.pn * HALF + wc * 32 + (ln & 31)]; }
;         {
;             LAS float* myr = rsl + wv * 128; LAS int* mypm = (LAS int*)(rsl + 1024) + wv;
;             if (__builtin_amdgcn_readfirstlane(*mypm) != u.pm) {
; #pragma unroll
;                 for (int ai = 0; ai < 2; ++ai)
; #pragma unroll
;                     for (int m = 0; m < 4; ++m) { const float r_ = row_rstd(ssq_in, rowt + ai * HALF + m * 16, fq); if (fq == 0) myr[(ai * 4 + m) * 16 + fr] = r_; }
;                 if (fq == 0 && fr == 0) *mypm = u.pm;
;                 asm volatile("s_waitcnt lgkmcnt(0)" ::: "memory");
;             }
	ds_read_b128 v[108:111], v175
	ds_read_b128 v[132:135], v175 offset:1024
	ds_read_b128 v[136:139], v175 offset:2048
	ds_read_b128 v[152:155], v175 offset:3072
	s_add_u32 s12, s12, 0x80080
	s_addc_u32 s13, s13, 0
	s_add_i32 s14, s14, s26
	s_mov_b32 m0, s14
	s_nop 0
	global_load_lds_dwordx4 v140, s[12:13]
	s_add_i32 m0, s14, 0x2000
	s_nop 0
	global_load_lds_dwordx4 v142, s[12:13]
	s_waitcnt vmcnt(6)
	s_barrier
	v_mfma_f32_16x16x32_bf16 v[60:63], v[196:199], v[156:159], v[60:63]
	v_mfma_f32_16x16x32_bf16 v[56:59], v[204:207], v[156:159], v[56:59]
	s_add_i32 s53, s53, 2
	s_add_u32 s2, s2, 0x100
	s_addc_u32 s3, s3, 0
	s_add_u32 s44, s44, 0x100
	s_addc_u32 s45, s45, 0
	s_cmp_gt_u32 s53, 29
	v_mfma_f32_16x16x32_bf16 v[44:47], v[196:199], v[164:167], v[44:47]
	v_mfma_f32_16x16x32_bf16 v[40:43], v[204:207], v[164:167], v[40:43]
	v_mfma_f32_16x16x32_bf16 v[36:39], v[196:199], v[180:183], v[36:39]
	v_mfma_f32_16x16x32_bf16 v[32:35], v[204:207], v[180:183], v[32:35]
	v_mfma_f32_16x16x32_bf16 v[4:7], v[196:199], v[188:191], v[4:7]
	v_mfma_f32_16x16x32_bf16 v[0:3], v[204:207], v[188:191], v[0:3]
	v_mfma_f32_16x16x32_bf16 v[60:63], v[200:203], v[160:163], v[60:63]
	v_mfma_f32_16x16x32_bf16 v[56:59], v[210:213], v[160:163], v[56:59]
	v_mfma_f32_16x16x32_bf16 v[44:47], v[200:203], v[168:171], v[44:47]
	v_mfma_f32_16x16x32_bf16 v[40:43], v[210:213], v[168:171], v[40:43]
	v_mfma_f32_16x16x32_bf16 v[36:39], v[200:203], v[184:187], v[36:39]
	v_mfma_f32_16x16x32_bf16 v[32:35], v[210:213], v[184:187], v[32:35]
	v_mfma_f32_16x16x32_bf16 v[4:7], v[200:203], v[192:195], v[4:7]
	v_mfma_f32_16x16x32_bf16 v[0:3], v[210:213], v[192:195], v[0:3]
	s_barrier
	s_cbranch_scc0 .LBB0_777
	s_waitcnt lgkmcnt(0)
	v_mbcnt_lo_u32_b32 v108, -1, 0
	v_mbcnt_hi_u32_b32 v108, -1, v108
	s_movk_i32 s3, 0x1600
	v_ashrrev_i32_e32 v132, 4, v108
	v_and_b32_e32 v179, 15, v108
	s_lshl_b32 s12, s8, 7
	v_lshl_add_u32 v164, v132, 4, v179
	v_lshrrev_b32_e32 v108, 5, v164
	v_mul_lo_u32 v108, v108, s3
	v_add_u32_e32 v108, s12, v108
	v_and_b32_e32 v109, 31, v164
	v_readlane_b32 s3, v254, 19
	s_lshl_b32 s2, s10, 8
	s_add_i32 s2, s2, s22
	v_or3_b32 v108, v108, v109, s3
	v_ashrrev_i32_e32 v109, 31, v108
	v_lshlrev_b64 v[108:109], 2, v[108:109]
	v_lshl_add_u64 v[110:111], s[76:77], 0, v[108:109]
	global_load_dword v165, v[110:111], off
	v_lshl_add_u64 v[110:111], s[34:35], 0, v[108:109]
	global_load_dword v166, v[110:111], off
	v_lshl_add_u64 v[110:111], s[48:49], 0, v[108:109]
	v_lshl_add_u64 v[108:109], s[78:79], 0, v[108:109]
	global_load_dword v167, v[110:111], off
	global_load_dword v168, v[108:109], off
	v_mov_b32_e32 v108, s25
	ds_read_b32 v108, v108
	v_add_u32_e32 v152, s2, v179
	v_lshl_add_u32 v155, v179, 2, s21
	s_waitcnt lgkmcnt(0)
	v_readfirstlane_b32 s2, v108
	s_cmp_eq_u32 s2, s10
	s_cbranch_scc1 .LBB0_798
	v_lshlrev_b32_e32 v108, 3, v132
	v_ashrrev_i32_e32 v109, 31, v108
	v_ashrrev_i32_e32 v153, 31, v152
	v_lshl_add_u64 v[108:109], v[108:109], 2, s[16:17]
	v_lshlrev_b64 v[110:111], 7, v[152:153]
	v_lshl_add_u64 v[110:111], v[108:109], 0, v[110:111]
	global_load_dwordx4 v[134:137], v[110:111], off
	global_load_dwordx4 v[156:159], v[110:111], off offset:16
	v_and_b32_e32 v138, 64, v209
	v_xor_b32_e32 v133, 16, v209
	v_add_u32_e32 v138, 64, v138
	v_cmp_lt_i32_e32 vcc, v133, v138
	v_cmp_eq_u32_e64 s[42:43], 0, v132
	s_waitcnt vmcnt(0)
	v_add_f32_e32 v134, v134, v135
	v_add_f32_e32 v135, v136, v137
	v_add_f32_e32 v136, v156, v157
	v_add_f32_e32 v137, v158, v159
	v_cndmask_b32_e32 v133, v209, v133, vcc
	v_add_f32_e32 v134, v134, v135
	v_add_f32_e32 v135, v136, v137
	v_lshlrev_b32_e32 v133, 2, v133
	v_add_f32_e32 v135, v134, v135
	ds_bpermute_b32 v136, v133, v135
	v_xor_b32_e32 v134, 32, v209
	v_cmp_lt_i32_e32 vcc, v134, v138
	s_waitcnt lgkmcnt(0)
	v_add_f32_e32 v135, v135, v136
	v_cndmask_b32_e32 v134, v209, v134, vcc
	v_lshlrev_b32_e32 v134, 2, v134
	ds_bpermute_b32 v136, v134, v135
	s_and_saveexec_b64 s[2:3], s[42:43]
	s_cbranch_execz .LBB0_781
	s_waitcnt lgkmcnt(0)
	v_add_f32_e32 v135, v135, v136
	v_fmamk_f32 v135, v135, 0x3a000000, v178
	v_mul_f32_e32 v136, 0x4b800000, v135
	v_cmp_gt_f32_e32 vcc, s65, v135
	s_nop 1
	v_cndmask_b32_e32 v135, v135, v136, vcc
	v_rsq_f32_e32 v135, v135
	s_nop 0
	v_mul_f32_e32 v136, 0x45800000, v135
	v_cndmask_b32_e32 v135, v135, v136, vcc
	ds_write_b32 v155, v135

; #define PG8_STAGE(bufoff, gbase, voff) do { _Pragma("unroll") for (int _i = 0; _i < 2; ++_i) \
;         __builtin_amdgcn_global_load_lds((const unsigned*)((const char*)(gbase) + (voff)[_i]), (LAS unsigned*)(lds + (bufoff) + ldsw + _i * 8192), 16, 0, 0); } while (0)
; #define PG8_LDA(dst, b, h) do { _Pragma("unroll") for (int m = 0; m < 4; ++m) _Pragma("unroll") for (int k = 0; k < 2; ++k) dst[m][k] = *(const LAS bf16x8*)(lds + PG8_SA(b, h) + aoff + m * 2048 + k * 1024); } while (0)
; #define PG8_LDB(dst, b, h) do { _Pragma("unroll") for (int n = 0; n < 2; ++n) _Pragma("unroll") for (int k = 0; k < 2; ++k) dst[n][k] = *(const LAS bf16x8*)(lds + PG8_SB(b, h) + boff + n * 2048 + k * 1024); } while (0)
; #define PG8_MMA(ai, bj, At, Bt) do { __builtin_amdgcn_s_setprio(1); _Pragma("unroll") for (int m = 0; m < 4; ++m) _Pragma("unroll") for (int n = 0; n < 2; ++n) _Pragma("unroll") for (int k = 0; k < 2; ++k) \
;         acc[ai][bj][m][n] = __builtin_amdgcn_mfma_f32_16x16x32_bf16(Bt[n][k], At[m][k], acc[ai][bj][m][n], 0, 0, 0); __builtin_amdgcn_s_setprio(0); } while (0)
; #define PG8_WAIT_L(n) asm volatile("s_waitcnt lgkmcnt(" #n ")" ::: "memory")
; #define PG8_BAR __builtin_amdgcn_s_barrier()
; #define PG8_SCHED __builtin_amdgcn_sched_barrier(0)
; template <class Epi, bool KS0 = false>
; __device__ __forceinline__ void gemm_phase(const int WID, LAS unsigned char* lds, const Gemm g, const StaticOrder& S, const Epi& E) {
;     ...
;         const bool has_next = S.next(ui + 1, nxt);
;         const char* nA = has_next ? (const char*)g.A + (size_t)nxt.pm * tstep : cA; const char* nB = has_next ? (const char*)g.Bt + (size_t)nxt.pn * tstep : cB;
;         for (int t = 0; t < nt; t += 2) {
;             const bool last = (t == nt - 2);
;             const char* a1 = cA + (size_t)(t + 1) * kstep;
;             const char* a2 = last ? nA : cA + (size_t)(t + 2) * kstep; const char* b2 = last ? nB : cB + (size_t)(t + 2) * kstep;
;             const char* a3 = a2 + kstep; const char* b3 = b2 + kstep;
;             PG8_LDB(B0, 0, 0); PG8_SCHED; PG8_LDA(At, 0, 0); PG8_STAGE(PG8_SA(1, 1), a1 + hstep, voffA);
;             PG8_WAIT_L(8); PG8_BAR; PG8_WAIT_L(0); PG8_MMA(0, 0, At, B0); PG8_BAR; PG8_SCHED;
;             PG8_LDB(B1, 0, 1); PG8_STAGE(PG8_SB(0, 0), b2, voffB);
;             PG8_BAR; PG8_WAIT_L(0); PG8_MMA(0, 1, At, B1); PG8_BAR;
.LBB0_913:
	s_add_u32 s40, s18, 0x100
	v_mov_b32_e32 v0, 0
	s_addc_u32 s41, s19, 0
	s_mov_b32 s42, -2
	s_waitcnt lgkmcnt(0)
	v_mov_b32_e32 v1, v0
	v_mov_b32_e32 v2, v0
	v_mov_b32_e32 v3, v0
	v_mov_b32_e32 v4, v0
	v_mov_b32_e32 v5, v0
	v_mov_b32_e32 v6, v0
	v_mov_b32_e32 v7, v0
	v_mov_b32_e32 v16, v0
	v_mov_b32_e32 v17, v0
	v_mov_b32_e32 v18, v0
	v_mov_b32_e32 v19, v0
	v_mov_b32_e32 v20, v0
	v_mov_b32_e32 v21, v0
	v_mov_b32_e32 v22, v0
	v_mov_b32_e32 v23, v0
	v_mov_b32_e32 v32, v0
	v_mov_b32_e32 v33, v0
	v_mov_b32_e32 v34, v0
	v_mov_b32_e32 v35, v0
	v_mov_b32_e32 v36, v0
	v_mov_b32_e32 v37, v0
	v_mov_b32_e32 v38, v0
	v_mov_b32_e32 v39, v0
	v_mov_b32_e32 v48, v0
	v_mov_b32_e32 v49, v0
	v_mov_b32_e32 v50, v0
	v_mov_b32_e32 v51, v0
	v_mov_b32_e32 v52, v0
	v_mov_b32_e32 v53, v0
	v_mov_b32_e32 v54, v0
	v_mov_b32_e32 v55, v0
	v_mov_b32_e32 v8, v0
	v_mov_b32_e32 v9, v0
	v_mov_b32_e32 v10, v0
	v_mov_b32_e32 v11, v0
	v_mov_b32_e32 v12, v0
	v_mov_b32_e32 v13, v0
	v_mov_b32_e32 v14, v0
	v_mov_b32_e32 v15, v0
	v_mov_b32_e32 v24, v0
	v_mov_b32_e32 v25, v0
	v_mov_b32_e32 v26, v0
	v_mov_b32_e32 v27, v0
	v_mov_b32_e32 v28, v0
	v_mov_b32_e32 v29, v0
	v_mov_b32_e32 v30, v0
	v_mov_b32_e32 v31, v0
	v_mov_b32_e32 v40, v0
	v_mov_b32_e32 v41, v0
	v_mov_b32_e32 v42, v0
	v_mov_b32_e32 v43, v0
	v_mov_b32_e32 v44, v0
	v_mov_b32_e32 v45, v0
	v_mov_b32_e32 v46, v0
	v_mov_b32_e32 v47, v0
	v_mov_b32_e32 v56, v0
	v_mov_b32_e32 v57, v0
	v_mov_b32_e32 v58, v0
	v_mov_b32_e32 v59, v0
	v_mov_b32_e32 v60, v0
	v_mov_b32_e32 v61, v0
	v_mov_b32_e32 v62, v0
	v_mov_b32_e32 v63, v0
	v_mov_b32_e32 v64, v0
	v_mov_b32_e32 v65, v0
	v_mov_b32_e32 v66, v0
	v_mov_b32_e32 v67, v0
	v_mov_b32_e32 v68, v0
	v_mov_b32_e32 v69, v0
	v_mov_b32_e32 v70, v0
	v_mov_b32_e32 v71, v0
	v_mov_b32_e32 v80, v0
	v_mov_b32_e32 v81, v0
	v_mov_b32_e32 v82, v0
	v_mov_b32_e32 v83, v0
	v_mov_b32_e32 v84, v0
	v_mov_b32_e32 v85, v0
	v_mov_b32_e32 v86, v0
	v_mov_b32_e32 v87, v0
	v_mov_b32_e32 v96, v0
	v_mov_b32_e32 v97, v0
	v_mov_b32_e32 v98, v0
	v_mov_b32_e32 v99, v0
	v_mov_b32_e32 v100, v0
	v_mov_b32_e32 v101, v0
	v_mov_b32_e32 v102, v0
	v_mov_b32_e32 v103, v0
	v_mov_b32_e32 v112, v0
	v_mov_b32_e32 v113, v0
	v_mov_b32_e32 v114, v0
	v_mov_b32_e32 v115, v0
	v_mov_b32_e32 v116, v0
	v_mov_b32_e32 v117, v0
	v_mov_b32_e32 v118, v0
	v_mov_b32_e32 v119, v0
	v_mov_b32_e32 v72, v0
	v_mov_b32_e32 v73, v0
	v_mov_b32_e32 v74, v0
	v_mov_b32_e32 v75, v0
	v_mov_b32_e32 v76, v0
	v_mov_b32_e32 v77, v0
	v_mov_b32_e32 v78, v0
	v_mov_b32_e32 v79, v0
	v_mov_b32_e32 v88, v0
	v_mov_b32_e32 v89, v0
	v_mov_b32_e32 v90, v0
	v_mov_b32_e32 v91, v0
	v_mov_b32_e32 v92, v0
	v_mov_b32_e32 v93, v0
	v_mov_b32_e32 v94, v0
	v_mov_b32_e32 v95, v0
	v_mov_b32_e32 v104, v0
	v_mov_b32_e32 v105, v0
	v_mov_b32_e32 v106, v0
	v_mov_b32_e32 v107, v0
	v_mov_b32_e32 v108, v0
	v_mov_b32_e32 v109, v0
	v_mov_b32_e32 v110, v0
	v_mov_b32_e32 v111, v0
	v_mov_b32_e32 v120, v0
	v_mov_b32_e32 v121, v0
	v_mov_b32_e32 v122, v0
	v_mov_b32_e32 v123, v0
	v_mov_b32_e32 v124, v0
	v_mov_b32_e32 v125, v0
	v_mov_b32_e32 v126, v0
	v_mov_b32_e32 v127, v0
	ds_read_b128 v[128:131], v187
	ds_read_b128 v[132:135], v187 offset:1024
	ds_read_b128 v[136:139], v187 offset:2048
	ds_read_b128 v[140:143], v187 offset:3072
.LBB0_914:
	ds_read_b128 v[144:147], v188
	ds_read_b128 v[148:151], v188 offset:1024
	ds_read_b128 v[168:171], v188 offset:2048
	ds_read_b128 v[172:175], v188 offset:3072
	ds_read_b128 v[176:179], v188 offset:4096
	ds_read_b128 v[180:183], v188 offset:5120
	ds_read_b128 v[190:193], v188 offset:6144
	ds_read_b128 v[194:197], v188 offset:7168
	s_add_u32 s18, s2, 0x100
	s_addc_u32 s19, s3, 0
	s_cmpk_eq_i32 s42, 0x54
	s_cselect_b32 s29, s13, s19
	s_cselect_b32 s28, s12, s18
	s_cselect_b32 s21, s15, s41
	s_cselect_b32 s20, s14, s40
	v_lshl_add_u64 v[184:185], s[2:3], 0, v[160:161]
	s_add_i32 m0, s25, 0xc000
	s_nop 0
	global_load_lds_dwordx4 v[184:185], off
	s_add_i32 m0, s25, 0xe000
	s_nop 0
	global_load_lds_dwordx4 v162, s[2:3]
	s_waitcnt lgkmcnt(8)
	s_barrier
	s_waitcnt lgkmcnt(0)
	v_mfma_f32_16x16x32_bf16 v[124:127], v[128:131], v[144:147], v[124:127]
	v_mfma_f32_16x16x32_bf16 v[120:123], v[136:139], v[144:147], v[120:123]
	v_mfma_f32_16x16x32_bf16 v[108:111], v[128:131], v[168:171], v[108:111]
	v_mfma_f32_16x16x32_bf16 v[104:107], v[136:139], v[168:171], v[104:107]
	v_mfma_f32_16x16x32_bf16 v[92:95], v[128:131], v[176:179], v[92:95]
	v_mfma_f32_16x16x32_bf16 v[88:91], v[136:139], v[176:179], v[88:91]
	v_mfma_f32_16x16x32_bf16 v[76:79], v[128:131], v[190:193], v[76:79]
	v_mfma_f32_16x16x32_bf16 v[72:75], v[136:139], v[190:193], v[72:75]
	v_mfma_f32_16x16x32_bf16 v[124:127], v[132:135], v[148:151], v[124:127]
	v_mfma_f32_16x16x32_bf16 v[120:123], v[140:143], v[148:151], v[120:123]
	v_mfma_f32_16x16x32_bf16 v[108:111], v[132:135], v[172:175], v[108:111]
	v_mfma_f32_16x16x32_bf16 v[104:107], v[140:143], v[172:175], v[104:107]
	v_mfma_f32_16x16x32_bf16 v[92:95], v[132:135], v[180:183], v[92:95]
	v_mfma_f32_16x16x32_bf16 v[88:91], v[140:143], v[180:183], v[88:91]
	v_mfma_f32_16x16x32_bf16 v[76:79], v[132:135], v[194:197], v[76:79]
	v_mfma_f32_16x16x32_bf16 v[72:75], v[140:143], v[194:197], v[72:75]
	s_barrier
	ds_read_b128 v[198:201], v189
	ds_read_b128 v[202:205], v189 offset:1024
	ds_read_b128 v[210:213], v189 offset:2048
	ds_read_b128 v[214:217], v189 offset:3072
	s_add_i32 s2, s47, s26
	v_lshl_add_u64 v[184:185], s[20:21], 0, v[154:155]
	s_mov_b32 m0, s2
	s_nop 0
	global_load_lds_dwordx4 v[184:185], off
	v_lshl_add_u64 v[206:207], s[20:21], 0, v[158:159]
	s_add_i32 m0, s2, 0x2000
	s_nop 0
	global_load_lds_dwordx4 v[206:207], off
	s_barrier
; #define PG8_STAGE(bufoff, gbase, voff) do { _Pragma("unroll") for (int _i = 0; _i < 2; ++_i) \
;         __builtin_amdgcn_global_load_lds((const unsigned*)((const char*)(gbase) + (voff)[_i]), (LAS unsigned*)(lds + (bufoff) + ldsw + _i * 8192), 16, 0, 0); } while (0)
; #define PG8_LDA(dst, b, h) do { _Pragma("unroll") for (int m = 0; m < 4; ++m) _Pragma("unroll") for (int k = 0; k < 2; ++k) dst[m][k] = *(const LAS bf16x8*)(lds + PG8_SA(b, h) + aoff + m * 2048 + k * 1024); } while (0)
; #define PG8_LDB(dst, b, h) do { _Pragma("unroll") for (int n = 0; n < 2; ++n) _Pragma("unroll") for (int k = 0; k < 2; ++k) dst[n][k] = *(const LAS bf16x8*)(lds + PG8_SB(b, h) + boff + n * 2048 + k * 1024); } while (0)
; #define PG8_MMA(ai, bj, At, Bt) do { __builtin_amdgcn_s_setprio(1); _Pragma("unroll") for (int m = 0; m < 4; ++m) _Pragma("unroll") for (int n = 0; n < 2; ++n) _Pragma("unroll") for (int k = 0; k < 2; ++k) \
;         acc[ai][bj][m][n] = __builtin_amdgcn_mfma_f32_16x16x32_bf16(Bt[n][k], At[m][k], acc[ai][bj][m][n], 0, 0, 0); __builtin_amdgcn_s_setprio(0); } while (0)
; #define PG8_WAIT_V(n) asm volatile("s_waitcnt vmcnt(" #n ")" ::: "memory")
; #define PG8_WAIT_L(n) asm volatile("s_waitcnt lgkmcnt(" #n ")" ::: "memory")
; #define PG8_BAR __builtin_amdgcn_s_barrier()
; #define PG8_SCHED __builtin_amdgcn_sched_barrier(0)
; template <class Epi, bool KS0 = false>
; __device__ __forceinline__ void gemm_phase(const int WID, LAS unsigned char* lds, const Gemm g, const StaticOrder& S, const Epi& E) {
;     ...
;             PG8_BAR; PG8_WAIT_L(0); PG8_MMA(0, 1, At, B1); PG8_BAR;
;             PG8_LDA(At, 0, 1); PG8_STAGE(PG8_SA(0, 0), a2, voffA);
;             PG8_BAR; PG8_WAIT_L(0); PG8_MMA(1, 0, At, B0); PG8_BAR; PG8_SCHED;
;             PG8_STAGE(PG8_SB(0, 1), b2 + hstep, voffB);
;             PG8_WAIT_V(6); PG8_BAR; PG8_MMA(1, 1, At, B1); PG8_BAR;
;             PG8_LDB(B0, 1, 0); PG8_SCHED; PG8_LDA(At, 1, 0); PG8_STAGE(PG8_SA(0, 1), a2 + hstep, voffA);
;             PG8_WAIT_L(8); PG8_BAR; PG8_WAIT_L(0); PG8_MMA(0, 0, At, B0); PG8_BAR; PG8_SCHED;
;             PG8_LDB(B1, 1, 1); PG8_STAGE(PG8_SB(1, 0), b3, voffB);
	s_waitcnt lgkmcnt(0)
	v_mfma_f32_16x16x32_bf16 v[116:119], v[198:201], v[144:147], v[116:119]
	v_mfma_f32_16x16x32_bf16 v[112:115], v[210:213], v[144:147], v[112:115]
	s_mov_b32 m0, s25
	v_lshl_add_u64 v[218:219], s[28:29], 0, v[152:153]
	v_mfma_f32_16x16x32_bf16 v[100:103], v[198:201], v[168:171], v[100:103]
	v_mfma_f32_16x16x32_bf16 v[96:99], v[210:213], v[168:171], v[96:99]
	v_mfma_f32_16x16x32_bf16 v[84:87], v[198:201], v[176:179], v[84:87]
	v_mfma_f32_16x16x32_bf16 v[80:83], v[210:213], v[176:179], v[80:83]
	v_mfma_f32_16x16x32_bf16 v[68:71], v[198:201], v[190:193], v[68:71]
	v_mfma_f32_16x16x32_bf16 v[64:67], v[210:213], v[190:193], v[64:67]
	v_mfma_f32_16x16x32_bf16 v[116:119], v[202:205], v[148:151], v[116:119]
	v_mfma_f32_16x16x32_bf16 v[112:115], v[214:217], v[148:151], v[112:115]
	v_mfma_f32_16x16x32_bf16 v[100:103], v[202:205], v[172:175], v[100:103]
	v_mfma_f32_16x16x32_bf16 v[96:99], v[214:217], v[172:175], v[96:99]
	v_mfma_f32_16x16x32_bf16 v[84:87], v[202:205], v[180:183], v[84:87]
	v_mfma_f32_16x16x32_bf16 v[80:83], v[214:217], v[180:183], v[80:83]
	v_mfma_f32_16x16x32_bf16 v[68:71], v[202:205], v[194:197], v[68:71]
	v_mfma_f32_16x16x32_bf16 v[64:67], v[214:217], v[194:197], v[64:67]
	s_barrier
	ds_read_b128 v[144:147], v188 offset:16384
	ds_read_b128 v[148:151], v188 offset:17408
	ds_read_b128 v[168:171], v188 offset:18432
	ds_read_b128 v[172:175], v188 offset:19456
	ds_read_b128 v[176:179], v188 offset:20480
	ds_read_b128 v[180:183], v188 offset:21504
	ds_read_b128 v[190:193], v188 offset:22528
	ds_read_b128 v[194:197], v188 offset:23552
	global_load_lds_dwordx4 v[218:219], off
	v_lshl_add_u64 v[220:221], s[28:29], 0, v[156:157]
	s_mov_b32 m0, s30
	s_nop 0
	global_load_lds_dwordx4 v[220:221], off
	s_waitcnt vmcnt(10)
	s_barrier
	s_waitcnt lgkmcnt(0)
	v_mfma_f32_16x16x32_bf16 v[60:63], v[128:131], v[144:147], v[60:63]
	v_mfma_f32_16x16x32_bf16 v[56:59], v[136:139], v[144:147], v[56:59]
	v_mfma_f32_16x16x32_bf16 v[44:47], v[128:131], v[168:171], v[44:47]
	v_mfma_f32_16x16x32_bf16 v[40:43], v[136:139], v[168:171], v[40:43]
	v_mfma_f32_16x16x32_bf16 v[28:31], v[128:131], v[176:179], v[28:31]
	v_mfma_f32_16x16x32_bf16 v[24:27], v[136:139], v[176:179], v[24:27]
	v_mfma_f32_16x16x32_bf16 v[12:15], v[128:131], v[190:193], v[12:15]
	v_mfma_f32_16x16x32_bf16 v[8:11], v[136:139], v[190:193], v[8:11]
	v_mfma_f32_16x16x32_bf16 v[60:63], v[132:135], v[148:151], v[60:63]
	v_mfma_f32_16x16x32_bf16 v[56:59], v[140:143], v[148:151], v[56:59]
	v_mfma_f32_16x16x32_bf16 v[44:47], v[132:135], v[172:175], v[44:47]
	v_mfma_f32_16x16x32_bf16 v[40:43], v[140:143], v[172:175], v[40:43]
	v_mfma_f32_16x16x32_bf16 v[28:31], v[132:135], v[180:183], v[28:31]
	v_mfma_f32_16x16x32_bf16 v[24:27], v[140:143], v[180:183], v[24:27]
	v_mfma_f32_16x16x32_bf16 v[12:15], v[132:135], v[194:197], v[12:15]
	v_mfma_f32_16x16x32_bf16 v[8:11], v[140:143], v[194:197], v[8:11]
	s_barrier
	v_add_u32_e32 v128, 0x18000, v186
	ds_read_b128 v[132:135], v128 offset:1024
	ds_read_b128 v[136:139], v128 offset:2048
	ds_read_b128 v[140:143], v128 offset:3072
	ds_read_b128 v[128:131], v128
	s_add_u32 s2, s20, 0x160000
	s_addc_u32 s3, s21, 0
	s_add_i32 s43, s48, s26
	s_mov_b32 m0, s43
	s_nop 0
	global_load_lds_dwordx4 v154, s[2:3]
	s_add_i32 m0, s43, 0x2000
	s_nop 0
	global_load_lds_dwordx4 v158, s[2:3]
	s_waitcnt vmcnt(6)
	s_barrier
	v_mfma_f32_16x16x32_bf16 v[52:55], v[198:201], v[144:147], v[52:55]
	v_mfma_f32_16x16x32_bf16 v[48:51], v[210:213], v[144:147], v[48:51]
	s_add_i32 s43, 0, 0x18000
	v_mfma_f32_16x16x32_bf16 v[36:39], v[198:201], v[168:171], v[36:39]
	v_mfma_f32_16x16x32_bf16 v[32:35], v[210:213], v[168:171], v[32:35]
	v_mfma_f32_16x16x32_bf16 v[20:23], v[198:201], v[176:179], v[20:23]
	v_mfma_f32_16x16x32_bf16 v[16:19], v[210:213], v[176:179], v[16:19]
	v_mfma_f32_16x16x32_bf16 v[4:7], v[198:201], v[190:193], v[4:7]
	v_mfma_f32_16x16x32_bf16 v[0:3], v[210:213], v[190:193], v[0:3]
	v_mfma_f32_16x16x32_bf16 v[52:55], v[202:205], v[148:151], v[52:55]
	v_mfma_f32_16x16x32_bf16 v[48:51], v[214:217], v[148:151], v[48:51]
	v_mfma_f32_16x16x32_bf16 v[36:39], v[202:205], v[172:175], v[36:39]
	v_mfma_f32_16x16x32_bf16 v[32:35], v[214:217], v[172:175], v[32:35]
	v_mfma_f32_16x16x32_bf16 v[20:23], v[202:205], v[180:183], v[20:23]
	v_mfma_f32_16x16x32_bf16 v[16:19], v[214:217], v[180:183], v[16:19]
	v_mfma_f32_16x16x32_bf16 v[4:7], v[202:205], v[194:197], v[4:7]
	v_mfma_f32_16x16x32_bf16 v[0:3], v[214:217], v[194:197], v[0:3]
	s_barrier
	ds_read_b128 v[144:147], v188 offset:32768
	ds_read_b128 v[148:151], v188 offset:33792
	ds_read_b128 v[168:171], v188 offset:34816
	ds_read_b128 v[172:175], v188 offset:35840
	ds_read_b128 v[176:179], v188 offset:36864
	ds_read_b128 v[180:183], v188 offset:37888
	ds_read_b128 v[190:193], v188 offset:38912
	ds_read_b128 v[194:197], v188 offset:39936
	s_add_u32 s2, s28, 0x160000
	s_addc_u32 s3, s29, 0
	s_mov_b32 m0, s31
	v_lshl_add_u64 v[198:199], s[2:3], 0, v[152:153]
	global_load_lds_dwordx4 v[198:199], off
	s_mov_b32 m0, s44
	s_nop 0
	global_load_lds_dwordx4 v156, s[2:3]
	s_waitcnt lgkmcnt(8)
	s_barrier
; #define PG8_STAGE(bufoff, gbase, voff) do { _Pragma("unroll") for (int _i = 0; _i < 2; ++_i) \
;         __builtin_amdgcn_global_load_lds((const unsigned*)((const char*)(gbase) + (voff)[_i]), (LAS unsigned*)(lds + (bufoff) + ldsw + _i * 8192), 16, 0, 0); } while (0)
; #define PG8_LDA(dst, b, h) do { _Pragma("unroll") for (int m = 0; m < 4; ++m) _Pragma("unroll") for (int k = 0; k < 2; ++k) dst[m][k] = *(const LAS bf16x8*)(lds + PG8_SA(b, h) + aoff + m * 2048 + k * 1024); } while (0)
; #define PG8_MMA(ai, bj, At, Bt) do { __builtin_amdgcn_s_setprio(1); _Pragma("unroll") for (int m = 0; m < 4; ++m) _Pragma("unroll") for (int n = 0; n < 2; ++n) _Pragma("unroll") for (int k = 0; k < 2; ++k) \
;         acc[ai][bj][m][n] = __builtin_amdgcn_mfma_f32_16x16x32_bf16(Bt[n][k], At[m][k], acc[ai][bj][m][n], 0, 0, 0); __builtin_amdgcn_s_setprio(0); } while (0)
; #define PG8_WAIT_L(n) asm volatile("s_waitcnt lgkmcnt(" #n ")" ::: "memory")
; #define PG8_BAR __builtin_amdgcn_s_barrier()
; #define PG8_SCHED __builtin_amdgcn_sched_barrier(0)
; template <class Epi, bool KS0 = false>
; __device__ __forceinline__ void gemm_phase(const int WID, LAS unsigned char* lds, const Gemm g, const StaticOrder& S, const Epi& E) {
;     ...
;             PG8_BAR; PG8_WAIT_L(0); PG8_MMA(0, 1, At, B1); PG8_BAR;
;             PG8_LDA(At, 1, 1); PG8_STAGE(PG8_SA(1, 0), a3, voffA);
;             PG8_BAR; PG8_WAIT_L(0); PG8_MMA(1, 0, At, B0); PG8_BAR; PG8_SCHED;
;             PG8_STAGE(PG8_SB(1, 1), b3 + hstep, voffB);
	s_waitcnt lgkmcnt(0)
	v_mfma_f32_16x16x32_bf16 v[124:127], v[128:131], v[144:147], v[124:127]
	v_mfma_f32_16x16x32_bf16 v[120:123], v[136:139], v[144:147], v[120:123]
	v_mfma_f32_16x16x32_bf16 v[108:111], v[128:131], v[168:171], v[108:111]
	v_mfma_f32_16x16x32_bf16 v[104:107], v[136:139], v[168:171], v[104:107]
	v_mfma_f32_16x16x32_bf16 v[92:95], v[128:131], v[176:179], v[92:95]
	v_mfma_f32_16x16x32_bf16 v[88:91], v[136:139], v[176:179], v[88:91]
	v_mfma_f32_16x16x32_bf16 v[76:79], v[128:131], v[190:193], v[76:79]
	v_mfma_f32_16x16x32_bf16 v[72:75], v[136:139], v[190:193], v[72:75]
	v_mfma_f32_16x16x32_bf16 v[124:127], v[132:135], v[148:151], v[124:127]
	v_mfma_f32_16x16x32_bf16 v[120:123], v[140:143], v[148:151], v[120:123]
	v_mfma_f32_16x16x32_bf16 v[108:111], v[132:135], v[172:175], v[108:111]
	v_mfma_f32_16x16x32_bf16 v[104:107], v[140:143], v[172:175], v[104:107]
	v_mfma_f32_16x16x32_bf16 v[92:95], v[132:135], v[180:183], v[92:95]
	v_mfma_f32_16x16x32_bf16 v[88:91], v[140:143], v[180:183], v[88:91]
	v_mfma_f32_16x16x32_bf16 v[76:79], v[132:135], v[194:197], v[76:79]
	v_mfma_f32_16x16x32_bf16 v[72:75], v[140:143], v[194:197], v[72:75]
	s_barrier
	s_add_i32 s28, 0, 0x1c000
	v_add_u32_e32 v208, s28, v186
	ds_read_b128 v[198:201], v208
	ds_read_b128 v[202:205], v208 offset:1024
	ds_read_b128 v[210:213], v208 offset:2048
	ds_read_b128 v[214:217], v208 offset:3072
	s_add_i32 s2, s43, s26
	v_lshl_add_u64 v[184:185], v[184:185], 0, s[10:11]
	s_mov_b32 m0, s2
	s_nop 0
	global_load_lds_dwordx4 v[184:185], off
	v_lshl_add_u64 v[184:185], v[206:207], 0, s[10:11]
	s_add_i32 m0, s2, 0x2000
	s_nop 0
	global_load_lds_dwordx4 v[184:185], off
	s_barrier
	s_waitcnt lgkmcnt(0)
	v_mfma_f32_16x16x32_bf16 v[116:119], v[198:201], v[144:147], v[116:119]
	v_mfma_f32_16x16x32_bf16 v[112:115], v[210:213], v[144:147], v[112:115]
	s_mov_b32 m0, s45
	v_lshl_add_u64 v[184:185], v[218:219], 0, s[10:11]
	v_mfma_f32_16x16x32_bf16 v[100:103], v[198:201], v[168:171], v[100:103]
	v_mfma_f32_16x16x32_bf16 v[96:99], v[210:213], v[168:171], v[96:99]
	v_mfma_f32_16x16x32_bf16 v[84:87], v[198:201], v[176:179], v[84:87]
	v_mfma_f32_16x16x32_bf16 v[80:83], v[210:213], v[176:179], v[80:83]
	v_mfma_f32_16x16x32_bf16 v[68:71], v[198:201], v[190:193], v[68:71]
	v_mfma_f32_16x16x32_bf16 v[64:67], v[210:213], v[190:193], v[64:67]
	v_mfma_f32_16x16x32_bf16 v[116:119], v[202:205], v[148:151], v[116:119]
	v_mfma_f32_16x16x32_bf16 v[112:115], v[214:217], v[148:151], v[112:115]
	v_mfma_f32_16x16x32_bf16 v[100:103], v[202:205], v[172:175], v[100:103]
	v_mfma_f32_16x16x32_bf16 v[96:99], v[214:217], v[172:175], v[96:99]
	v_mfma_f32_16x16x32_bf16 v[84:87], v[202:205], v[180:183], v[84:87]
	v_mfma_f32_16x16x32_bf16 v[80:83], v[214:217], v[180:183], v[80:83]
	v_mfma_f32_16x16x32_bf16 v[68:71], v[202:205], v[194:197], v[68:71]
	v_mfma_f32_16x16x32_bf16 v[64:67], v[214:217], v[194:197], v[64:67]
	s_barrier
	ds_read_b128 v[144:147], v188 offset:49152
	ds_read_b128 v[148:151], v188 offset:50176
	ds_read_b128 v[168:171], v188 offset:51200
	ds_read_b128 v[172:175], v188 offset:52224
	ds_read_b128 v[176:179], v188 offset:53248
	ds_read_b128 v[180:183], v188 offset:54272
	ds_read_b128 v[190:193], v188 offset:55296
	ds_read_b128 v[194:197], v188 offset:56320
	global_load_lds_dwordx4 v[184:185], off
	v_lshl_add_u64 v[184:185], v[220:221], 0, s[10:11]
	s_mov_b32 m0, s46
	s_nop 0
	global_load_lds_dwordx4 v[184:185], off
	s_waitcnt vmcnt(10)
	s_barrier
	s_waitcnt lgkmcnt(0)
	v_mfma_f32_16x16x32_bf16 v[60:63], v[128:131], v[144:147], v[60:63]
	v_mfma_f32_16x16x32_bf16 v[56:59], v[136:139], v[144:147], v[56:59]
	v_mfma_f32_16x16x32_bf16 v[44:47], v[128:131], v[168:171], v[44:47]
	v_mfma_f32_16x16x32_bf16 v[40:43], v[136:139], v[168:171], v[40:43]
	v_mfma_f32_16x16x32_bf16 v[28:31], v[128:131], v[176:179], v[28:31]
	v_mfma_f32_16x16x32_bf16 v[24:27], v[136:139], v[176:179], v[24:27]
	v_mfma_f32_16x16x32_bf16 v[12:15], v[128:131], v[190:193], v[12:15]
	v_mfma_f32_16x16x32_bf16 v[8:11], v[136:139], v[190:193], v[8:11]
	v_mfma_f32_16x16x32_bf16 v[60:63], v[132:135], v[148:151], v[60:63]
	v_mfma_f32_16x16x32_bf16 v[56:59], v[140:143], v[148:151], v[56:59]
	v_mfma_f32_16x16x32_bf16 v[44:47], v[132:135], v[172:175], v[44:47]
	v_mfma_f32_16x16x32_bf16 v[40:43], v[140:143], v[172:175], v[40:43]
	v_mfma_f32_16x16x32_bf16 v[28:31], v[132:135], v[180:183], v[28:31]
	v_mfma_f32_16x16x32_bf16 v[24:27], v[140:143], v[180:183], v[24:27]
	v_mfma_f32_16x16x32_bf16 v[12:15], v[132:135], v[194:197], v[12:15]
	v_mfma_f32_16x16x32_bf16 v[8:11], v[140:143], v[194:197], v[8:11]
	s_barrier
	ds_read_b128 v[128:131], v187
	ds_read_b128 v[132:135], v187 offset:1024
	ds_read_b128 v[136:139], v187 offset:2048
	ds_read_b128 v[140:143], v187 offset:3072
	s_add_u32 s2, s20, 0x160080
	s_addc_u32 s3, s21, 0
	s_add_i32 s20, s28, s26
	s_mov_b32 m0, s20
	s_nop 0
	global_load_lds_dwordx4 v154, s[2:3]
	s_add_i32 m0, s20, 0x2000
	s_nop 0
	global_load_lds_dwordx4 v158, s[2:3]
	s_waitcnt vmcnt(6)
	s_barrier
; __device__ __forceinline__ unsigned cvt_pk_bf16(float lo, float hi) { unsigned r; asm volatile("v_cvt_pk_bf16_f32 %0, %1, %2" : "=v"(r) : "v"(lo), "v"(hi)); return r; }
; __device__ __forceinline__ float bflo(unsigned w) { return __uint_as_float(w << 16); }
; __device__ __forceinline__ float bfhi(unsigned w) { return __uint_as_float(w & 0xffff0000u); }
; template <class Epi, bool KS0 = false>
; __device__ __forceinline__ void gemm_phase(const int WID, LAS unsigned char* lds, const Gemm g, const StaticOrder& S, const Epi& E) {
;     ...
;             PG8_WAIT_V(6); PG8_BAR; PG8_MMA(1, 1, At, B1); PG8_BAR;
;     __device__ __forceinline__ void operator()(f32x4 (&acc)[2][2][4][2], const Unit& u, int wr, int wc, int fr, int fq) const {
;         const int row0 = u.pm * BM + wr * 64 + fr, col0 = u.pn * BM + wc * 32 + 8 * fq;
; #pragma unroll
;         for (int ai = 0; ai < 2; ++ai) {
;             f32x4 r[4][2][2];
; #pragma unroll
;             for (int m = 0; m < 4; ++m)
; #pragma unroll
;                 for (int bj = 0; bj < 2; ++bj) { const size_t o = (size_t)(row0 + ai * HALF + m * 16) * DM + col0 + bj * HALF;
;                     if (RB) { const u32x4 w = *(const u32x4*)((const bf16_t*)res + o); r[m][bj][0] = (f32x4){bflo(w.x), bfhi(w.x), bflo(w.y), bfhi(w.y)}; r[m][bj][1] = (f32x4){bflo(w.z), bfhi(w.z), bflo(w.w), bfhi(w.w)}; }
;                     else { r[m][bj][0] = __builtin_nontemporal_load((const f32x4*)((const float*)res + o)); r[m][bj][1] = __builtin_nontemporal_load((const f32x4*)((const float*)res + o + 4)); } }
; #pragma unroll
;             for (int m = 0; m < 4; ++m) { const int row = row0 + ai * HALF + m * 16; const size_t off = (size_t)row * DM + col0; float s = 0.f;
; #pragma unroll
;                 for (int bj = 0; bj < 2; ++bj) { const f32x4 v0 = acc[ai][bj][m][0] + r[m][bj][0], v1 = acc[ai][bj][m][1] + r[m][bj][1];
;                     u32x4 w; w.x = cvt_pk_bf16(v0[0], v0[1]); w.y = cvt_pk_bf16(v0[2], v0[3]); w.z = cvt_pk_bf16(v1[0], v1[1]); w.w = cvt_pk_bf16(v1[2], v1[3]);
;                     *(u32x4*)(outb + off + bj * HALF) = w;
;                     s += ((v0[0] * v0[0] + v0[1] * v0[1]) + (v0[2] * v0[2] + v0[3] * v0[3])) + ((v1[0] * v1[0] + v1[1] * v1[1]) + (v1[2] * v1[2] + v1[3] * v1[3])); }
;                 s += __shfl_xor(s, 16); s += __shfl_xor(s, 32);
;                 if (fq == 0) ssq[(size_t)row * 32 + u.pn * 4 + wc] = s; }
	v_mfma_f32_16x16x32_bf16 v[52:55], v[198:201], v[144:147], v[52:55]
	v_mfma_f32_16x16x32_bf16 v[48:51], v[210:213], v[144:147], v[48:51]
	s_add_i32 s42, s42, 2
	s_add_u32 s40, s40, 0x100
	s_addc_u32 s41, s41, 0
	s_cmpk_gt_u32 s42, 0x55
	s_mov_b64 s[2:3], s[18:19]
	v_mfma_f32_16x16x32_bf16 v[36:39], v[198:201], v[168:171], v[36:39]
	v_mfma_f32_16x16x32_bf16 v[32:35], v[210:213], v[168:171], v[32:35]
	v_mfma_f32_16x16x32_bf16 v[20:23], v[198:201], v[176:179], v[20:23]
	v_mfma_f32_16x16x32_bf16 v[16:19], v[210:213], v[176:179], v[16:19]
	v_mfma_f32_16x16x32_bf16 v[4:7], v[198:201], v[190:193], v[4:7]
	v_mfma_f32_16x16x32_bf16 v[0:3], v[210:213], v[190:193], v[0:3]
	v_mfma_f32_16x16x32_bf16 v[52:55], v[202:205], v[148:151], v[52:55]
	v_mfma_f32_16x16x32_bf16 v[48:51], v[214:217], v[148:151], v[48:51]
	v_mfma_f32_16x16x32_bf16 v[36:39], v[202:205], v[172:175], v[36:39]
	v_mfma_f32_16x16x32_bf16 v[32:35], v[214:217], v[172:175], v[32:35]
	v_mfma_f32_16x16x32_bf16 v[20:23], v[202:205], v[180:183], v[20:23]
	v_mfma_f32_16x16x32_bf16 v[16:19], v[214:217], v[180:183], v[16:19]
	v_mfma_f32_16x16x32_bf16 v[4:7], v[202:205], v[194:197], v[4:7]
	v_mfma_f32_16x16x32_bf16 v[0:3], v[214:217], v[194:197], v[0:3]
	s_barrier
	s_cbranch_scc0 .LBB0_914
	s_waitcnt lgkmcnt(0)
	v_mbcnt_lo_u32_b32 v128, -1, 0
	v_mbcnt_hi_u32_b32 v128, -1, v128
	s_lshl_b32 s2, s52, 8
	v_ashrrev_i32_e32 v129, 4, v128
	v_and_b32_e32 v128, 15, v128
	s_add_i32 s2, s2, s22
	v_readlane_b32 s3, v254, 19
	v_add_u32_e32 v172, s2, v128
	s_lshl_b32 s2, s8, 8
	s_or_b32 s2, s2, s3
	v_lshl_add_u32 v168, v129, 3, s2
	v_ashrrev_i32_e32 v169, 31, v168
	v_lshlrev_b64 v[190:191], 1, v[168:169]
	v_ashrrev_i32_e32 v173, 31, v172
	v_lshl_add_u64 v[170:171], s[6:7], 0, v[190:191]
	v_lshlrev_b64 v[192:193], 12, v[172:173]
	v_lshl_add_u64 v[132:133], v[170:171], 0, v[192:193]
	v_cmp_eq_u32_e32 vcc, 0, v129
	global_load_dwordx4 v[128:131], v[132:133], off
	v_add_u32_e32 v182, 16, v172
	v_ashrrev_i32_e32 v183, 31, v182
	v_add_u32_e32 v178, 32, v172
	v_lshlrev_b64 v[184:185], 12, v[182:183]
	v_ashrrev_i32_e32 v179, 31, v178
	v_add_u32_e32 v174, 48, v172
	v_lshlrev_b64 v[180:181], 12, v[178:179]
	v_ashrrev_i32_e32 v175, 31, v174
	v_lshlrev_b64 v[176:177], 12, v[174:175]
	v_lshl_add_u64 v[192:193], s[6:7], 0, v[192:193]
	v_lshl_add_u64 v[190:191], v[192:193], 0, v[190:191]
	s_lshl_b32 s18, s8, 2
	s_ashr_i32 s19, s18, 31
	s_waitcnt vmcnt(0)
	v_lshlrev_b32_e32 v194, 16, v128
	v_and_b32_e32 v195, 0xffff0000, v128
	v_lshlrev_b32_e32 v196, 16, v129
	v_and_b32_e32 v197, 0xffff0000, v129
	v_lshlrev_b32_e32 v198, 16, v130
	v_and_b32_e32 v199, 0xffff0000, v130
	v_lshlrev_b32_e32 v200, 16, v131
	v_and_b32_e32 v201, 0xffff0000, v131
	global_load_dwordx4 v[128:131], v[132:133], off offset:256
	v_pk_add_f32 v[126:127], v[126:127], v[196:197]
	v_pk_add_f32 v[124:125], v[124:125], v[194:195]
	v_pk_add_f32 v[196:197], v[120:121], v[198:199]
	v_pk_add_f32 v[194:195], v[122:123], v[200:201]
	s_waitcnt vmcnt(0)
	v_lshlrev_b32_e32 v202, 16, v128
	v_and_b32_e32 v203, 0xffff0000, v128
	v_lshlrev_b32_e32 v204, 16, v129
	v_and_b32_e32 v205, 0xffff0000, v129
	v_lshl_add_u64 v[128:129], v[170:171], 0, v[184:185]
	global_load_dwordx4 v[148:151], v[128:129], off
	global_load_dwordx4 v[144:147], v[128:129], off offset:256
	v_lshl_add_u64 v[128:129], v[170:171], 0, v[180:181]
	global_load_dwordx4 v[140:143], v[128:129], off
	global_load_dwordx4 v[136:139], v[128:129], off offset:256
	v_lshl_add_u64 v[128:129], v[170:171], 0, v[176:177]
	v_lshlrev_b32_e32 v206, 16, v130
	v_and_b32_e32 v207, 0xffff0000, v130
	v_lshlrev_b32_e32 v210, 16, v131
	v_and_b32_e32 v211, 0xffff0000, v131
	global_load_dwordx4 v[132:135], v[128:129], off
	s_nop 0
	global_load_dwordx4 v[128:131], v[128:129], off offset:256
	v_cvt_pk_bf16_f32 v120, v124, v125
	v_cvt_pk_bf16_f32 v121, v126, v127
	v_cvt_pk_bf16_f32 v122, v196, v197
	v_cvt_pk_bf16_f32 v123, v194, v195
	global_store_dwordx4 v[190:191], v[120:123], off
	v_pk_add_f32 v[118:119], v[118:119], v[204:205]
	v_pk_add_f32 v[116:117], v[116:117], v[202:203]
	v_mul_f32_e32 v120, v125, v125
	v_mul_f32_e32 v121, v127, v127
	v_fmac_f32_e32 v120, v124, v124
	v_fmac_f32_e32 v121, v126, v126
	v_add_f32_e32 v120, v120, v121
	v_mul_f32_e32 v121, v197, v197
	v_mul_f32_e32 v122, v195, v195
	v_fmac_f32_e32 v121, v196, v196
	v_fmac_f32_e32 v122, v194, v194
	v_add_f32_e32 v121, v121, v122
	v_pk_add_f32 v[122:123], v[112:113], v[206:207]
	v_cvt_pk_bf16_f32 v112, v116, v117
	v_cvt_pk_bf16_f32 v113, v118, v119
	v_add_f32_e32 v124, v120, v121
	v_pk_add_f32 v[120:121], v[114:115], v[210:211]
	v_cvt_pk_bf16_f32 v114, v122, v123
	s_nop 0
	v_cvt_pk_bf16_f32 v115, v120, v121
	global_store_dwordx4 v[190:191], v[112:115], off offset:256
	s_nop 1
	v_mul_f32_e32 v112, v117, v117
	v_mul_f32_e32 v113, v119, v119
	v_fmac_f32_e32 v112, v116, v116
	v_fmac_f32_e32 v113, v118, v118
	v_add_f32_e32 v112, v112, v113
	v_mul_f32_e32 v113, v123, v123
	v_mul_f32_e32 v114, v121, v121
	v_fmac_f32_e32 v113, v122, v122
	v_fmac_f32_e32 v114, v120, v120
	v_add_f32_e32 v113, v113, v114
	v_add_f32_e32 v112, v112, v113
	v_and_b32_e32 v114, 64, v209
	v_add_f32_e32 v113, v124, v112
	v_xor_b32_e32 v112, 16, v209
	v_add_u32_e32 v115, 64, v114
	v_cmp_lt_i32_e64 s[2:3], v112, v115
	s_nop 1
	v_cndmask_b32_e64 v112, v209, v112, s[2:3]
	v_lshlrev_b32_e32 v112, 2, v112
	ds_bpermute_b32 v114, v112, v113
	s_waitcnt lgkmcnt(0)
	v_add_f32_e32 v114, v113, v114
	v_xor_b32_e32 v113, 32, v209
	v_cmp_lt_i32_e64 s[2:3], v113, v115
	s_nop 1
	v_cndmask_b32_e64 v113, v209, v113, s[2:3]
	v_lshlrev_b32_e32 v113, 2, v113
	ds_bpermute_b32 v115, v113, v114
	s_and_saveexec_b64 s[2:3], vcc
	s_cbranch_execz .LBB0_917
	v_lshlrev_b64 v[116:117], 7, v[172:173]
	v_lshl_add_u64 v[116:117], s[16:17], 0, v[116:117]
	v_lshl_add_u64 v[116:117], s[18:19], 2, v[116:117]
	s_lshl_b32 s8, s27, 2
	v_lshl_add_u64 v[116:117], v[116:117], 0, s[8:9]
	s_waitcnt lgkmcnt(0)
	v_add_f32_e32 v114, v114, v115
	global_store_dword v[116:117], v114, off

; #define PG8_STAGE(bufoff, gbase, voff) do { _Pragma("unroll") for (int _i = 0; _i < 2; ++_i) \
;         __builtin_amdgcn_global_load_lds((const unsigned*)((const char*)(gbase) + (voff)[_i]), (LAS unsigned*)(lds + (bufoff) + ldsw + _i * 8192), 16, 0, 0); } while (0)
; #define PG8_LDA(dst, b, h) do { _Pragma("unroll") for (int m = 0; m < 4; ++m) _Pragma("unroll") for (int k = 0; k < 2; ++k) dst[m][k] = *(const LAS bf16x8*)(lds + PG8_SA(b, h) + aoff + m * 2048 + k * 1024); } while (0)
; #define PG8_LDB(dst, b, h) do { _Pragma("unroll") for (int n = 0; n < 2; ++n) _Pragma("unroll") for (int k = 0; k < 2; ++k) dst[n][k] = *(const LAS bf16x8*)(lds + PG8_SB(b, h) + boff + n * 2048 + k * 1024); } while (0)
; #define PG8_MMA(ai, bj, At, Bt) do { __builtin_amdgcn_s_setprio(1); _Pragma("unroll") for (int m = 0; m < 4; ++m) _Pragma("unroll") for (int n = 0; n < 2; ++n) _Pragma("unroll") for (int k = 0; k < 2; ++k) \
;         acc[ai][bj][m][n] = __builtin_amdgcn_mfma_f32_16x16x32_bf16(Bt[n][k], At[m][k], acc[ai][bj][m][n], 0, 0, 0); __builtin_amdgcn_s_setprio(0); } while (0)
; #define PG8_WAIT_L(n) asm volatile("s_waitcnt lgkmcnt(" #n ")" ::: "memory")
; template <class Epi, bool KS0 = false>
; __device__ __forceinline__ void gemm_phase(const int WID, LAS unsigned char* lds, const Gemm g, const StaticOrder& S, const Epi& E) {
;     ...
;         const bool has_next = S.next(ui + 1, nxt);
;         const char* nA = has_next ? (const char*)g.A + (size_t)nxt.pm * tstep : cA; const char* nB = has_next ? (const char*)g.Bt + (size_t)nxt.pn * tstep : cB;
;         for (int t = 0; t < nt; t += 2) {
;             const bool last = (t == nt - 2);
;             const char* a1 = cA + (size_t)(t + 1) * kstep;
;             const char* a2 = last ? nA : cA + (size_t)(t + 2) * kstep; const char* b2 = last ? nB : cB + (size_t)(t + 2) * kstep;
;             const char* a3 = a2 + kstep; const char* b3 = b2 + kstep;
;             PG8_LDB(B0, 0, 0); PG8_SCHED; PG8_LDA(At, 0, 0); PG8_STAGE(PG8_SA(1, 1), a1 + hstep, voffA);
;             PG8_WAIT_L(8); PG8_BAR; PG8_WAIT_L(0); PG8_MMA(0, 0, At, B0); PG8_BAR; PG8_SCHED;
;     ...
;         for (int a = 0; a < 2; ++a)
; #pragma unroll
;             for (int b = 0; b < 2; ++b)
; #pragma unroll
;                 for (int m = 0; m < 4; ++m)
; #pragma unroll
;                     for (int n = 0; n < 2; ++n) acc[a][b][m][n] = (f32x4){0.f, 0.f, 0.f, 0.f};
.LBB0_1005:
	s_ashr_i32 s43, s42, 31
	v_cmp_lt_i64_e32 vcc, s[12:13], v[204:205]
	s_lshl_b64 s[12:13], s[42:43], 20
	s_add_u32 s44, s6, s12
	s_addc_u32 s45, s7, s13
	s_and_b64 s[12:13], vcc, exec
	s_cselect_b32 s3, s45, s9
	s_cselect_b32 s14, s44, s8
	s_ashr_i32 s41, s40, 31
	s_lshl_b64 s[12:13], s[40:41], 20
	s_add_u32 s46, s56, s12
	s_addc_u32 s47, s57, s13
	s_and_b64 s[12:13], vcc, exec
	s_cselect_b32 s15, s47, s11
	s_cselect_b32 s36, s46, s10
	s_add_u32 s8, s8, 0x80080
	s_addc_u32 s9, s9, 0
	s_add_u32 s37, s10, 0x100
	v_mov_b32_e32 v0, 0
	s_addc_u32 s41, s11, 0
	s_mov_b32 s43, -2
	s_waitcnt lgkmcnt(0)
	v_mov_b32_e32 v1, v0
	v_mov_b32_e32 v2, v0
	v_mov_b32_e32 v3, v0
	v_mov_b32_e32 v4, v0
	v_mov_b32_e32 v5, v0
	v_mov_b32_e32 v6, v0
	v_mov_b32_e32 v7, v0
	v_mov_b32_e32 v16, v0
	v_mov_b32_e32 v17, v0
	v_mov_b32_e32 v18, v0
	v_mov_b32_e32 v19, v0
	v_mov_b32_e32 v20, v0
	v_mov_b32_e32 v21, v0
	v_mov_b32_e32 v22, v0
	v_mov_b32_e32 v23, v0
	v_mov_b32_e32 v32, v0
	v_mov_b32_e32 v33, v0
	v_mov_b32_e32 v34, v0
	v_mov_b32_e32 v35, v0
	v_mov_b32_e32 v36, v0
	v_mov_b32_e32 v37, v0
	v_mov_b32_e32 v38, v0
	v_mov_b32_e32 v39, v0
	v_mov_b32_e32 v48, v0
	v_mov_b32_e32 v49, v0
	v_mov_b32_e32 v50, v0
	v_mov_b32_e32 v51, v0
	v_mov_b32_e32 v52, v0
	v_mov_b32_e32 v53, v0
	v_mov_b32_e32 v54, v0
	v_mov_b32_e32 v55, v0
	v_mov_b32_e32 v8, v0
	v_mov_b32_e32 v9, v0
	v_mov_b32_e32 v10, v0
	v_mov_b32_e32 v11, v0
	v_mov_b32_e32 v12, v0
	v_mov_b32_e32 v13, v0
	v_mov_b32_e32 v14, v0
	v_mov_b32_e32 v15, v0
	v_mov_b32_e32 v24, v0
	v_mov_b32_e32 v25, v0
	v_mov_b32_e32 v26, v0
	v_mov_b32_e32 v27, v0
	v_mov_b32_e32 v28, v0
	v_mov_b32_e32 v29, v0
	v_mov_b32_e32 v30, v0
	v_mov_b32_e32 v31, v0
	v_mov_b32_e32 v40, v0
	v_mov_b32_e32 v41, v0
	v_mov_b32_e32 v42, v0
	v_mov_b32_e32 v43, v0
	v_mov_b32_e32 v44, v0
	v_mov_b32_e32 v45, v0
	v_mov_b32_e32 v46, v0
	v_mov_b32_e32 v47, v0
	v_mov_b32_e32 v56, v0
	v_mov_b32_e32 v57, v0
	v_mov_b32_e32 v58, v0
	v_mov_b32_e32 v59, v0
	v_mov_b32_e32 v60, v0
	v_mov_b32_e32 v61, v0
	v_mov_b32_e32 v62, v0
	v_mov_b32_e32 v63, v0
	v_mov_b32_e32 v64, v0
	v_mov_b32_e32 v65, v0
	v_mov_b32_e32 v66, v0
	v_mov_b32_e32 v67, v0
	v_mov_b32_e32 v68, v0
	v_mov_b32_e32 v69, v0
	v_mov_b32_e32 v70, v0
	v_mov_b32_e32 v71, v0
	v_mov_b32_e32 v80, v0
	v_mov_b32_e32 v81, v0
	v_mov_b32_e32 v82, v0
	v_mov_b32_e32 v83, v0
	v_mov_b32_e32 v84, v0
	v_mov_b32_e32 v85, v0
	v_mov_b32_e32 v86, v0
	v_mov_b32_e32 v87, v0
	v_mov_b32_e32 v96, v0
	v_mov_b32_e32 v97, v0
	v_mov_b32_e32 v98, v0
	v_mov_b32_e32 v99, v0
	v_mov_b32_e32 v100, v0
	v_mov_b32_e32 v101, v0
	v_mov_b32_e32 v102, v0
	v_mov_b32_e32 v103, v0
	v_mov_b32_e32 v128, v0
	v_mov_b32_e32 v129, v0
	v_mov_b32_e32 v130, v0
	v_mov_b32_e32 v131, v0
	v_mov_b32_e32 v132, v0
	v_mov_b32_e32 v133, v0
	v_mov_b32_e32 v134, v0
	v_mov_b32_e32 v135, v0
	v_mov_b32_e32 v72, v0
	v_mov_b32_e32 v73, v0
	v_mov_b32_e32 v74, v0
	v_mov_b32_e32 v75, v0
	v_mov_b32_e32 v76, v0
	v_mov_b32_e32 v77, v0
	v_mov_b32_e32 v78, v0
	v_mov_b32_e32 v79, v0
	v_mov_b32_e32 v88, v0
	v_mov_b32_e32 v89, v0
	v_mov_b32_e32 v90, v0
	v_mov_b32_e32 v91, v0
	v_mov_b32_e32 v92, v0
	v_mov_b32_e32 v93, v0
	v_mov_b32_e32 v94, v0
	v_mov_b32_e32 v95, v0
	v_mov_b32_e32 v116, v0
	v_mov_b32_e32 v117, v0
	v_mov_b32_e32 v118, v0
	v_mov_b32_e32 v119, v0
	v_mov_b32_e32 v124, v0
	v_mov_b32_e32 v125, v0
	v_mov_b32_e32 v126, v0
	v_mov_b32_e32 v127, v0
	v_mov_b32_e32 v140, v0
	v_mov_b32_e32 v141, v0
	v_mov_b32_e32 v142, v0
	v_mov_b32_e32 v143, v0
	v_mov_b32_e32 v152, v0
	v_mov_b32_e32 v153, v0
	v_mov_b32_e32 v154, v0
	v_mov_b32_e32 v155, v0
	ds_read_b128 v[104:107], v246
	ds_read_b128 v[108:111], v246 offset:1024
	ds_read_b128 v[112:115], v246 offset:2048
	ds_read_b128 v[120:123], v246 offset:3072
.LBB0_1006:
	ds_read_b128 v[136:139], v247
	ds_read_b128 v[144:147], v247 offset:1024
	ds_read_b128 v[148:151], v247 offset:2048
	ds_read_b128 v[156:159], v247 offset:3072
	ds_read_b128 v[160:163], v247 offset:4096
	ds_read_b128 v[164:167], v247 offset:5120
	ds_read_b128 v[168:171], v247 offset:6144
	ds_read_b128 v[172:175], v247 offset:7168
	s_add_u32 s10, s8, 0xfff80080
	s_addc_u32 s11, s9, -1
	s_cmp_eq_u32 s43, 28
	s_cselect_b32 s13, s3, s11
	s_cselect_b32 s12, s14, s10
	s_cselect_b32 s11, s15, s41
	s_cselect_b32 s10, s36, s37
	v_lshl_add_u64 v[176:177], s[8:9], 0, v[200:201]
	s_add_i32 m0, s18, 0xc000
	s_nop 0
	global_load_lds_dwordx4 v[176:177], off
	s_add_i32 m0, s18, 0xe000
	s_nop 0
	global_load_lds_dwordx4 v202, s[8:9]
	s_waitcnt lgkmcnt(8)
	s_barrier
	s_waitcnt lgkmcnt(0)
	v_mfma_f32_16x16x32_bf16 v[152:155], v[104:107], v[136:139], v[152:155]
	v_mfma_f32_16x16x32_bf16 v[140:143], v[112:115], v[136:139], v[140:143]
	v_mfma_f32_16x16x32_bf16 v[124:127], v[104:107], v[148:151], v[124:127]
	v_mfma_f32_16x16x32_bf16 v[116:119], v[112:115], v[148:151], v[116:119]
	v_mfma_f32_16x16x32_bf16 v[92:95], v[104:107], v[160:163], v[92:95]
	v_mfma_f32_16x16x32_bf16 v[88:91], v[112:115], v[160:163], v[88:91]
	v_mfma_f32_16x16x32_bf16 v[76:79], v[104:107], v[168:171], v[76:79]
	v_mfma_f32_16x16x32_bf16 v[72:75], v[112:115], v[168:171], v[72:75]
	v_mfma_f32_16x16x32_bf16 v[152:155], v[108:111], v[144:147], v[152:155]
	v_mfma_f32_16x16x32_bf16 v[140:143], v[120:123], v[144:147], v[140:143]
	v_mfma_f32_16x16x32_bf16 v[124:127], v[108:111], v[156:159], v[124:127]
	v_mfma_f32_16x16x32_bf16 v[116:119], v[120:123], v[156:159], v[116:119]
	v_mfma_f32_16x16x32_bf16 v[92:95], v[108:111], v[164:167], v[92:95]
	v_mfma_f32_16x16x32_bf16 v[88:91], v[120:123], v[164:167], v[88:91]
	v_mfma_f32_16x16x32_bf16 v[76:79], v[108:111], v[172:175], v[76:79]
	v_mfma_f32_16x16x32_bf16 v[72:75], v[120:123], v[172:175], v[72:75]
	s_barrier
; #define PG8_STAGE(bufoff, gbase, voff) do { _Pragma("unroll") for (int _i = 0; _i < 2; ++_i) \
;         __builtin_amdgcn_global_load_lds((const unsigned*)((const char*)(gbase) + (voff)[_i]), (LAS unsigned*)(lds + (bufoff) + ldsw + _i * 8192), 16, 0, 0); } while (0)
; #define PG8_LDA(dst, b, h) do { _Pragma("unroll") for (int m = 0; m < 4; ++m) _Pragma("unroll") for (int k = 0; k < 2; ++k) dst[m][k] = *(const LAS bf16x8*)(lds + PG8_SA(b, h) + aoff + m * 2048 + k * 1024); } while (0)
; #define PG8_LDB(dst, b, h) do { _Pragma("unroll") for (int n = 0; n < 2; ++n) _Pragma("unroll") for (int k = 0; k < 2; ++k) dst[n][k] = *(const LAS bf16x8*)(lds + PG8_SB(b, h) + boff + n * 2048 + k * 1024); } while (0)
; #define PG8_MMA(ai, bj, At, Bt) do { __builtin_amdgcn_s_setprio(1); _Pragma("unroll") for (int m = 0; m < 4; ++m) _Pragma("unroll") for (int n = 0; n < 2; ++n) _Pragma("unroll") for (int k = 0; k < 2; ++k) \
;         acc[ai][bj][m][n] = __builtin_amdgcn_mfma_f32_16x16x32_bf16(Bt[n][k], At[m][k], acc[ai][bj][m][n], 0, 0, 0); __builtin_amdgcn_s_setprio(0); } while (0)
; #define PG8_WAIT_V(n) asm volatile("s_waitcnt vmcnt(" #n ")" ::: "memory")
; #define PG8_WAIT_L(n) asm volatile("s_waitcnt lgkmcnt(" #n ")" ::: "memory")
; #define PG8_BAR __builtin_amdgcn_s_barrier()
; #define PG8_SCHED __builtin_amdgcn_sched_barrier(0)
; template <class Epi, bool KS0 = false>
; __device__ __forceinline__ void gemm_phase(const int WID, LAS unsigned char* lds, const Gemm g, const StaticOrder& S, const Epi& E) {
;     ...
;             PG8_LDB(B1, 0, 1); PG8_STAGE(PG8_SB(0, 0), b2, voffB);
;             PG8_BAR; PG8_WAIT_L(0); PG8_MMA(0, 1, At, B1); PG8_BAR;
;             PG8_LDA(At, 0, 1); PG8_STAGE(PG8_SA(0, 0), a2, voffA);
;             PG8_BAR; PG8_WAIT_L(0); PG8_MMA(1, 0, At, B0); PG8_BAR; PG8_SCHED;
;             PG8_STAGE(PG8_SB(0, 1), b2 + hstep, voffB);
;             PG8_WAIT_V(6); PG8_BAR; PG8_MMA(1, 1, At, B1); PG8_BAR;
;             PG8_LDB(B0, 1, 0); PG8_SCHED; PG8_LDA(At, 1, 0); PG8_STAGE(PG8_SA(0, 1), a2 + hstep, voffA);
;             PG8_WAIT_L(8); PG8_BAR; PG8_WAIT_L(0); PG8_MMA(0, 0, At, B0); PG8_BAR; PG8_SCHED;
	ds_read_b128 v[176:179], v248
	ds_read_b128 v[180:183], v248 offset:1024
	ds_read_b128 v[184:187], v248 offset:2048
	ds_read_b128 v[188:191], v248 offset:3072
	s_add_i32 s48, s50, s26
	v_lshl_add_u64 v[210:211], s[10:11], 0, v[194:195]
	s_mov_b32 m0, s48
	s_nop 0
	global_load_lds_dwordx4 v[210:211], off
	v_lshl_add_u64 v[212:213], s[10:11], 0, v[198:199]
	s_add_i32 m0, s48, 0x2000
	s_nop 0
	global_load_lds_dwordx4 v[212:213], off
	s_barrier
	s_waitcnt lgkmcnt(0)
	v_mfma_f32_16x16x32_bf16 v[132:135], v[176:179], v[136:139], v[132:135]
	v_mfma_f32_16x16x32_bf16 v[128:131], v[184:187], v[136:139], v[128:131]
	s_mov_b32 m0, s18
	v_lshl_add_u64 v[214:215], s[12:13], 0, v[192:193]
	v_mfma_f32_16x16x32_bf16 v[100:103], v[176:179], v[148:151], v[100:103]
	v_mfma_f32_16x16x32_bf16 v[96:99], v[184:187], v[148:151], v[96:99]
	v_mfma_f32_16x16x32_bf16 v[84:87], v[176:179], v[160:163], v[84:87]
	v_mfma_f32_16x16x32_bf16 v[80:83], v[184:187], v[160:163], v[80:83]
	v_mfma_f32_16x16x32_bf16 v[68:71], v[176:179], v[168:171], v[68:71]
	v_mfma_f32_16x16x32_bf16 v[64:67], v[184:187], v[168:171], v[64:67]
	v_mfma_f32_16x16x32_bf16 v[132:135], v[180:183], v[144:147], v[132:135]
	v_mfma_f32_16x16x32_bf16 v[128:131], v[188:191], v[144:147], v[128:131]
	v_mfma_f32_16x16x32_bf16 v[100:103], v[180:183], v[156:159], v[100:103]
	v_mfma_f32_16x16x32_bf16 v[96:99], v[188:191], v[156:159], v[96:99]
	v_mfma_f32_16x16x32_bf16 v[84:87], v[180:183], v[164:167], v[84:87]
	v_mfma_f32_16x16x32_bf16 v[80:83], v[188:191], v[164:167], v[80:83]
	v_mfma_f32_16x16x32_bf16 v[68:71], v[180:183], v[172:175], v[68:71]
	v_mfma_f32_16x16x32_bf16 v[64:67], v[188:191], v[172:175], v[64:67]
	s_barrier
	ds_read_b128 v[136:139], v247 offset:16384
	ds_read_b128 v[144:147], v247 offset:17408
	ds_read_b128 v[148:151], v247 offset:18432
	ds_read_b128 v[156:159], v247 offset:19456
	ds_read_b128 v[160:163], v247 offset:20480
	ds_read_b128 v[164:167], v247 offset:21504
	ds_read_b128 v[168:171], v247 offset:22528
	ds_read_b128 v[172:175], v247 offset:23552
	global_load_lds_dwordx4 v[214:215], off
	v_lshl_add_u64 v[216:217], s[12:13], 0, v[196:197]
	s_mov_b32 m0, s19
	s_nop 0
	global_load_lds_dwordx4 v[216:217], off
	s_waitcnt vmcnt(10)
	s_barrier
	s_waitcnt lgkmcnt(0)
	v_mfma_f32_16x16x32_bf16 v[60:63], v[104:107], v[136:139], v[60:63]
	v_mfma_f32_16x16x32_bf16 v[56:59], v[112:115], v[136:139], v[56:59]
	v_mfma_f32_16x16x32_bf16 v[44:47], v[104:107], v[148:151], v[44:47]
	v_mfma_f32_16x16x32_bf16 v[40:43], v[112:115], v[148:151], v[40:43]
	v_mfma_f32_16x16x32_bf16 v[28:31], v[104:107], v[160:163], v[28:31]
	v_mfma_f32_16x16x32_bf16 v[24:27], v[112:115], v[160:163], v[24:27]
	v_mfma_f32_16x16x32_bf16 v[12:15], v[104:107], v[168:171], v[12:15]
	v_mfma_f32_16x16x32_bf16 v[8:11], v[112:115], v[168:171], v[8:11]
	v_mfma_f32_16x16x32_bf16 v[60:63], v[108:111], v[144:147], v[60:63]
	v_mfma_f32_16x16x32_bf16 v[56:59], v[120:123], v[144:147], v[56:59]
	v_mfma_f32_16x16x32_bf16 v[44:47], v[108:111], v[156:159], v[44:47]
	v_mfma_f32_16x16x32_bf16 v[40:43], v[120:123], v[156:159], v[40:43]
	v_mfma_f32_16x16x32_bf16 v[28:31], v[108:111], v[164:167], v[28:31]
	v_mfma_f32_16x16x32_bf16 v[24:27], v[120:123], v[164:167], v[24:27]
	v_mfma_f32_16x16x32_bf16 v[12:15], v[108:111], v[172:175], v[12:15]
	v_mfma_f32_16x16x32_bf16 v[8:11], v[120:123], v[172:175], v[8:11]
	s_barrier
	v_add_u32_e32 v104, 0x18000, v245
	ds_read_b128 v[108:111], v104 offset:1024
	ds_read_b128 v[112:115], v104 offset:2048
	ds_read_b128 v[120:123], v104 offset:3072
	ds_read_b128 v[104:107], v104
	s_add_u32 s48, s10, 0x80000
	s_addc_u32 s49, s11, 0
	s_add_i32 s54, s51, s26
	s_mov_b32 m0, s54
	s_nop 0
	global_load_lds_dwordx4 v194, s[48:49]
	s_add_i32 m0, s54, 0x2000
	s_nop 0
	global_load_lds_dwordx4 v198, s[48:49]
	s_waitcnt vmcnt(6)
	s_barrier
	v_mfma_f32_16x16x32_bf16 v[52:55], v[176:179], v[136:139], v[52:55]
	v_mfma_f32_16x16x32_bf16 v[48:51], v[184:187], v[136:139], v[48:51]
	s_add_i32 s48, 0, 0x18000
	v_mfma_f32_16x16x32_bf16 v[36:39], v[176:179], v[148:151], v[36:39]
	v_mfma_f32_16x16x32_bf16 v[32:35], v[184:187], v[148:151], v[32:35]
	v_mfma_f32_16x16x32_bf16 v[20:23], v[176:179], v[160:163], v[20:23]
	v_mfma_f32_16x16x32_bf16 v[16:19], v[184:187], v[160:163], v[16:19]
	v_mfma_f32_16x16x32_bf16 v[4:7], v[176:179], v[168:171], v[4:7]
	v_mfma_f32_16x16x32_bf16 v[0:3], v[184:187], v[168:171], v[0:3]
	v_mfma_f32_16x16x32_bf16 v[52:55], v[180:183], v[144:147], v[52:55]
	v_mfma_f32_16x16x32_bf16 v[48:51], v[188:191], v[144:147], v[48:51]
	v_mfma_f32_16x16x32_bf16 v[36:39], v[180:183], v[156:159], v[36:39]
	v_mfma_f32_16x16x32_bf16 v[32:35], v[188:191], v[156:159], v[32:35]
	v_mfma_f32_16x16x32_bf16 v[20:23], v[180:183], v[164:167], v[20:23]
	v_mfma_f32_16x16x32_bf16 v[16:19], v[188:191], v[164:167], v[16:19]
	v_mfma_f32_16x16x32_bf16 v[4:7], v[180:183], v[172:175], v[4:7]
	v_mfma_f32_16x16x32_bf16 v[0:3], v[188:191], v[172:175], v[0:3]
	s_barrier
	ds_read_b128 v[136:139], v247 offset:32768
	ds_read_b128 v[144:147], v247 offset:33792
	ds_read_b128 v[148:151], v247 offset:34816
	ds_read_b128 v[156:159], v247 offset:35840
	ds_read_b128 v[160:163], v247 offset:36864
	ds_read_b128 v[164:167], v247 offset:37888
	ds_read_b128 v[168:171], v247 offset:38912
	ds_read_b128 v[172:175], v247 offset:39936
	s_add_u32 s12, s12, 0x80000
	s_addc_u32 s13, s13, 0
	s_mov_b32 m0, s20
	v_lshl_add_u64 v[176:177], s[12:13], 0, v[192:193]
	global_load_lds_dwordx4 v[176:177], off
	s_mov_b32 m0, s21
	s_nop 0
	global_load_lds_dwordx4 v196, s[12:13]
	s_waitcnt lgkmcnt(8)
	s_barrier
; #define PG8_STAGE(bufoff, gbase, voff) do { _Pragma("unroll") for (int _i = 0; _i < 2; ++_i) \
;         __builtin_amdgcn_global_load_lds((const unsigned*)((const char*)(gbase) + (voff)[_i]), (LAS unsigned*)(lds + (bufoff) + ldsw + _i * 8192), 16, 0, 0); } while (0)
; #define PG8_LDA(dst, b, h) do { _Pragma("unroll") for (int m = 0; m < 4; ++m) _Pragma("unroll") for (int k = 0; k < 2; ++k) dst[m][k] = *(const LAS bf16x8*)(lds + PG8_SA(b, h) + aoff + m * 2048 + k * 1024); } while (0)
; #define PG8_LDB(dst, b, h) do { _Pragma("unroll") for (int n = 0; n < 2; ++n) _Pragma("unroll") for (int k = 0; k < 2; ++k) dst[n][k] = *(const LAS bf16x8*)(lds + PG8_SB(b, h) + boff + n * 2048 + k * 1024); } while (0)
; #define PG8_MMA(ai, bj, At, Bt) do { __builtin_amdgcn_s_setprio(1); _Pragma("unroll") for (int m = 0; m < 4; ++m) _Pragma("unroll") for (int n = 0; n < 2; ++n) _Pragma("unroll") for (int k = 0; k < 2; ++k) \
;         acc[ai][bj][m][n] = __builtin_amdgcn_mfma_f32_16x16x32_bf16(Bt[n][k], At[m][k], acc[ai][bj][m][n], 0, 0, 0); __builtin_amdgcn_s_setprio(0); } while (0)
; #define PG8_WAIT_V(n) asm volatile("s_waitcnt vmcnt(" #n ")" ::: "memory")
; #define PG8_WAIT_L(n) asm volatile("s_waitcnt lgkmcnt(" #n ")" ::: "memory")
; #define PG8_BAR __builtin_amdgcn_s_barrier()
; #define PG8_SCHED __builtin_amdgcn_sched_barrier(0)
; template <class Epi, bool KS0 = false>
; __device__ __forceinline__ void gemm_phase(const int WID, LAS unsigned char* lds, const Gemm g, const StaticOrder& S, const Epi& E) {
;     ...
;             PG8_WAIT_L(8); PG8_BAR; PG8_WAIT_L(0); PG8_MMA(0, 0, At, B0); PG8_BAR; PG8_SCHED;
;             PG8_LDB(B1, 1, 1); PG8_STAGE(PG8_SB(1, 0), b3, voffB);
;             PG8_BAR; PG8_WAIT_L(0); PG8_MMA(0, 1, At, B1); PG8_BAR;
;             PG8_LDA(At, 1, 1); PG8_STAGE(PG8_SA(1, 0), a3, voffA);
;             PG8_BAR; PG8_WAIT_L(0); PG8_MMA(1, 0, At, B0); PG8_BAR; PG8_SCHED;
;             PG8_STAGE(PG8_SB(1, 1), b3 + hstep, voffB);
;             PG8_WAIT_V(6); PG8_BAR; PG8_MMA(1, 1, At, B1); PG8_BAR;
	s_waitcnt lgkmcnt(0)
	v_mfma_f32_16x16x32_bf16 v[152:155], v[104:107], v[136:139], v[152:155]
	v_mfma_f32_16x16x32_bf16 v[140:143], v[112:115], v[136:139], v[140:143]
	v_mfma_f32_16x16x32_bf16 v[124:127], v[104:107], v[148:151], v[124:127]
	v_mfma_f32_16x16x32_bf16 v[116:119], v[112:115], v[148:151], v[116:119]
	v_mfma_f32_16x16x32_bf16 v[92:95], v[104:107], v[160:163], v[92:95]
	v_mfma_f32_16x16x32_bf16 v[88:91], v[112:115], v[160:163], v[88:91]
	v_mfma_f32_16x16x32_bf16 v[76:79], v[104:107], v[168:171], v[76:79]
	v_mfma_f32_16x16x32_bf16 v[72:75], v[112:115], v[168:171], v[72:75]
	v_mfma_f32_16x16x32_bf16 v[152:155], v[108:111], v[144:147], v[152:155]
	v_mfma_f32_16x16x32_bf16 v[140:143], v[120:123], v[144:147], v[140:143]
	v_mfma_f32_16x16x32_bf16 v[124:127], v[108:111], v[156:159], v[124:127]
	v_mfma_f32_16x16x32_bf16 v[116:119], v[120:123], v[156:159], v[116:119]
	v_mfma_f32_16x16x32_bf16 v[92:95], v[108:111], v[164:167], v[92:95]
	v_mfma_f32_16x16x32_bf16 v[88:91], v[120:123], v[164:167], v[88:91]
	v_mfma_f32_16x16x32_bf16 v[76:79], v[108:111], v[172:175], v[76:79]
	v_mfma_f32_16x16x32_bf16 v[72:75], v[120:123], v[172:175], v[72:75]
	s_barrier
	s_add_i32 s12, 0, 0x1c000
	v_add_u32_e32 v188, s12, v245
	ds_read_b128 v[176:179], v188
	ds_read_b128 v[180:183], v188 offset:1024
	ds_read_b128 v[184:187], v188 offset:2048
	ds_read_b128 v[188:191], v188 offset:3072
	s_add_i32 s13, s48, s26
	v_lshl_add_u64 v[210:211], v[210:211], 0, s[30:31]
	s_mov_b32 m0, s13
	s_nop 0
	global_load_lds_dwordx4 v[210:211], off
	v_lshl_add_u64 v[210:211], v[212:213], 0, s[30:31]
	s_add_i32 m0, s13, 0x2000
	s_nop 0
	global_load_lds_dwordx4 v[210:211], off
	s_barrier
	s_waitcnt lgkmcnt(0)
	v_mfma_f32_16x16x32_bf16 v[132:135], v[176:179], v[136:139], v[132:135]
	v_mfma_f32_16x16x32_bf16 v[128:131], v[184:187], v[136:139], v[128:131]
	s_mov_b32 m0, s25
	v_lshl_add_u64 v[210:211], v[214:215], 0, s[30:31]
	v_mfma_f32_16x16x32_bf16 v[100:103], v[176:179], v[148:151], v[100:103]
	v_mfma_f32_16x16x32_bf16 v[96:99], v[184:187], v[148:151], v[96:99]
	v_mfma_f32_16x16x32_bf16 v[84:87], v[176:179], v[160:163], v[84:87]
	v_mfma_f32_16x16x32_bf16 v[80:83], v[184:187], v[160:163], v[80:83]
	v_mfma_f32_16x16x32_bf16 v[68:71], v[176:179], v[168:171], v[68:71]
	v_mfma_f32_16x16x32_bf16 v[64:67], v[184:187], v[168:171], v[64:67]
	v_mfma_f32_16x16x32_bf16 v[132:135], v[180:183], v[144:147], v[132:135]
	v_mfma_f32_16x16x32_bf16 v[128:131], v[188:191], v[144:147], v[128:131]
	v_mfma_f32_16x16x32_bf16 v[100:103], v[180:183], v[156:159], v[100:103]
	v_mfma_f32_16x16x32_bf16 v[96:99], v[188:191], v[156:159], v[96:99]
	v_mfma_f32_16x16x32_bf16 v[84:87], v[180:183], v[164:167], v[84:87]
	v_mfma_f32_16x16x32_bf16 v[80:83], v[188:191], v[164:167], v[80:83]
	v_mfma_f32_16x16x32_bf16 v[68:71], v[180:183], v[172:175], v[68:71]
	v_mfma_f32_16x16x32_bf16 v[64:67], v[188:191], v[172:175], v[64:67]
	s_barrier
	ds_read_b128 v[136:139], v247 offset:49152
	ds_read_b128 v[144:147], v247 offset:50176
	ds_read_b128 v[148:151], v247 offset:51200
	ds_read_b128 v[156:159], v247 offset:52224
	ds_read_b128 v[160:163], v247 offset:53248
	ds_read_b128 v[164:167], v247 offset:54272
	ds_read_b128 v[168:171], v247 offset:55296
	ds_read_b128 v[172:175], v247 offset:56320
	global_load_lds_dwordx4 v[210:211], off
	v_lshl_add_u64 v[210:211], v[216:217], 0, s[30:31]
	s_mov_b32 m0, s39
	s_nop 0
	global_load_lds_dwordx4 v[210:211], off
	s_waitcnt vmcnt(10)
	s_barrier
	s_waitcnt lgkmcnt(0)
	v_mfma_f32_16x16x32_bf16 v[60:63], v[104:107], v[136:139], v[60:63]
	v_mfma_f32_16x16x32_bf16 v[56:59], v[112:115], v[136:139], v[56:59]
	v_mfma_f32_16x16x32_bf16 v[44:47], v[104:107], v[148:151], v[44:47]
	v_mfma_f32_16x16x32_bf16 v[40:43], v[112:115], v[148:151], v[40:43]
	v_mfma_f32_16x16x32_bf16 v[28:31], v[104:107], v[160:163], v[28:31]
	v_mfma_f32_16x16x32_bf16 v[24:27], v[112:115], v[160:163], v[24:27]
	v_mfma_f32_16x16x32_bf16 v[12:15], v[104:107], v[168:171], v[12:15]
	v_mfma_f32_16x16x32_bf16 v[8:11], v[112:115], v[168:171], v[8:11]
	v_mfma_f32_16x16x32_bf16 v[60:63], v[108:111], v[144:147], v[60:63]
	v_mfma_f32_16x16x32_bf16 v[56:59], v[120:123], v[144:147], v[56:59]
	v_mfma_f32_16x16x32_bf16 v[44:47], v[108:111], v[156:159], v[44:47]
	v_mfma_f32_16x16x32_bf16 v[40:43], v[120:123], v[156:159], v[40:43]
	v_mfma_f32_16x16x32_bf16 v[28:31], v[108:111], v[164:167], v[28:31]
	v_mfma_f32_16x16x32_bf16 v[24:27], v[120:123], v[164:167], v[24:27]
	v_mfma_f32_16x16x32_bf16 v[12:15], v[108:111], v[172:175], v[12:15]
	v_mfma_f32_16x16x32_bf16 v[8:11], v[120:123], v[172:175], v[8:11]
	s_barrier
	ds_read_b128 v[104:107], v246
	ds_read_b128 v[108:111], v246 offset:1024
	ds_read_b128 v[112:115], v246 offset:2048
	ds_read_b128 v[120:123], v246 offset:3072
	s_add_u32 s10, s10, 0x80080
	s_addc_u32 s11, s11, 0
	s_add_i32 s12, s12, s26
	s_mov_b32 m0, s12
	s_nop 0
	global_load_lds_dwordx4 v194, s[10:11]
	s_add_i32 m0, s12, 0x2000
	s_nop 0
	global_load_lds_dwordx4 v198, s[10:11]
	s_waitcnt vmcnt(6)
	s_barrier
	v_mfma_f32_16x16x32_bf16 v[52:55], v[176:179], v[136:139], v[52:55]
	v_mfma_f32_16x16x32_bf16 v[48:51], v[184:187], v[136:139], v[48:51]
	s_add_i32 s43, s43, 2
	s_add_u32 s8, s8, 0x100
	s_addc_u32 s9, s9, 0
	s_add_u32 s37, s37, 0x100
	s_addc_u32 s41, s41, 0
	s_cmp_gt_u32 s43, 29
	v_mfma_f32_16x16x32_bf16 v[36:39], v[176:179], v[148:151], v[36:39]
	v_mfma_f32_16x16x32_bf16 v[32:35], v[184:187], v[148:151], v[32:35]
	v_mfma_f32_16x16x32_bf16 v[20:23], v[176:179], v[160:163], v[20:23]
	v_mfma_f32_16x16x32_bf16 v[16:19], v[184:187], v[160:163], v[16:19]
	v_mfma_f32_16x16x32_bf16 v[4:7], v[176:179], v[168:171], v[4:7]
	v_mfma_f32_16x16x32_bf16 v[0:3], v[184:187], v[168:171], v[0:3]
	v_mfma_f32_16x16x32_bf16 v[52:55], v[180:183], v[144:147], v[52:55]
	v_mfma_f32_16x16x32_bf16 v[48:51], v[188:191], v[144:147], v[48:51]
	v_mfma_f32_16x16x32_bf16 v[36:39], v[180:183], v[156:159], v[36:39]
	v_mfma_f32_16x16x32_bf16 v[32:35], v[188:191], v[156:159], v[32:35]
	v_mfma_f32_16x16x32_bf16 v[20:23], v[180:183], v[164:167], v[20:23]
	v_mfma_f32_16x16x32_bf16 v[16:19], v[188:191], v[164:167], v[16:19]
	v_mfma_f32_16x16x32_bf16 v[4:7], v[180:183], v[172:175], v[4:7]
	v_mfma_f32_16x16x32_bf16 v[0:3], v[188:191], v[172:175], v[0:3]
	s_barrier
; __device__ __forceinline__ float row_rstd(const float* ssq, int row, int fq) {
;     const f32x4 a = *(const f32x4*)(ssq + (size_t)row * 32 + 8 * fq), b = *(const f32x4*)(ssq + (size_t)row * 32 + 8 * fq + 4);
;     float t = ((a[0] + a[1]) + (a[2] + a[3])) + ((b[0] + b[1]) + (b[2] + b[3]));
;     t += __shfl_xor(t, 16); t += __shfl_xor(t, 32);
;     return rsqrtf(t * (1.0f / 2048.0f) + EPS);
;     __device__ __forceinline__ void operator()(f32x4 (&acc)[2][2][4][2], const Unit& u, int wr, int wc, int fr, int fq) const {
;         const int row0 = u.pm * BM + wr * 64 + fr, col0 = u.pn * BM + wc * 32 + 8 * fq;
;         const bf16_t* ppf = pp + ((size_t)(u.pm * (DM / 256) + u.pn) << 16) + (size_t)((((wr * 4 + wc) * 16) * 64 + fq * 16 + fr) << 3);
; #pragma unroll
;         for (int ai = 0; ai < 2; ++ai) {
;             u32x4 hw[4][2], pw[4][2]; float rstd[4];
; #pragma unroll
;             for (int m = 0; m < 4; ++m) { const int row = row0 + ai * HALF + m * 16;
; #pragma unroll
;                 for (int bj = 0; bj < 2; ++bj) { const size_t o = (size_t)row * DM + col0 + bj * HALF; hw[m][bj] = *(const u32x4*)(hb + o); pw[m][bj] = *(const u32x4*)(ppf + (((ai * 4 + m) * 2 + bj) << 9)); }
;                 rstd[m] = row_rstd(ssq_in, row, fq); }
	s_cbranch_scc0 .LBB0_1006
	s_waitcnt lgkmcnt(0)
	s_lshl_b32 s3, s4, 8
	v_mbcnt_lo_u32_b32 v104, -1, 0
	v_mbcnt_hi_u32_b32 v104, -1, v104
	s_add_i32 s3, s3, s22
	v_ashrrev_i32_e32 v108, 4, v104
	v_and_b32_e32 v109, 15, v104
	v_readlane_b32 s8, v254, 19
	v_add_u32_e32 v212, s3, v109
	v_lshlrev_b32_e32 v104, 3, v108
	v_ashrrev_i32_e32 v105, 31, v104
	v_ashrrev_i32_e32 v213, 31, v212
	v_add_u32_e32 v160, 16, v212
	v_lshl_add_u64 v[214:215], v[104:105], 2, s[16:17]
	v_lshlrev_b64 v[236:237], 7, v[212:213]
	v_ashrrev_i32_e32 v161, 31, v160
	v_lshl_add_u64 v[106:107], v[214:215], 0, v[236:237]
	v_lshlrev_b64 v[228:229], 7, v[160:161]
	global_load_dwordx4 v[136:139], v[106:107], off
	global_load_dwordx4 v[144:147], v[106:107], off offset:16
	v_lshl_add_u64 v[106:107], v[214:215], 0, v[228:229]
	global_load_dwordx4 v[148:151], v[106:107], off
	global_load_dwordx4 v[156:159], v[106:107], off offset:16
	v_and_b32_e32 v106, 64, v209
	v_xor_b32_e32 v105, 16, v209
	v_add_u32_e32 v106, 64, v106
	v_add_u32_e32 v162, 32, v212
	v_xor_b32_e32 v107, 32, v209
	v_cmp_lt_i32_e32 vcc, v105, v106
	v_ashrrev_i32_e32 v163, 31, v162
	v_lshlrev_b64 v[222:223], 7, v[162:163]
	v_cndmask_b32_e32 v105, v209, v105, vcc
	v_cmp_lt_i32_e32 vcc, v107, v106
	v_add_u32_e32 v226, 48, v212
	s_lshl_b32 s3, s2, 8
	v_cndmask_b32_e32 v110, v209, v107, vcc
	v_lshl_add_u64 v[106:107], v[214:215], 0, v[222:223]
	v_ashrrev_i32_e32 v227, 31, v226
	s_or_b32 s3, s3, s8
	global_load_dwordx4 v[112:115], v[106:107], off
	global_load_dwordx4 v[120:123], v[106:107], off offset:16
	v_lshlrev_b64 v[220:221], 7, v[226:227]
	v_lshlrev_b32_e32 v250, 2, v105
	v_add_u32_e32 v210, s3, v104
	v_lshl_add_u64 v[104:105], v[214:215], 0, v[220:221]
	v_add_u32_e32 v164, s55, v109
	v_lshlrev_b32_e32 v165, 7, v108
	v_lshlrev_b32_e32 v249, 2, v110
	v_cmp_eq_u32_e64 s[36:37], 0, v108
	global_load_dwordx4 v[108:111], v[104:105], off
	s_nop 0
	global_load_dwordx4 v[104:107], v[104:105], off offset:16
	s_lshl_b32 s4, s4, 3
	s_add_i32 s8, s4, s2
	s_ashr_i32 s9, s8, 31
	s_lshl_b64 s[8:9], s[8:9], 17
	v_ashrrev_i32_e32 v211, 31, v210
	s_add_u32 s8, s23, s8
	v_lshl_add_u32 v164, v164, 3, v165
	v_lshlrev_b64 v[240:241], 1, v[210:211]
	s_addc_u32 s9, s24, s9
	v_ashrrev_i32_e32 v165, 31, v164
	v_lshlrev_b64 v[238:239], 12, v[212:213]
	v_lshl_add_u64 v[216:217], s[6:7], 0, v[240:241]
	v_lshl_add_u64 v[218:219], v[164:165], 1, s[8:9]
	v_lshl_add_u64 v[164:165], v[216:217], 0, v[238:239]
	global_load_dwordx4 v[184:187], v[218:219], off
	global_load_dwordx4 v[188:191], v[164:165], off
	global_load_dwordx4 v[176:179], v[218:219], off offset:1024
	s_lshl_b32 s48, s2, 2
	v_lshlrev_b64 v[234:235], 12, v[160:161]
	v_lshlrev_b64 v[224:225], 12, v[162:163]
	v_lshlrev_b64 v[226:227], 12, v[226:227]
	s_ashr_i32 s49, s48, 31
	s_waitcnt vmcnt(0)
	v_mov_b32_e32 v166, v136
	v_mov_b32_e32 v167, v144
	v_mov_b32_e32 v144, v137
	v_mov_b32_e32 v136, v138
	v_mov_b32_e32 v137, v146
	v_mov_b32_e32 v146, v139
	v_pk_add_f32 v[138:139], v[166:167], v[144:145]
	v_pk_add_f32 v[136:137], v[136:137], v[146:147]
	v_mov_b32_e32 v144, v148
	v_mov_b32_e32 v145, v156
	v_mov_b32_e32 v156, v149
	v_mov_b32_e32 v146, v150
	v_mov_b32_e32 v147, v158
	v_mov_b32_e32 v158, v151
	v_pk_add_f32 v[136:137], v[138:139], v[136:137]
	v_pk_add_f32 v[138:139], v[144:145], v[156:157]
	v_pk_add_f32 v[144:145], v[146:147], v[158:159]
	v_lshl_add_u64 v[150:151], v[216:217], 0, v[234:235]
	v_pk_add_f32 v[138:139], v[138:139], v[144:145]
	v_mov_b32_e32 v145, v136
	v_mov_b32_e32 v144, v138
	v_mov_b32_e32 v136, v139
	v_pk_add_f32 v[136:137], v[144:145], v[136:137]
	ds_bpermute_b32 v139, v250, v137
	ds_bpermute_b32 v138, v250, v136
	v_mov_b32_e32 v232, v112
	v_mov_b32_e32 v233, v120
	v_mov_b32_e32 v120, v113
	v_pk_add_f32 v[112:113], v[232:233], v[120:121]
	s_waitcnt lgkmcnt(0)
	v_pk_add_f32 v[146:147], v[136:137], v[138:139]
	global_load_dwordx4 v[168:171], v[218:219], off offset:2048
	global_load_dwordx4 v[136:139], v[218:219], off offset:3072
	global_load_dwordx4 v[180:183], v[164:165], off offset:256
	ds_bpermute_b32 v149, v249, v147
	ds_bpermute_b32 v148, v249, v146
	v_mov_b32_e32 v120, v114
	v_mov_b32_e32 v121, v122
	v_mov_b32_e32 v122, v115
	v_pk_add_f32 v[114:115], v[120:121], v[122:123]
	s_waitcnt lgkmcnt(0)
; __device__ __forceinline__ float bflo(unsigned w) { return __uint_as_float(w << 16); }
; __device__ __forceinline__ float bfhi(unsigned w) { return __uint_as_float(w & 0xffff0000u); }
; __device__ __forceinline__ float sigmoidf_(float x) { return __builtin_amdgcn_rcpf(1.0f + __expf(-x)); }
;     __device__ __forceinline__ void operator()(f32x4 (&acc)[2][2][4][2], const Unit& u, int wr, int wc, int fr, int fq) const {
;     ...
;                 rstd[m] = row_rstd(ssq_in, row, fq); }
; #pragma unroll
;             for (int m = 0; m < 4; ++m) { const int row = row0 + ai * HALF + m * 16; const size_t off = (size_t)row * DM + col0; float s = 0.f;
; #pragma unroll
;                 for (int bj = 0; bj < 2; ++bj) { const f32x4 z0 = acc[ai][bj][m][0] * rstd[m], z1 = acc[ai][bj][m][1] * rstd[m]; const u32x4 h2 = hw[m][bj], p2 = pw[m][bj]; f32x4 v0, v1;
;                     v0[0] = bflo(h2.x) + sigmoidf_(z0[0]) * bflo(p2.x); v0[1] = bfhi(h2.x) + sigmoidf_(z0[1]) * bfhi(p2.x);
;                     v0[2] = bflo(h2.y) + sigmoidf_(z0[2]) * bflo(p2.y); v0[3] = bfhi(h2.y) + sigmoidf_(z0[3]) * bfhi(p2.y);
;                     v1[0] = bflo(h2.z) + sigmoidf_(z1[0]) * bflo(p2.z); v1[1] = bfhi(h2.z) + sigmoidf_(z1[1]) * bfhi(p2.z);
;                     v1[2] = bflo(h2.w) + sigmoidf_(z1[2]) * bflo(p2.w); v1[3] = bfhi(h2.w) + sigmoidf_(z1[3]) * bfhi(p2.w);
	v_pk_add_f32 v[146:147], v[146:147], v[148:149]
	v_mov_b32_e32 v120, v108
	v_pk_fma_f32 v[242:243], v[146:147], s[38:39], v[208:209] op_sel_hi:[1,0,0]
	v_mov_b32_e32 v121, v104
	v_mul_f32_e32 v146, 0x4b800000, v243
	v_cmp_gt_f32_e64 s[2:3], s52, v243
	v_mov_b32_e32 v104, v109
	v_mov_b32_e32 v108, v110
	v_cndmask_b32_e64 v146, v243, v146, s[2:3]
	v_rsq_f32_e32 v146, v146
	v_mov_b32_e32 v109, v106
	v_mov_b32_e32 v106, v111
	v_pk_add_f32 v[104:105], v[120:121], v[104:105]
	v_mul_f32_e32 v147, 0x45800000, v146
	v_cndmask_b32_e64 v244, v146, v147, s[2:3]
	v_pk_add_f32 v[106:107], v[108:109], v[106:107]
	v_pk_mul_f32 v[152:153], v[152:153], v[244:245] op_sel_hi:[1,0]
	s_movk_i32 s2, 0x1000
	v_pk_add_f32 v[112:113], v[112:113], v[114:115]
	v_pk_add_f32 v[104:105], v[104:105], v[106:107]
	v_mul_f32_e32 v152, 0xbfb8aa3b, v152
	v_lshl_add_u64 v[144:145], v[216:217], 0, v[224:225]
	v_add_co_u32_e64 v230, s[2:3], s2, v218
	v_lshl_add_u64 v[114:115], v[216:217], 0, v[226:227]
	v_mov_b32_e32 v106, v104
	v_mov_b32_e32 v107, v112
	v_mov_b32_e32 v112, v105
	v_exp_f32_e32 v152, v152
	v_mul_f32_e32 v153, 0xbfb8aa3b, v153
	global_load_dwordx4 v[172:175], v[150:151], off
	global_load_dwordx4 v[156:159], v[150:151], off offset:256
	v_addc_co_u32_e64 v231, s[2:3], 0, v219, s[2:3]
	global_load_dwordx4 v[160:163], v[144:145], off
	s_nop 0
	global_load_dwordx4 v[144:147], v[144:145], off offset:256
	s_nop 0
	global_load_dwordx4 v[164:167], v[230:231], off
	global_load_dwordx4 v[148:151], v[230:231], off offset:1024
	v_pk_add_f32 v[232:233], v[106:107], v[112:113]
	global_load_dwordx4 v[120:123], v[114:115], off
	global_load_dwordx4 v[108:111], v[114:115], off offset:256
	s_nop 0
	global_load_dwordx4 v[112:115], v[230:231], off offset:2048
	global_load_dwordx4 v[104:107], v[230:231], off offset:3072
	v_exp_f32_e32 v153, v153
	v_add_f32_e32 v152, 1.0, v152
	v_rcp_f32_e32 v152, v152
	v_lshlrev_b32_e32 v213, 16, v188
	v_add_f32_e32 v153, 1.0, v153
	v_rcp_f32_e32 v153, v153
	v_lshlrev_b32_e32 v243, 16, v184
	v_pk_mul_f32 v[154:155], v[154:155], v[244:245] op_sel_hi:[1,0]
	v_fmac_f32_e32 v213, v152, v243
	v_and_b32_e32 v152, 0xffff0000, v188
	v_and_b32_e32 v184, 0xffff0000, v184
	v_fmac_f32_e32 v152, v153, v184
	v_mul_f32_e32 v153, 0xbfb8aa3b, v154
	v_pk_mul_f32 v[140:141], v[140:141], v[244:245] op_sel_hi:[1,0]
	v_exp_f32_e32 v153, v153
	v_mul_f32_e32 v155, 0xbfb8aa3b, v155
	v_exp_f32_e32 v155, v155
	v_mul_f32_e32 v140, 0xbfb8aa3b, v140
	v_exp_f32_e32 v140, v140
	v_mul_f32_e32 v141, 0xbfb8aa3b, v141
	v_exp_f32_e32 v141, v141
	v_add_f32_e32 v153, 1.0, v153
	v_rcp_f32_e32 v153, v153
	v_add_f32_e32 v155, 1.0, v155
	v_rcp_f32_e32 v155, v155
	v_add_f32_e32 v140, 1.0, v140
	v_rcp_f32_e32 v140, v140
	v_add_f32_e32 v141, 1.0, v141
	v_lshlrev_b32_e32 v154, 16, v189
	v_lshlrev_b32_e32 v184, 16, v185
	v_rcp_f32_e32 v141, v141
	v_fmac_f32_e32 v154, v153, v184
	v_and_b32_e32 v153, 0xffff0000, v189
	v_and_b32_e32 v184, 0xffff0000, v185
	v_fmac_f32_e32 v153, v155, v184
	v_lshlrev_b32_e32 v155, 16, v190
	v_lshlrev_b32_e32 v184, 16, v186
	v_pk_mul_f32 v[142:143], v[142:143], v[244:245] op_sel_hi:[1,0]
	v_fmac_f32_e32 v155, v140, v184
	v_and_b32_e32 v184, 0xffff0000, v190
	v_and_b32_e32 v140, 0xffff0000, v186
	v_fmac_f32_e32 v184, v141, v140
	v_mul_f32_e32 v140, 0xbfb8aa3b, v142
	v_exp_f32_e32 v140, v140
	v_mul_f32_e32 v141, 0xbfb8aa3b, v143
	v_exp_f32_e32 v141, v141
	v_pk_mul_f32 v[132:133], v[132:133], v[244:245] op_sel_hi:[1,0]
	v_add_f32_e32 v140, 1.0, v140
	v_rcp_f32_e32 v140, v140
	v_add_f32_e32 v141, 1.0, v141
	v_rcp_f32_e32 v141, v141
	v_mul_f32_e32 v132, 0xbfb8aa3b, v132
	v_exp_f32_e32 v132, v132
	v_mul_f32_e32 v133, 0xbfb8aa3b, v133
	v_lshlrev_b32_e32 v185, 16, v191
	v_lshlrev_b32_e32 v142, 16, v187
	v_exp_f32_e32 v133, v133
	v_fmac_f32_e32 v185, v140, v142
	v_and_b32_e32 v186, 0xffff0000, v191
	v_and_b32_e32 v140, 0xffff0000, v187
	v_fmac_f32_e32 v186, v141, v140
	v_cvt_pk_bf16_f32 v140, v213, v152
	v_cvt_pk_bf16_f32 v141, v154, v153
	v_mul_f32_e32 v152, v152, v152
	v_mul_f32_e32 v153, v153, v153
	v_fmac_f32_e32 v152, v213, v213
	v_fmac_f32_e32 v153, v154, v154
	v_add_f32_e32 v132, 1.0, v132
	v_add_f32_e32 v152, v152, v153
	v_mul_f32_e32 v153, v184, v184
	v_mul_f32_e32 v154, v186, v186
	v_rcp_f32_e32 v132, v132
	v_add_f32_e32 v133, 1.0, v133
	v_fmac_f32_e32 v153, v155, v155
	v_fmac_f32_e32 v154, v185, v185
	v_rcp_f32_e32 v133, v133
	v_add_f32_e32 v153, v153, v154
	v_add_f32_e32 v152, v152, v153
	s_waitcnt vmcnt(10)
; __device__ __forceinline__ unsigned cvt_pk_bf16(float lo, float hi) { unsigned r; asm volatile("v_cvt_pk_bf16_f32 %0, %1, %2" : "=v"(r) : "v"(lo), "v"(hi)); return r; }
; __device__ __forceinline__ float bflo(unsigned w) { return __uint_as_float(w << 16); }
; __device__ __forceinline__ float bfhi(unsigned w) { return __uint_as_float(w & 0xffff0000u); }
; __device__ __forceinline__ float sigmoidf_(float x) { return __builtin_amdgcn_rcpf(1.0f + __expf(-x)); }
;     __device__ __forceinline__ void operator()(f32x4 (&acc)[2][2][4][2], const Unit& u, int wr, int wc, int fr, int fq) const {
;     ...
;             for (int m = 0; m < 4; ++m) { const int row = row0 + ai * HALF + m * 16; const size_t off = (size_t)row * DM + col0; float s = 0.f;
; #pragma unroll
;                 for (int bj = 0; bj < 2; ++bj) { const f32x4 z0 = acc[ai][bj][m][0] * rstd[m], z1 = acc[ai][bj][m][1] * rstd[m]; const u32x4 h2 = hw[m][bj], p2 = pw[m][bj]; f32x4 v0, v1;
;                     v0[0] = bflo(h2.x) + sigmoidf_(z0[0]) * bflo(p2.x); v0[1] = bfhi(h2.x) + sigmoidf_(z0[1]) * bfhi(p2.x);
;                     v0[2] = bflo(h2.y) + sigmoidf_(z0[2]) * bflo(p2.y); v0[3] = bfhi(h2.y) + sigmoidf_(z0[3]) * bfhi(p2.y);
;                     v1[0] = bflo(h2.z) + sigmoidf_(z1[0]) * bflo(p2.z); v1[1] = bfhi(h2.z) + sigmoidf_(z1[1]) * bfhi(p2.z);
;                     v1[2] = bflo(h2.w) + sigmoidf_(z1[2]) * bflo(p2.w); v1[3] = bfhi(h2.w) + sigmoidf_(z1[3]) * bfhi(p2.w);
;                     u32x4 w; w.x = cvt_pk_bf16(v0[0], v0[1]); w.y = cvt_pk_bf16(v0[2], v0[3]); w.z = cvt_pk_bf16(v1[0], v1[1]); w.w = cvt_pk_bf16(v1[2], v1[3]);
;                     *(u32x4*)(out + off + bj * HALF) = w;
;                     s += ((v0[0] * v0[0] + v0[1] * v0[1]) + (v0[2] * v0[2] + v0[3] * v0[3])) + ((v1[0] * v1[0] + v1[1] * v1[1]) + (v1[2] * v1[2] + v1[3] * v1[3])); }
;                 s += __shfl_xor(s, 16); s += __shfl_xor(s, 32);
;                 if (fq == 0) ssq[(size_t)row * 32 + u.pn * 4 + wc] = s; }
	v_lshlrev_b32_e32 v153, 16, v180
	v_lshlrev_b32_e32 v154, 16, v176
	v_pk_mul_f32 v[134:135], v[134:135], v[244:245] op_sel_hi:[1,0]
	v_fmac_f32_e32 v153, v132, v154
	v_and_b32_e32 v132, 0xffff0000, v180
	v_and_b32_e32 v154, 0xffff0000, v176
	v_fmac_f32_e32 v132, v133, v154
	v_mul_f32_e32 v133, 0xbfb8aa3b, v134
	v_pk_mul_f32 v[128:129], v[128:129], v[244:245] op_sel_hi:[1,0]
	v_exp_f32_e32 v133, v133
	v_mul_f32_e32 v134, 0xbfb8aa3b, v135
	v_exp_f32_e32 v134, v134
	v_mul_f32_e32 v128, 0xbfb8aa3b, v128
	v_exp_f32_e32 v128, v128
	v_mul_f32_e32 v129, 0xbfb8aa3b, v129
	v_exp_f32_e32 v129, v129
	v_add_f32_e32 v133, 1.0, v133
	v_rcp_f32_e32 v133, v133
	v_add_f32_e32 v134, 1.0, v134
	v_rcp_f32_e32 v134, v134
	v_add_f32_e32 v128, 1.0, v128
	v_rcp_f32_e32 v128, v128
	v_add_f32_e32 v129, 1.0, v129
	v_lshlrev_b32_e32 v154, 16, v181
	v_lshlrev_b32_e32 v135, 16, v177
	v_rcp_f32_e32 v129, v129
	v_fmac_f32_e32 v154, v133, v135
	v_and_b32_e32 v133, 0xffff0000, v181
	v_and_b32_e32 v135, 0xffff0000, v177
	v_cvt_pk_bf16_f32 v142, v155, v184
	v_fmac_f32_e32 v133, v134, v135
	v_lshlrev_b32_e32 v155, 16, v182
	v_lshlrev_b32_e32 v134, 16, v178
	v_pk_mul_f32 v[130:131], v[130:131], v[244:245] op_sel_hi:[1,0]
	v_fmac_f32_e32 v155, v128, v134
	v_and_b32_e32 v176, 0xffff0000, v182
	v_and_b32_e32 v128, 0xffff0000, v178
	v_fmac_f32_e32 v176, v129, v128
	v_mul_f32_e32 v128, 0xbfb8aa3b, v130
	v_exp_f32_e32 v128, v128
	v_mul_f32_e32 v129, 0xbfb8aa3b, v131
	v_exp_f32_e32 v129, v129
	v_lshlrev_b32_e32 v177, 16, v183
	v_add_f32_e32 v128, 1.0, v128
	v_rcp_f32_e32 v128, v128
	v_add_f32_e32 v129, 1.0, v129
	v_rcp_f32_e32 v129, v129
	v_lshlrev_b32_e32 v130, 16, v179
	v_fmac_f32_e32 v177, v128, v130
	v_and_b32_e32 v178, 0xffff0000, v183
	v_and_b32_e32 v128, 0xffff0000, v179
	v_fmac_f32_e32 v178, v129, v128
	v_mul_f32_e32 v128, v132, v132
	v_mul_f32_e32 v129, v133, v133
	v_fmac_f32_e32 v128, v153, v153
	v_fmac_f32_e32 v129, v154, v154
	v_add_f32_e32 v128, v128, v129
	v_mul_f32_e32 v129, v176, v176
	v_mul_f32_e32 v130, v178, v178
	v_fmac_f32_e32 v129, v155, v155
	v_fmac_f32_e32 v130, v177, v177
	v_add_f32_e32 v129, v129, v130
	v_add_f32_e32 v128, v128, v129
	v_add_f32_e32 v131, v152, v128
	ds_bpermute_b32 v253, v250, v233
	ds_bpermute_b32 v252, v250, v232
	ds_bpermute_b32 v152, v250, v131
	v_lshl_add_u64 v[128:129], s[0:1], 0, v[238:239]
	v_lshl_add_u64 v[134:135], v[128:129], 0, v[240:241]
	v_cmp_gt_f32_e32 vcc, s52, v242
	s_waitcnt lgkmcnt(1)
	v_pk_add_f32 v[230:231], v[232:233], v[252:253]
	s_waitcnt lgkmcnt(0)
	v_add_f32_e32 v128, v131, v152
	ds_bpermute_b32 v233, v249, v231
	ds_bpermute_b32 v232, v249, v230
	ds_bpermute_b32 v129, v249, v128
	v_cvt_pk_bf16_f32 v143, v185, v186
	global_store_dwordx4 v[134:135], v[140:143], off
	v_cvt_pk_bf16_f32 v130, v153, v132
	v_cvt_pk_bf16_f32 v131, v154, v133
	v_cvt_pk_bf16_f32 v132, v155, v176
	v_cvt_pk_bf16_f32 v133, v177, v178
	global_store_dwordx4 v[134:135], v[130:133], off offset:256
	s_and_saveexec_b64 s[2:3], s[36:37]
	s_cbranch_execz .LBB0_1009
	v_lshl_add_u64 v[130:131], s[28:29], 0, v[236:237]
	v_lshl_add_u64 v[130:131], s[48:49], 2, v[130:131]
	s_lshl_b32 s4, s27, 2
	v_lshl_add_u64 v[130:131], v[130:131], 0, s[4:5]
	s_waitcnt lgkmcnt(0)
	v_add_f32_e32 v128, v128, v129
	global_store_dword v[130:131], v128, off
